# butterfly reductions in attention/decode epilogues and HGRN stage C: ds_bpermute xor1/2/4/8 steps replaced by v_mov_b32_dpp (bitwise identical)
# speedup vs baseline: 1.0008x; 1.0008x over previous
; DI unsigned pk2(float lo, float hi) { return f2bf(lo) | (f2bf(hi) << 16); }
; #define CACHE_MK IN_(5)
; #define CACHE_MV IN_(6)
; __global__ void __launch_bounds__(512, 2) fwd(Args args) {
;     ...
;         for (int it = gw; it < DB * NMEM * 2; it += NGW) {
;             const int row = it >> 1, kv = it & 1;
;             const v4f* src = (const v4f*)((kv ? CACHE_MV : CACHE_MK) + (size_t)row * 1024) + lane; v2u* dst = (v2u*)(MKV_ + (size_t)(2048 + row) * 2048 + kv * 1024) + lane;
; #pragma unroll
;             for (int j = 0; j < 4; ++j) { const v4f v = src[64 * j]; dst[64 * j] = (v2u){pk2(v.x, v.y), pk2(v.z, v.w)}; }
;         }
.LBB0_86:
	s_ashr_i32 s8, s2, 1
	s_ashr_i32 s9, s8, 31
	s_lshl_b64 s[8:9], s[8:9], 12
	v_lshl_add_u64 v[10:11], v[4:5], 0, s[8:9]
	global_load_dwordx4 v[6:9], v[10:11], off
	v_lshl_add_u64 v[12:13], v[2:3], 0, s[8:9]
	v_add_co_u32_e32 v14, vcc, s6, v12
	s_add_i32 s2, s2, s0
	s_nop 0
	v_addc_co_u32_e32 v15, vcc, 0, v13, vcc
	v_lshl_add_u64 v[12:13], v[12:13], 0, s[4:5]
	s_cmpk_gt_i32 s2, 0x3fff
	s_waitcnt vmcnt(0)
	v_bfe_u32 v1, v6, 16, 1
	v_bfe_u32 v16, v7, 16, 1
	v_bfe_u32 v17, v8, 16, 1
	v_bfe_u32 v18, v9, 16, 1
	v_add3_u32 v1, v6, v1, s1
	v_add3_u32 v6, v7, v16, s1
	v_add3_u32 v7, v8, v17, s1
	v_add3_u32 v8, v9, v18, s1
	v_lshrrev_b32_e32 v1, 16, v1
	v_lshrrev_b32_e32 v7, 16, v7
	v_and_or_b32 v6, v6, s3, v1
	v_and_or_b32 v7, v8, s3, v7
	global_store_dwordx2 v[14:15], v[6:7], off
	global_load_dwordx4 v[6:9], v[10:11], off offset:1024
	s_waitcnt vmcnt(0)
	v_bfe_u32 v1, v6, 16, 1
	v_bfe_u32 v14, v7, 16, 1
	v_bfe_u32 v15, v8, 16, 1
	v_bfe_u32 v16, v9, 16, 1
	v_add3_u32 v1, v6, v1, s1
	v_add3_u32 v6, v7, v14, s1
	v_add3_u32 v7, v8, v15, s1
	v_add3_u32 v8, v9, v16, s1
	v_lshrrev_b32_e32 v1, 16, v1
	v_lshrrev_b32_e32 v7, 16, v7
	v_and_or_b32 v6, v6, s3, v1
	v_and_or_b32 v7, v8, s3, v7
	global_store_dwordx2 v[12:13], v[6:7], off offset:512
	global_load_dwordx4 v[6:9], v[10:11], off offset:2048
	s_waitcnt vmcnt(0)
	v_bfe_u32 v1, v6, 16, 1
	v_bfe_u32 v14, v7, 16, 1
	v_bfe_u32 v15, v8, 16, 1
	v_bfe_u32 v16, v9, 16, 1
	v_add3_u32 v1, v6, v1, s1
	v_add3_u32 v6, v7, v14, s1
	v_add3_u32 v7, v8, v15, s1
	v_add3_u32 v8, v9, v16, s1
	v_lshrrev_b32_e32 v1, 16, v1
	v_lshrrev_b32_e32 v7, 16, v7
	v_and_or_b32 v6, v6, s3, v1
	v_and_or_b32 v7, v8, s3, v7
	global_store_dwordx2 v[12:13], v[6:7], off offset:1024
	global_load_dwordx4 v[6:9], v[10:11], off offset:3072
	s_waitcnt vmcnt(0)
	v_bfe_u32 v1, v6, 16, 1
	v_bfe_u32 v10, v7, 16, 1
	v_bfe_u32 v11, v8, 16, 1
	v_bfe_u32 v14, v9, 16, 1
	v_add3_u32 v1, v6, v1, s1
	v_add3_u32 v6, v7, v10, s1
	v_add3_u32 v7, v8, v11, s1
	v_add3_u32 v8, v9, v14, s1
	v_lshrrev_b32_e32 v1, 16, v1
	v_lshrrev_b32_e32 v7, 16, v7
	v_and_or_b32 v6, v6, s3, v1
	v_and_or_b32 v7, v8, s3, v7
	global_store_dwordx2 v[12:13], v[6:7], off offset:1536
	s_cbranch_scc0 .LBB0_86

; #define LAS __attribute__((address_space(3)))
; DI int crow(int i, int hh) { return (i & 3) + 8 * (i >> 2) + 4 * hh; }
; DI s16x4 vtr(const LAS unsigned char* p) { return __builtin_bit_cast(s16x4, __builtin_amdgcn_ds_read_tr16_b64_v4i16((LAS v4i16_t*)p)); }
; DI void hgrn_unit(Ctx A_, LAS unsigned char* lds, int row0, int T, int NC, int h, const float* s0, float* sout, int wave, int lane, int tid) {
;     ...
; #pragma unroll
;         for (int i = 0; i < 4; ++i)
; #pragma unroll
;             for (int s2 = 0; s2 < 2; ++s2) {
;                 const LAS unsigned char* ap = lds + OFF_QS + (32 * tb + r) * RP + (32 * i + 16 * s2 + 4 * hh) * 2;
;                 const v2u alo = *(const LAS v2u*)ap, ahi = *(const LAS v2u*)(ap + 16);
;                 const v4u a4 = {alo.x, alo.y, ahi.x, ahi.y};
;                 o = __builtin_amdgcn_mfma_f32_32x32x16_bf16(__builtin_bit_cast(bf16x8, a4), pack8(S[i], 8 * s2), o, 0, 0, 0);
;             }
; #pragma unroll
;         for (int e = 0; e < 16; ++e) *(LAS float*)(lds + OFF_OX + ((32 * tb + crow(e, hh)) * 128 + 32 * j + r) * 4) = o[e];
; #pragma unroll
;         for (int i = 0; i < 4; ++i)
; #pragma unroll
;             for (int k4 = 0; k4 < 4; ++k4) { const v4f dq = *(const LAS v4f*)(lds + OFF_DEC + (32 * i + 8 * k4 + 4 * hh) * 4);
;                 S[i][4 * k4] *= dq.x; S[i][4 * k4 + 1] *= dq.y; S[i][4 * k4 + 2] *= dq.z; S[i][4 * k4 + 3] *= dq.w; }
; #pragma unroll
;         for (int ks = 0; ks < 4; ++ks) {
;             const LAS unsigned char* vq = lds + OFF_V + j * 4096 + (16 * ks + 8 * hh + q4) * 64 + g16 * 32 + p4 * 8;
;             const s16x4 vlo = vtr(vq), vhi = vtr(vq + 256);
;             const bf16x8 vb = __builtin_shufflevector(vlo, vhi, 0, 1, 2, 3, 4, 5, 6, 7);
; #pragma unroll
;             for (int i = 0; i < 4; ++i) {
;                 const LAS unsigned char* kq = lds + OFF_KS + (16 * ks + 8 * hh + q4) * RP + (32 * i + 16 * g16 + 4 * p4) * 2;
;                 const s16x4 klo = vtr(kq), khi = vtr(kq + 4 * RP);
;                 const bf16x8 ka = __builtin_shufflevector(klo, khi, 0, 1, 2, 3, 4, 5, 6, 7);
;                 S[i] = __builtin_amdgcn_mfma_f32_32x32x16_bf16(ka, vb, S[i], 0, 0, 0);
;             }
.LBB0_813:
	v_add_u32_e32 v3, v195, v197
	v_add_u32_e32 v3, 0x8800, v3
	ds_read2_b64 v[4:7], v3 offset1:2
	ds_read2_b64 v[8:11], v3 offset0:4 offset1:6
	v_cvt_pk_bf16_f32 v12, v18, v19
	v_cvt_pk_bf16_f32 v13, v20, v21
	v_cvt_pk_bf16_f32 v14, v22, v23
	v_cvt_pk_bf16_f32 v15, v24, v25
	s_waitcnt lgkmcnt(1)
	s_nop 0
	v_mfma_f32_32x32x16_bf16 v[98:113], v[4:7], v[12:15], v[98:113]
	v_cvt_pk_bf16_f32 v4, v26, v27
	v_cvt_pk_bf16_f32 v5, v28, v29
	v_cvt_pk_bf16_f32 v6, v30, v31
	v_cvt_pk_bf16_f32 v7, v32, v33
	s_waitcnt lgkmcnt(0)
	s_nop 0
	v_mfma_f32_32x32x16_bf16 v[98:113], v[8:11], v[4:7], v[98:113]
	ds_read2_b64 v[4:7], v3 offset0:8 offset1:10
	v_cvt_pk_bf16_f32 v8, v34, v35
	v_cvt_pk_bf16_f32 v9, v36, v37
	v_cvt_pk_bf16_f32 v10, v38, v39
	v_cvt_pk_bf16_f32 v11, v40, v41
	s_waitcnt lgkmcnt(0)
	s_nop 0
	v_mfma_f32_32x32x16_bf16 v[98:113], v[4:7], v[8:11], v[98:113]
	ds_read2_b64 v[4:7], v3 offset0:12 offset1:14
	v_cvt_pk_bf16_f32 v8, v42, v43
	v_cvt_pk_bf16_f32 v9, v44, v45
	v_cvt_pk_bf16_f32 v10, v46, v47
	v_cvt_pk_bf16_f32 v11, v48, v49
	s_waitcnt lgkmcnt(0)
	s_nop 0
	v_mfma_f32_32x32x16_bf16 v[98:113], v[4:7], v[8:11], v[98:113]
	ds_read2_b64 v[4:7], v3 offset0:16 offset1:18
	v_cvt_pk_bf16_f32 v8, v50, v51
	v_cvt_pk_bf16_f32 v9, v52, v53
	v_cvt_pk_bf16_f32 v10, v54, v55
	v_cvt_pk_bf16_f32 v11, v56, v57
	s_waitcnt lgkmcnt(0)
	s_nop 0
	v_mfma_f32_32x32x16_bf16 v[98:113], v[4:7], v[8:11], v[98:113]
	ds_read2_b64 v[4:7], v3 offset0:20 offset1:22
	v_cvt_pk_bf16_f32 v8, v58, v59
	v_cvt_pk_bf16_f32 v9, v60, v61
	v_cvt_pk_bf16_f32 v10, v62, v63
	v_cvt_pk_bf16_f32 v11, v64, v65
	s_waitcnt lgkmcnt(0)
	s_nop 0
	v_mfma_f32_32x32x16_bf16 v[98:113], v[4:7], v[8:11], v[98:113]
	ds_read2_b64 v[4:7], v3 offset0:24 offset1:26
	v_cvt_pk_bf16_f32 v8, v66, v67
	v_cvt_pk_bf16_f32 v9, v68, v69
	v_cvt_pk_bf16_f32 v10, v70, v71
	v_cvt_pk_bf16_f32 v11, v72, v73
	s_waitcnt lgkmcnt(0)
	s_nop 0
	v_mfma_f32_32x32x16_bf16 v[98:113], v[4:7], v[8:11], v[98:113]
	ds_read2_b64 v[4:7], v3 offset0:28 offset1:30
	v_cvt_pk_bf16_f32 v8, v74, v75
	v_cvt_pk_bf16_f32 v9, v76, v77
	v_cvt_pk_bf16_f32 v10, v78, v79
	v_cvt_pk_bf16_f32 v11, v80, v81
	v_add_u32_e32 v3, 0, v194
	v_add_u32_e32 v12, 0x1e040, v3
	s_waitcnt lgkmcnt(0)
	v_mfma_f32_32x32x16_bf16 v[98:113], v[4:7], v[8:11], v[98:113]
	s_nop 11
	ds_write_b32 v215, v98
	ds_write_b32 v216, v99
	ds_write_b32 v217, v100
	ds_write_b32 v218, v101
	ds_write_b32 v219, v102
	ds_write_b32 v220, v103
	ds_write_b32 v221, v104
	ds_write_b32 v222, v105
	ds_write_b32 v223, v106
	ds_write_b32 v224, v107
	ds_write_b32 v225, v108
	ds_write_b32 v226, v109
	ds_write_b32 v227, v110
	ds_write_b32 v228, v111
	ds_write_b32 v229, v112
	ds_write_b32 v230, v113
	v_add_u32_e32 v4, 0x1e000, v3
	v_add_u32_e32 v8, 0x1e020, v3
	ds_read_b128 v[4:7], v4
	ds_read_b128 v[8:11], v8
	ds_read_b128 v[12:15], v12
	v_add_u32_e32 v16, 0x1e060, v3
	ds_read_b128 v[82:85], v16
	s_waitcnt lgkmcnt(3)
	v_pk_mul_f32 v[18:19], v[18:19], v[4:5]
	s_waitcnt lgkmcnt(2)
	v_pk_mul_f32 v[22:23], v[22:23], v[8:9]
	v_add_u32_e32 v4, 0x1e080, v3
	v_add_u32_e32 v8, 0x1e0a0, v3
	v_pk_mul_f32 v[24:25], v[24:25], v[10:11]
	v_pk_mul_f32 v[20:21], v[20:21], v[6:7]
	ds_read_b128 v[4:7], v4
	ds_read_b128 v[8:11], v8
	s_waitcnt lgkmcnt(1)
	v_pk_mul_f32 v[34:35], v[34:35], v[4:5]
	s_waitcnt lgkmcnt(0)
	v_pk_mul_f32 v[38:39], v[38:39], v[8:9]
	v_add_u32_e32 v4, 0x1e100, v3
	v_add_u32_e32 v8, 0x1e120, v3
	v_pk_mul_f32 v[40:41], v[40:41], v[10:11]
	v_pk_mul_f32 v[36:37], v[36:37], v[6:7]
	ds_read_b128 v[4:7], v4
	ds_read_b128 v[8:11], v8
	s_waitcnt lgkmcnt(1)
	v_pk_mul_f32 v[50:51], v[50:51], v[4:5]
	s_waitcnt lgkmcnt(0)
	v_pk_mul_f32 v[54:55], v[54:55], v[8:9]
	v_add_u32_e32 v8, 0x1e1a0, v3
	v_pk_mul_f32 v[56:57], v[56:57], v[10:11]
	ds_read_b128 v[8:11], v8
	v_pk_mul_f32 v[26:27], v[26:27], v[12:13]
	v_add_u32_e32 v12, 0x1e0c0, v3
	v_pk_mul_f32 v[28:29], v[28:29], v[14:15]
	ds_read_b128 v[12:15], v12
	v_add_u32_e32 v16, 0x1e0e0, v3
	v_pk_mul_f32 v[30:31], v[30:31], v[82:83]
	v_pk_mul_f32 v[32:33], v[32:33], v[84:85]
	ds_read_b128 v[82:85], v16
	s_waitcnt lgkmcnt(1)
	v_pk_mul_f32 v[42:43], v[42:43], v[12:13]
	v_add_u32_e32 v12, 0x1e140, v3
	v_pk_mul_f32 v[44:45], v[44:45], v[14:15]
	ds_read_b128 v[12:15], v12
	v_add_u32_e32 v16, 0x1e160, v3
	s_waitcnt lgkmcnt(1)
	v_pk_mul_f32 v[46:47], v[46:47], v[82:83]
	v_pk_mul_f32 v[48:49], v[48:49], v[84:85]
	ds_read_b128 v[82:85], v16
	v_add_u32_e32 v4, 0x1e180, v3
	v_pk_mul_f32 v[52:53], v[52:53], v[6:7]
	ds_read_b128 v[4:7], v4
	s_waitcnt lgkmcnt(2)
	v_pk_mul_f32 v[58:59], v[58:59], v[12:13]
	v_add_u32_e32 v12, 0x1e1c0, v3
	v_add_u32_e32 v3, 0x1e1e0, v3
	v_pk_mul_f32 v[60:61], v[60:61], v[14:15]
	ds_read_b128 v[12:15], v12
	s_waitcnt lgkmcnt(2)
	v_pk_mul_f32 v[62:63], v[62:63], v[82:83]
	v_pk_mul_f32 v[64:65], v[64:65], v[84:85]
	ds_read_b128 v[82:85], v3
	v_add_u32_e32 v3, v196, v199
	v_pk_mul_f32 v[70:71], v[70:71], v[8:9]
	v_pk_mul_f32 v[72:73], v[72:73], v[10:11]
	s_waitcnt lgkmcnt(2)
	v_pk_mul_f32 v[68:69], v[68:69], v[6:7]
	v_pk_mul_f32 v[66:67], v[66:67], v[4:5]
	ds_read_b64_tr_b16 v[4:5], v3
	ds_read_b64_tr_b16 v[6:7], v3 offset:256
	ds_read_b64_tr_b16 v[8:9], v202 offset:52224
	ds_read_b64_tr_b16 v[10:11], v202 offset:53312
	s_waitcnt lgkmcnt(0)
	v_mfma_f32_32x32x16_bf16 v[18:33], v[8:11], v[4:7], v[18:33]
	ds_read_b64_tr_b16 v[8:9], v202 offset:52288
	ds_read_b64_tr_b16 v[10:11], v202 offset:53376
	v_mul_f32_e64 v78, v78, v82
	v_mul_f32_e64 v79, v79, v83
	v_mul_f32_e64 v74, v74, v12
	v_mul_f32_e64 v75, v75, v13
	v_pk_mul_f32 v[80:81], v[80:81], v[84:85]
	v_pk_mul_f32 v[76:77], v[76:77], v[14:15]
	s_waitcnt lgkmcnt(0)
; #define LAS __attribute__((address_space(3)))
; DI s16x4 vtr(const LAS unsigned char* p) { return __builtin_bit_cast(s16x4, __builtin_amdgcn_ds_read_tr16_b64_v4i16((LAS v4i16_t*)p)); }
; #define HG_LBAR() do { asm volatile("s_waitcnt lgkmcnt(0)" ::: "memory"); __builtin_amdgcn_s_barrier(); asm volatile("" ::: "memory"); } while (0)
; DI void hgrn_unit(Ctx A_, LAS unsigned char* lds, int row0, int T, int NC, int h, const float* s0, float* sout, int wave, int lane, int tid) {
;     ...
;         for (int ks = 0; ks < 4; ++ks) {
;             const LAS unsigned char* vq = lds + OFF_V + j * 4096 + (16 * ks + 8 * hh + q4) * 64 + g16 * 32 + p4 * 8;
;             const s16x4 vlo = vtr(vq), vhi = vtr(vq + 256);
;             const bf16x8 vb = __builtin_shufflevector(vlo, vhi, 0, 1, 2, 3, 4, 5, 6, 7);
; #pragma unroll
;             for (int i = 0; i < 4; ++i) {
;                 const LAS unsigned char* kq = lds + OFF_KS + (16 * ks + 8 * hh + q4) * RP + (32 * i + 16 * g16 + 4 * p4) * 2;
;                 const s16x4 klo = vtr(kq), khi = vtr(kq + 4 * RP);
;                 const bf16x8 ka = __builtin_shufflevector(klo, khi, 0, 1, 2, 3, 4, 5, 6, 7);
;                 S[i] = __builtin_amdgcn_mfma_f32_32x32x16_bf16(ka, vb, S[i], 0, 0, 0);
;             }
;         }
;         HG_LBAR();
;         {
;             const int t = tid >> 3, cg = tid & 7;
;             const LAS v4f* ox = (const LAS v4f*)(lds + OFF_OX + (t * 128 + 16 * cg) * 4);
;             const v4f x0 = ox[0], x1 = ox[1], x2 = ox[2], x3 = ox[3];
;             float ss = (x0.x * x0.x + x0.y * x0.y + x0.z * x0.z + x0.w * x0.w) + (x1.x * x1.x + x1.y * x1.y + x1.z * x1.z + x1.w * x1.w)
;                      + (x2.x * x2.x + x2.y * x2.y + x2.z * x2.z + x2.w * x2.w) + (x3.x * x3.x + x3.y * x3.y + x3.z * x3.z + x3.w * x3.w);
;             ss += __shfl_xor(ss, 1); ss += __shfl_xor(ss, 2); ss += __shfl_xor(ss, 4);
	v_mfma_f32_32x32x16_bf16 v[34:49], v[8:11], v[4:7], v[34:49]
	ds_read_b64_tr_b16 v[8:9], v202 offset:52352
	ds_read_b64_tr_b16 v[10:11], v202 offset:53440
	s_waitcnt lgkmcnt(0)
	v_mfma_f32_32x32x16_bf16 v[50:65], v[8:11], v[4:7], v[50:65]
	ds_read_b64_tr_b16 v[8:9], v202 offset:52416
	ds_read_b64_tr_b16 v[10:11], v202 offset:53504
	s_waitcnt lgkmcnt(0)
	v_mfma_f32_32x32x16_bf16 v[66:81], v[8:11], v[4:7], v[66:81]
	ds_read_b64_tr_b16 v[4:5], v203
	ds_read_b64_tr_b16 v[6:7], v203 offset:256
	ds_read_b64_tr_b16 v[8:9], v202 offset:56576
	ds_read_b64_tr_b16 v[10:11], v202 offset:57664
	s_waitcnt lgkmcnt(0)
	v_mfma_f32_32x32x16_bf16 v[18:33], v[8:11], v[4:7], v[18:33]
	ds_read_b64_tr_b16 v[8:9], v202 offset:56640
	ds_read_b64_tr_b16 v[10:11], v202 offset:57728
	s_waitcnt lgkmcnt(0)
	v_mfma_f32_32x32x16_bf16 v[34:49], v[8:11], v[4:7], v[34:49]
	ds_read_b64_tr_b16 v[8:9], v202 offset:56704
	ds_read_b64_tr_b16 v[10:11], v202 offset:57792
	s_waitcnt lgkmcnt(0)
	v_mfma_f32_32x32x16_bf16 v[50:65], v[8:11], v[4:7], v[50:65]
	ds_read_b64_tr_b16 v[8:9], v202 offset:56768
	ds_read_b64_tr_b16 v[10:11], v202 offset:57856
	s_waitcnt lgkmcnt(0)
	v_mfma_f32_32x32x16_bf16 v[66:81], v[8:11], v[4:7], v[66:81]
	ds_read_b64_tr_b16 v[4:5], v210
	ds_read_b64_tr_b16 v[6:7], v210 offset:256
	ds_read_b64_tr_b16 v[8:9], v202 offset:60928
	ds_read_b64_tr_b16 v[10:11], v202 offset:62016
	s_waitcnt lgkmcnt(0)
	v_mfma_f32_32x32x16_bf16 v[18:33], v[8:11], v[4:7], v[18:33]
	ds_read_b64_tr_b16 v[8:9], v202 offset:60992
	ds_read_b64_tr_b16 v[10:11], v202 offset:62080
	s_waitcnt lgkmcnt(0)
	v_mfma_f32_32x32x16_bf16 v[34:49], v[8:11], v[4:7], v[34:49]
	ds_read_b64_tr_b16 v[8:9], v202 offset:61056
	ds_read_b64_tr_b16 v[10:11], v202 offset:62144
	s_waitcnt lgkmcnt(0)
	v_mfma_f32_32x32x16_bf16 v[50:65], v[8:11], v[4:7], v[50:65]
	ds_read_b64_tr_b16 v[8:9], v202 offset:61120
	ds_read_b64_tr_b16 v[10:11], v202 offset:62208
	s_waitcnt lgkmcnt(0)
	v_mfma_f32_32x32x16_bf16 v[66:81], v[8:11], v[4:7], v[66:81]
	ds_read_b64_tr_b16 v[4:5], v211
	ds_read_b64_tr_b16 v[6:7], v211 offset:256
	ds_read_b64_tr_b16 v[8:9], v202 offset:65280
	ds_read_b64_tr_b16 v[10:11], v212 offset:62016
	s_waitcnt lgkmcnt(0)
	v_mfma_f32_32x32x16_bf16 v[18:33], v[8:11], v[4:7], v[18:33]
	ds_read_b64_tr_b16 v[8:9], v202 offset:65344
	ds_read_b64_tr_b16 v[10:11], v212 offset:62080
	s_waitcnt lgkmcnt(0)
	v_mfma_f32_32x32x16_bf16 v[34:49], v[8:11], v[4:7], v[34:49]
	ds_read_b64_tr_b16 v[8:9], v202 offset:65408
	ds_read_b64_tr_b16 v[10:11], v212 offset:62144
	s_waitcnt lgkmcnt(0)
	v_mfma_f32_32x32x16_bf16 v[50:65], v[8:11], v[4:7], v[50:65]
	ds_read_b64_tr_b16 v[8:9], v202 offset:65472
	ds_read_b64_tr_b16 v[10:11], v212 offset:62208
	s_waitcnt lgkmcnt(0)
	s_barrier
	s_waitcnt lgkmcnt(0)
	v_mfma_f32_32x32x16_bf16 v[66:81], v[8:11], v[4:7], v[66:81]
	ds_read_b128 v[82:85], v213
	ds_read_b128 v[12:15], v213 offset:16
	ds_read_b128 v[8:11], v213 offset:32
	ds_read_b128 v[4:7], v213 offset:48
	s_waitcnt lgkmcnt(3)
	v_mul_f32_e32 v3, v83, v83
	s_waitcnt lgkmcnt(2)
	v_mul_f32_e32 v16, v13, v13
	v_fmac_f32_e32 v3, v82, v82
	v_fmac_f32_e32 v16, v12, v12
	v_fmac_f32_e32 v3, v84, v84
	v_fmac_f32_e32 v16, v14, v14
	v_fmac_f32_e32 v3, v85, v85
	v_fmac_f32_e32 v16, v15, v15
	v_add_f32_e32 v3, v3, v16
	s_waitcnt lgkmcnt(1)
	v_mul_f32_e32 v16, v9, v9
	v_fmac_f32_e32 v16, v8, v8
	v_fmac_f32_e32 v16, v10, v10
	v_fmac_f32_e32 v16, v11, v11
	v_add_f32_e32 v3, v3, v16
	s_waitcnt lgkmcnt(0)
	v_mul_f32_e32 v16, v5, v5
	v_fmac_f32_e32 v16, v4, v4
	v_fmac_f32_e32 v16, v6, v6
	v_fmac_f32_e32 v16, v7, v7
	v_add_f32_e32 v3, v3, v16
	s_nop 1
	v_mov_b32_dpp v16, v3 quad_perm:[1,0,3,2] row_mask:0xf bank_mask:0xf
	s_waitcnt lgkmcnt(0)
	v_add_f32_e32 v3, v3, v16
	s_nop 1
	v_mov_b32_dpp v16, v3 quad_perm:[2,3,0,1] row_mask:0xf bank_mask:0xf
	s_waitcnt lgkmcnt(0)
	v_add_f32_e32 v3, v3, v16
	s_nop 1
	v_mov_b32_dpp v16, v3 row_half_mirror row_mask:0xf bank_mask:0xf
	s_and_saveexec_b64 s[56:57], s[18:19]
	s_cbranch_execz .LBB0_776
; DI float bflo(unsigned u) { return __uint_as_float(u << 16); }
; DI float bfhi(unsigned u) { return __uint_as_float(u & 0xffff0000u); }
; DI void hgrn_unit(Ctx A_, LAS unsigned char* lds, int row0, int T, int NC, int h, const float* s0, float* sout, int wave, int lane, int tid) {
;     ...
;             ss += __shfl_xor(ss, 1); ss += __shfl_xor(ss, 2); ss += __shfl_xor(ss, 4);
;             if (t < T) {
;                 const float inv = 1.0f / sqrtf(ss * (1.0f / 128.0f) + NORM_EPS);
;                 const size_t row = (size_t)row0 + 64 * c + t;
;                 const float* gn = HGRN_NORM + h * 128 + 16 * cg;
;                 bf16* yp = Y_ + row * YLD + C_YB + h * 128 + 16 * cg;
;                 const float og[16] = {bflo(ogw0.x), bfhi(ogw0.x), bflo(ogw0.y), bfhi(ogw0.y), bflo(ogw0.z), bfhi(ogw0.z), bflo(ogw0.w), bfhi(ogw0.w), bflo(ogw1.x), bfhi(ogw1.x), bflo(ogw1.y), bfhi(ogw1.y), bflo(ogw1.z), bfhi(ogw1.z), bflo(ogw1.w), bfhi(ogw1.w)};
;                 const float z[16] = {bflo(zw0.x), bfhi(zw0.x), bflo(zw0.y), bfhi(zw0.y), bflo(zw0.z), bfhi(zw0.z), bflo(zw0.w), bfhi(zw0.w), bflo(zw1.x), bfhi(zw1.x), bflo(zw1.y), bfhi(zw1.y), bflo(zw1.z), bfhi(zw1.z), bflo(zw1.w), bfhi(zw1.w)};
;                 const float xv[16] = {x0.x, x0.y, x0.z, x0.w, x1.x, x1.y, x1.z, x1.w, x2.x, x2.y, x2.z, x2.w, x3.x, x3.y, x3.z, x3.w};
;                 float y[16];
; #pragma unroll
;                 for (int e = 0; e < 16; ++e) y[e] = xv[e] * inv * gn[e] * og[e] * z[e];
;                 st8bf(yp, *(float(*)[8])y); st8bf(yp + 8, *(float(*)[8])(y + 8));
;             }
	s_waitcnt lgkmcnt(0)
	v_add_f32_e32 v3, v3, v16
	v_fmamk_f32 v3, v3, 0x3c000000, v184
	s_mov_b32 s54, 0xf800000
	v_cmp_gt_f32_e32 vcc, s54, v3
	v_mul_f32_e32 v16, 0x4f800000, v3
	s_waitcnt vmcnt(3)
	v_lshlrev_b32_e32 v109, 16, v134
	v_cndmask_b32_e32 v3, v3, v16, vcc
	v_sqrt_f32_e32 v16, v3
	s_waitcnt vmcnt(1)
	v_lshlrev_b32_e32 v119, 16, v130
	v_and_b32_e32 v107, 0xffff0000, v134
	v_and_b32_e32 v118, 0xffff0000, v130
	v_add_u32_e32 v17, -1, v16
	v_fma_f32 v86, -v17, v16, v3
	v_cmp_ge_f32_e64 s[54:55], 0, v86
	v_add_u32_e32 v86, 1, v16
	v_lshlrev_b32_e32 v103, 16, v136
	v_cndmask_b32_e64 v17, v16, v17, s[54:55]
	v_fma_f32 v16, -v86, v16, v3
	v_cmp_lt_f32_e64 s[54:55], 0, v16
	v_lshlrev_b32_e32 v105, 16, v135
	v_lshlrev_b32_e32 v112, 16, v132
	v_cndmask_b32_e64 v16, v17, v86, s[54:55]
	v_mul_f32_e32 v17, 0x37800000, v16
	v_cndmask_b32_e32 v16, v16, v17, vcc
	v_cmp_class_f32_e32 vcc, v3, v185
	v_lshlrev_b32_e32 v116, 16, v131
	v_and_b32_e32 v102, 0xffff0000, v136
	v_cndmask_b32_e32 v3, v16, v3, vcc
	v_div_scale_f32 v16, s[54:55], v3, v3, 1.0
	v_rcp_f32_e32 v17, v16
	v_and_b32_e32 v104, 0xffff0000, v135
	v_and_b32_e32 v110, 0xffff0000, v132
	v_and_b32_e32 v114, 0xffff0000, v131
	v_fma_f32 v86, -v16, v17, 1.0
	v_fmac_f32_e32 v17, v86, v17
	v_div_scale_f32 v86, vcc, 1.0, v3, 1.0
	v_mul_f32_e32 v87, v86, v17
	v_fma_f32 v88, -v16, v87, v86
	v_fmac_f32_e32 v87, v88, v17
	v_fma_f32 v16, -v16, v87, v86
	v_div_fmas_f32 v16, v16, v17, v87
	global_load_dwordx4 v[86:89], v[170:171], off offset:48
	global_load_dwordx4 v[90:93], v[170:171], off offset:32
	global_load_dwordx4 v[94:97], v[170:171], off offset:16
	global_load_dwordx4 v[98:101], v[170:171], off
	v_div_fixup_f32 v3, v16, v3, 1.0
	v_mul_f32_e32 v8, v8, v3
	v_mul_f32_e32 v4, v4, v3
	v_mul_f32_e32 v82, v82, v3
	v_mul_f32_e32 v83, v83, v3
	v_mul_f32_e32 v84, v84, v3
	v_mul_f32_e32 v85, v85, v3
	v_mul_f32_e32 v12, v12, v3
	v_mul_f32_e32 v13, v13, v3
	v_mul_f32_e32 v14, v14, v3
	v_mul_f32_e32 v15, v15, v3
	v_lshlrev_b32_e32 v235, 16, v142
	v_and_b32_e32 v127, 0xffff0000, v142
	v_lshlrev_b32_e32 v126, 16, v143
	v_and_b32_e32 v122, 0xffff0000, v143
	v_lshlrev_b32_e32 v117, 16, v144
	v_and_b32_e32 v115, 0xffff0000, v144
	v_lshlrev_b32_e32 v113, 16, v145
	v_and_b32_e32 v111, 0xffff0000, v145
	v_lshlrev_b32_e32 v17, 16, v137
	v_and_b32_e32 v16, 0xffff0000, v137
	s_waitcnt vmcnt(4)
	v_lshlrev_b32_e32 v134, 16, v138
	v_and_b32_e32 v129, 0xffff0000, v138
	v_lshlrev_b32_e32 v128, 16, v139
	v_and_b32_e32 v125, 0xffff0000, v139
	v_lshlrev_b32_e32 v124, 16, v140
	v_and_b32_e32 v123, 0xffff0000, v140
	v_lshlrev_b32_e32 v121, 16, v141
	v_and_b32_e32 v120, 0xffff0000, v141
	v_lshlrev_b32_e32 v108, 16, v133
	v_and_b32_e32 v106, 0xffff0000, v133
	s_waitcnt vmcnt(3)
	v_mul_f32_e32 v4, v4, v86
	s_waitcnt vmcnt(2)
	v_mul_f32_e32 v8, v8, v90
	v_mul_f32_e32 v8, v8, v109
	v_mul_f32_e32 v90, v8, v119
	v_mul_f32_e32 v8, v9, v3
	v_mul_f32_e32 v8, v8, v91
	v_mul_f32_e32 v8, v8, v107
	v_mul_f32_e32 v91, v8, v118
	v_mul_f32_e32 v8, v10, v3
	v_mul_f32_e32 v8, v8, v92
	v_mul_f32_e32 v4, v4, v103
	v_mul_f32_e32 v8, v8, v105
	v_mul_f32_e32 v86, v4, v112
	v_mul_f32_e32 v4, v5, v3
	v_mul_f32_e32 v10, v8, v116
	v_mul_f32_e32 v8, v11, v3
	v_mul_f32_e32 v4, v4, v87
	v_mul_f32_e32 v8, v8, v93
	v_mul_f32_e32 v4, v4, v102
	v_mul_f32_e32 v8, v8, v104
	v_mul_f32_e32 v87, v4, v110
	v_mul_f32_e32 v4, v6, v3
	s_waitcnt vmcnt(0)
	v_mul_f32_e32 v82, v82, v98
	v_mul_f32_e32 v83, v83, v99
	v_mul_f32_e32 v84, v84, v100
	v_mul_f32_e32 v85, v85, v101
	v_mul_f32_e32 v12, v12, v94
	v_mul_f32_e32 v13, v13, v95
	v_mul_f32_e32 v14, v14, v96
	v_mul_f32_e32 v15, v15, v97
	v_mul_f32_e32 v11, v8, v114
	v_mul_f32_e32 v4, v4, v88
	v_mul_f32_e32 v3, v7, v3
	v_lshl_add_u64 v[8:9], s[50:51], 0, v[176:177]
	v_mul_f32_e32 v82, v82, v235
	v_mul_f32_e32 v83, v83, v127
	v_mul_f32_e32 v84, v84, v126
	v_mul_f32_e32 v85, v85, v122
	v_mul_f32_e32 v12, v12, v117
	v_mul_f32_e32 v13, v13, v115
	v_mul_f32_e32 v14, v14, v113
	v_mul_f32_e32 v15, v15, v111
	v_mul_f32_e32 v4, v4, v17
	v_mul_f32_e32 v3, v3, v89
	v_add_co_u32_e32 v8, vcc, 0x64900000, v8
	v_mul_f32_e32 v82, v82, v134
	v_mul_f32_e32 v83, v83, v129
	v_mul_f32_e32 v84, v84, v128
	v_mul_f32_e32 v85, v85, v125
	v_mul_f32_e32 v12, v12, v124
	v_mul_f32_e32 v13, v13, v123
	v_mul_f32_e32 v14, v14, v121
	v_mul_f32_e32 v15, v15, v120
	v_mul_f32_e32 v17, v4, v108
	v_mul_f32_e32 v3, v3, v16
	v_cvt_pk_bf16_f32 v4, v82, v83
	v_cvt_pk_bf16_f32 v5, v84, v85
	v_cvt_pk_bf16_f32 v6, v12, v13
	v_cvt_pk_bf16_f32 v7, v14, v15
	v_addc_co_u32_e32 v9, vcc, 0, v9, vcc
	v_mul_f32_e32 v3, v3, v106
	global_store_dwordx4 v[8:9], v[4:7], off offset:2048
	s_nop 1
	v_cvt_pk_bf16_f32 v4, v90, v91
	v_cvt_pk_bf16_f32 v5, v10, v11
	v_cvt_pk_bf16_f32 v6, v86, v87
	v_cvt_pk_bf16_f32 v7, v17, v3
	global_store_dwordx4 v[8:9], v[4:7], off offset:2064
	s_branch .LBB0_776

; #define LAS __attribute__((address_space(3)))
; DI float bf2f(unsigned short u) { return __uint_as_float((unsigned)u << 16); }
; DI unsigned f2bf(float f) { unsigned u = __float_as_uint(f); return (u + 0x7fffu + ((u >> 16) & 1u)) >> 16; }
; DI int crow(int i, int hh) { return (i & 3) + 8 * (i >> 2) + 4 * hh; }
; #define DA_BAR() do { asm volatile("s_waitcnt lgkmcnt(0)" ::: "memory"); __builtin_amdgcn_s_barrier(); asm volatile("" ::: "memory"); } while (0)
; DI void decode_unit(Ctx A_, LAS unsigned char* lds, int b, int h, float lam, int wave, int lane, int tid) {
;     ...
;     DA_BAR();
;     if (kr == 0 && mp == 0) {
;         float ssq[8];
; #pragma unroll
;         for (int i = 0; i < 8; ++i) ssq[i] = 0.f;
; #pragma unroll
;         for (int nb = 0; nb < 4; ++nb)
; #pragma unroll
;             for (int i = 0; i < 8; ++i) { const float d = acc[nb][i] - *(const LAS float*)(lds + X2_OFF + ((nb * 8 + i) * 64 + lane) * 4); acc[nb][i] = d; ssq[i] += d * d; }
; #pragma unroll
;         for (int i = 0; i < 8; ++i) { float v = ssq[i];
; #pragma unroll
;             for (int x = 1; x < 32; x <<= 1) v += __shfl_xor(v, x);
;             ssq[i] = ONE_M_LAMINIT / sqrtf(v * (1.0f / 128.0f) + NORM_EPS); }
; #pragma unroll
;         for (int nb = 0; nb < 4; ++nb) { const float sn = SUB_NORM[nb * 32 + r_e];
; #pragma unroll
;             for (int i = 0; i < 8; ++i) { const size_t rw = rowq + crow(i, hh); Y_[rw * YLD + C_YA + h * 128 + nb * 32 + r_e] = (bf16)f2bf(acc[nb][i] * ssq[i] * sn * bf2f(P[rw * PLD + C_ZA + h * 128 + nb * 32 + r_e])); } }
.LBB0_855:
	s_waitcnt lgkmcnt(0)
	s_barrier
	v_readlane_b32 s4, v255, 23
	v_readlane_b32 s5, v255, 24
	s_andn2_b64 vcc, exec, s[4:5]
	s_cbranch_vccnz .LBB0_819
	v_lshl_add_u32 v12, v165, 2, 0
	v_add_u32_e32 v13, 0x10800, v12
	v_add_u32_e32 v16, 0x10900, v12
	v_add_u32_e32 v42, 0x10f00, v12
	v_add_u32_e32 v17, 0x10a00, v12
	v_add_u32_e32 v36, 0x10b00, v12
	v_add_u32_e32 v37, 0x10c00, v12
	v_add_u32_e32 v40, 0x10d00, v12
	v_add_u32_e32 v41, 0x10e00, v12
	ds_read_b32 v13, v13
	ds_read_b32 v16, v16
	ds_read_b32 v59, v17
	ds_read_b32 v54, v36
	ds_read_b32 v50, v37
	ds_read_b32 v46, v40
	ds_read_b32 v43, v41
	ds_read_b32 v42, v42
	s_waitcnt vmcnt(0) lgkmcnt(7)
	v_sub_f32_e32 v68, v34, v13
	v_add_u32_e32 v13, 0x11000, v12
	v_add_u32_e32 v17, 0x11100, v12
	v_add_u32_e32 v34, 0x11200, v12
	v_add_u32_e32 v40, 0x11500, v12
	v_add_u32_e32 v41, 0x11600, v12
	v_add_u32_e32 v44, 0x11700, v12
	v_add_u32_e32 v36, 0x11300, v12
	v_add_u32_e32 v37, 0x11400, v12
	ds_read_b32 v13, v13
	ds_read_b32 v17, v17
	ds_read_b32 v63, v34
	ds_read_b32 v57, v36
	ds_read_b32 v53, v37
	ds_read_b32 v49, v40
	ds_read_b32 v45, v41
	ds_read_b32 v34, v44
	s_waitcnt lgkmcnt(7)
	v_sub_f32_e32 v61, v32, v13
	v_add_u32_e32 v32, 0x11800, v12
	v_add_u32_e32 v40, 0x11b00, v12
	v_add_u32_e32 v41, 0x11c00, v12
	v_add_u32_e32 v44, 0x11d00, v12
	v_add_u32_e32 v47, 0x11e00, v12
	v_add_u32_e32 v48, 0x11f00, v12
	v_readlane_b32 s64, v254, 22
	v_add_u32_e32 v36, 0x11900, v12
	v_add_u32_e32 v37, 0x11a00, v12
	ds_read_b32 v52, v32
	ds_read_b32 v69, v36
	ds_read_b32 v66, v37
	ds_read_b32 v60, v40
	ds_read_b32 v55, v41
	ds_read_b32 v51, v44
	ds_read_b32 v47, v47
	ds_read_b32 v32, v48
	s_waitcnt lgkmcnt(7)
	v_sub_f32_e32 v64, v30, v52
	v_add_u32_e32 v30, 0x12000, v12
	v_add_u32_e32 v40, 0x12300, v12
	v_add_u32_e32 v41, 0x12400, v12
	v_add_u32_e32 v44, 0x12500, v12
	v_add_u32_e32 v48, 0x12600, v12
	v_ashrrev_i32_e32 v165, 31, v164
	v_readlane_b32 s74, v254, 32
	v_readlane_b32 s75, v254, 33
	v_add_u32_e32 v36, 0x12100, v12
	v_add_u32_e32 v37, 0x12200, v12
	v_add_u32_e32 v12, 0x12700, v12
	ds_read_b32 v30, v30
	ds_read_b32 v74, v36
	ds_read_b32 v67, v37
	ds_read_b32 v62, v40
	ds_read_b32 v56, v41
	ds_read_b32 v52, v44
	ds_read_b32 v48, v48
	ds_read_b32 v44, v12
	v_lshl_add_u64 v[40:41], v[164:165], 2, s[74:75]
	s_waitcnt lgkmcnt(7)
	v_sub_f32_e32 v65, v38, v30
	global_load_dword v38, v[40:41], off
	v_mul_f32_e32 v13, v61, v61
	v_fmac_f32_e32 v13, v68, v68
	v_fmac_f32_e32 v13, v64, v64
	v_fmac_f32_e32 v13, v65, v65
	s_nop 1
	v_mov_b32_dpp v12, v13 quad_perm:[1,0,3,2] row_mask:0xf bank_mask:0xf
	v_readlane_b32 s4, v255, 9
	v_readlane_b32 s5, v255, 10
	v_lshl_or_b32 v58, v179, 2, s61
	s_lshl_b32 s2, s60, 1
	v_mov_b64_e32 v[36:37], s[4:5]
	v_mad_u64_u32 v[70:71], s[4:5], v58, s53, v[36:37]
	v_mad_i32_i24 v71, s59, v174, v71
	s_waitcnt lgkmcnt(0)
	v_add_f32_e32 v30, v13, v12
	v_lshlrev_b64 v[12:13], 1, v[164:165]
	v_lshl_add_u64 v[70:71], v[70:71], 0, s[2:3]
	v_lshl_add_u64 v[72:73], v[70:71], 0, v[12:13]
	v_add_co_u32_e32 v70, vcc, s54, v72
	v_sub_f32_e32 v76, v35, v16
	s_nop 0
	v_addc_co_u32_e32 v71, vcc, 0, v73, vcc
	global_load_ushort v75, v[70:71], off offset:2048
	s_nop 1
	v_mov_b32_dpp v70, v30 quad_perm:[2,3,0,1] row_mask:0xf bank_mask:0xf
	v_sub_f32_e32 v69, v31, v69
	v_sub_f32_e32 v71, v33, v17
	v_mul_f32_e32 v17, v71, v71
	v_fmac_f32_e32 v17, v76, v76
	s_waitcnt lgkmcnt(0)
	v_add_f32_e32 v30, v30, v70
	s_nop 1
	v_mov_b32_dpp v70, v30 row_half_mirror row_mask:0xf bank_mask:0xf
	v_fmac_f32_e32 v17, v69, v69
	v_sub_f32_e32 v28, v28, v59
	v_sub_f32_e32 v66, v24, v66
	v_sub_f32_e32 v63, v26, v63
	s_waitcnt lgkmcnt(0)
	v_add_f32_e32 v30, v30, v70
	s_nop 1
	v_mov_b32_dpp v70, v30 row_mirror row_mask:0xf bank_mask:0xf
	v_sub_f32_e32 v67, v22, v67
	v_mul_f32_e32 v26, v63, v63
	v_fmac_f32_e32 v26, v28, v28
	v_fmac_f32_e32 v26, v66, v66
	s_waitcnt lgkmcnt(0)
	v_add_f32_e32 v16, v30, v70
	ds_bpermute_b32 v30, v209, v16
	v_sub_f32_e32 v70, v39, v74
	v_fmac_f32_e32 v17, v70, v70
	v_fmac_f32_e32 v26, v67, v67
	v_sub_f32_e32 v29, v29, v54
	s_waitcnt lgkmcnt(0)
	v_add_f32_e32 v16, v16, v30
	v_fmamk_f32 v16, v16, 0x3c000000, v172
	v_mul_f32_e32 v30, 0x4f800000, v16
	v_cmp_gt_f32_e32 vcc, s55, v16
	v_sub_f32_e32 v54, v27, v57
	v_sub_f32_e32 v57, v25, v60
	v_cndmask_b32_e32 v16, v16, v30, vcc
	v_sqrt_f32_e32 v30, v16
	v_sub_f32_e32 v60, v23, v62
	v_mul_f32_e32 v27, v54, v54
	v_fmac_f32_e32 v27, v29, v29
	v_add_u32_e32 v31, -1, v30
	v_fma_f32 v33, -v31, v30, v16
	v_cmp_ge_f32_e64 s[4:5], 0, v33
	v_add_u32_e32 v33, 1, v30
	v_fmac_f32_e32 v27, v57, v57
	v_cndmask_b32_e64 v31, v30, v31, s[4:5]
	v_fma_f32 v30, -v33, v30, v16
	v_cmp_lt_f32_e64 s[4:5], 0, v30
	v_fmac_f32_e32 v27, v60, v60
	v_sub_f32_e32 v20, v20, v50
	v_cndmask_b32_e64 v30, v31, v33, s[4:5]
	v_mul_f32_e32 v31, 0x37800000, v30
	s_nop 1
	v_mov_b32_dpp v33, v17 quad_perm:[1,0,3,2] row_mask:0xf bank_mask:0xf
	v_cndmask_b32_e32 v30, v30, v31, vcc
	v_cmp_class_f32_e32 vcc, v16, v173
	v_sub_f32_e32 v50, v18, v53
	v_sub_f32_e32 v53, v14, v55
	v_cndmask_b32_e32 v16, v30, v16, vcc
	v_div_scale_f32 v30, s[4:5], v16, v16, s56
	v_rcp_f32_e32 v31, v30
	s_waitcnt lgkmcnt(0)
	v_add_f32_e32 v17, v17, v33
	s_nop 1
	v_mov_b32_dpp v33, v17 quad_perm:[2,3,0,1] row_mask:0xf bank_mask:0xf
	s_add_u32 s4, s44, s2
	v_fma_f32 v35, -v30, v31, 1.0
	v_fmac_f32_e32 v31, v35, v31
	v_div_scale_f32 v35, vcc, s56, v16, s56
	v_mul_f32_e32 v39, v35, v31
	v_fma_f32 v74, -v30, v39, v35
	s_waitcnt lgkmcnt(0)
	v_add_f32_e32 v17, v17, v33
	v_fmac_f32_e32 v39, v74, v31
	s_nop 1
	v_mov_b32_dpp v33, v17 row_half_mirror row_mask:0xf bank_mask:0xf
	v_fma_f32 v30, -v30, v39, v35
	v_div_fmas_f32 v30, v30, v31, v39
	v_div_fixup_f32 v74, v30, v16, s56
	v_mul_f32_e32 v68, v68, v74
	v_lshl_add_u64 v[30:31], v[72:73], 0, s[14:15]
	s_waitcnt lgkmcnt(0)
; #define LAS __attribute__((address_space(3)))
; DI float bf2f(unsigned short u) { return __uint_as_float((unsigned)u << 16); }
; DI unsigned f2bf(float f) { unsigned u = __float_as_uint(f); return (u + 0x7fffu + ((u >> 16) & 1u)) >> 16; }
; DI int crow(int i, int hh) { return (i & 3) + 8 * (i >> 2) + 4 * hh; }
; DI void decode_unit(Ctx A_, LAS unsigned char* lds, int b, int h, float lam, int wave, int lane, int tid) {
;     ...
;     if (kr == 0 && mp == 0) {
;         float ssq[8];
; #pragma unroll
;         for (int i = 0; i < 8; ++i) ssq[i] = 0.f;
; #pragma unroll
;         for (int nb = 0; nb < 4; ++nb)
; #pragma unroll
;             for (int i = 0; i < 8; ++i) { const float d = acc[nb][i] - *(const LAS float*)(lds + X2_OFF + ((nb * 8 + i) * 64 + lane) * 4); acc[nb][i] = d; ssq[i] += d * d; }
; #pragma unroll
;         for (int i = 0; i < 8; ++i) { float v = ssq[i];
; #pragma unroll
;             for (int x = 1; x < 32; x <<= 1) v += __shfl_xor(v, x);
;             ssq[i] = ONE_M_LAMINIT / sqrtf(v * (1.0f / 128.0f) + NORM_EPS); }
; #pragma unroll
;         for (int nb = 0; nb < 4; ++nb) { const float sn = SUB_NORM[nb * 32 + r_e];
; #pragma unroll
;             for (int i = 0; i < 8; ++i) { const size_t rw = rowq + crow(i, hh); Y_[rw * YLD + C_YA + h * 128 + nb * 32 + r_e] = (bf16)f2bf(acc[nb][i] * ssq[i] * sn * bf2f(P[rw * PLD + C_ZA + h * 128 + nb * 32 + r_e])); } }
	v_add_f32_e32 v77, v17, v33
	global_load_ushort v79, v[30:31], off offset:64
	global_load_dword v33, v[40:41], off offset:128
	global_load_dword v35, v[40:41], off offset:256
	global_load_dword v39, v[40:41], off offset:384
	s_waitcnt vmcnt(5)
	v_mul_f32_e32 v40, v68, v38
	global_load_ushort v68, v[30:31], off offset:128
	global_load_ushort v80, v[30:31], off offset:192
	s_addc_u32 s5, s45, 0
	v_lshl_add_u64 v[16:17], s[4:5], 0, v[12:13]
	s_nop 1
	v_mov_b32_dpp v78, v77 row_mirror row_mask:0xf bank_mask:0xf
	s_waitcnt vmcnt(6)
	v_lshlrev_b32_e32 v30, 16, v75
	v_mul_f32_e32 v30, v40, v30
	v_bfe_u32 v31, v30, 16, 1
	v_add3_u32 v40, v30, v31, s57
	v_mad_u64_u32 v[30:31], s[4:5], v58, s58, v[16:17]
	v_mad_i32_i24 v31, s59, v178, v31
	v_or_b32_e32 v75, 1, v58
	global_store_short_d16_hi v[30:31], v40, off
	v_mad_u64_u32 v[40:41], s[4:5], v75, s53, v[36:37]
	v_mad_i32_i24 v41, s59, v174, v41
	v_lshl_add_u64 v[40:41], v[40:41], 0, s[2:3]
	v_lshl_add_u64 v[40:41], v[40:41], 0, v[12:13]
	v_add_co_u32_e32 v72, vcc, s54, v40
	s_waitcnt lgkmcnt(0)
	v_add_f32_e32 v59, v77, v78
	v_addc_co_u32_e32 v73, vcc, 0, v41, vcc
	global_load_ushort v72, v[72:73], off offset:2048
	ds_bpermute_b32 v73, v209, v59
	v_mul_f32_e32 v61, v61, v74
	v_mul_f32_e32 v64, v64, v74
	v_lshl_add_u64 v[40:41], v[40:41], 0, s[14:15]
	v_mul_f32_e32 v18, v50, v50
	s_waitcnt lgkmcnt(0)
	v_add_f32_e32 v24, v59, v73
	v_fmamk_f32 v24, v24, 0x3c000000, v172
	v_mul_f32_e32 v59, 0x4f800000, v24
	v_cmp_gt_f32_e32 vcc, s55, v24
	v_fmac_f32_e32 v18, v20, v20
	v_fmac_f32_e32 v18, v53, v53
	v_cndmask_b32_e32 v24, v24, v59, vcc
	v_sqrt_f32_e32 v59, v24
	v_sub_f32_e32 v21, v21, v46
	v_sub_f32_e32 v8, v8, v43
	v_sub_f32_e32 v9, v9, v42
	v_add_u32_e32 v22, -1, v59
	v_fma_f32 v73, -v22, v59, v24
	v_cmp_ge_f32_e64 s[4:5], 0, v73
	v_add_u32_e32 v73, 1, v59
	v_readlane_b32 s65, v254, 23
	v_cndmask_b32_e64 v22, v59, v22, s[4:5]
	v_fma_f32 v59, -v73, v59, v24
	v_cmp_lt_f32_e64 s[4:5], 0, v59
	v_readlane_b32 s66, v254, 24
	v_readlane_b32 s67, v254, 25
	v_cndmask_b32_e64 v22, v22, v73, s[4:5]
	s_nop 1
	v_mov_b32_dpp v73, v26 quad_perm:[1,0,3,2] row_mask:0xf bank_mask:0xf
	v_mul_f32_e32 v59, 0x37800000, v22
	v_cndmask_b32_e32 v22, v22, v59, vcc
	v_cmp_class_f32_e32 vcc, v24, v173
	v_readlane_b32 s68, v254, 26
	s_waitcnt lgkmcnt(0)
	v_add_f32_e32 v26, v26, v73
	v_cndmask_b32_e32 v22, v22, v24, vcc
	v_div_scale_f32 v24, s[4:5], v22, v22, s56
	v_rcp_f32_e32 v59, v24
	s_nop 1
	v_mov_b32_dpp v73, v26 quad_perm:[2,3,0,1] row_mask:0xf bank_mask:0xf
	v_readlane_b32 s69, v254, 27
	v_readlane_b32 s70, v254, 28
	v_fma_f32 v77, -v24, v59, 1.0
	v_fmac_f32_e32 v59, v77, v59
	v_div_scale_f32 v77, vcc, s56, v22, s56
	s_waitcnt lgkmcnt(0)
	v_add_f32_e32 v26, v26, v73
	v_mul_f32_e32 v78, v77, v59
	s_nop 1
	v_mov_b32_dpp v73, v26 row_half_mirror row_mask:0xf bank_mask:0xf
	v_fma_f32 v81, -v24, v78, v77
	v_fmac_f32_e32 v78, v81, v59
	v_fma_f32 v24, -v24, v78, v77
	v_div_fmas_f32 v24, v24, v59, v78
	v_div_fixup_f32 v24, v24, v22, s56
	s_waitcnt lgkmcnt(0)
	v_add_f32_e32 v22, v26, v73
	s_waitcnt vmcnt(6)
	v_mul_f32_e32 v61, v61, v33
	v_lshlrev_b32_e32 v73, 16, v79
	v_mul_f32_e32 v61, v61, v73
	s_waitcnt vmcnt(5)
	v_mul_f32_e32 v64, v64, v35
	s_waitcnt vmcnt(3)
	v_lshlrev_b32_e32 v68, 16, v68
	v_bfe_u32 v73, v61, 16, 1
	v_mul_f32_e32 v64, v64, v68
	v_add3_u32 v61, v61, v73, s57
	v_bfe_u32 v68, v64, 16, 1
	global_store_short_d16_hi v[30:31], v61, off offset:64
	v_add3_u32 v64, v64, v68, s57
	global_load_ushort v61, v[40:41], off offset:64
	v_mul_f32_e32 v59, v76, v24
	global_store_short_d16_hi v[30:31], v64, off offset:128
	v_mul_f32_e32 v64, v65, v74
	v_mul_f32_e32 v64, v64, v39
	s_waitcnt vmcnt(5)
	v_lshlrev_b32_e32 v65, 16, v80
	v_mul_f32_e32 v64, v64, v65
	v_bfe_u32 v65, v64, 16, 1
	v_add3_u32 v64, v64, v65, s57
	global_store_short_d16_hi v[30:31], v64, off offset:192
	global_load_ushort v68, v[40:41], off offset:128
	global_load_ushort v73, v[40:41], off offset:192
	v_mul_f32_e32 v59, v59, v38
	s_nop 1
	v_mov_b32_dpp v26, v22 row_mirror row_mask:0xf bank_mask:0xf
	v_readlane_b32 s71, v254, 29
	v_readlane_b32 s72, v254, 30
	s_waitcnt vmcnt(6)
	v_lshlrev_b32_e32 v30, 16, v72
	v_mul_f32_e32 v30, v59, v30
	v_bfe_u32 v31, v30, 16, 1
	v_add3_u32 v40, v30, v31, s57
	v_mad_u64_u32 v[30:31], s[4:5], v75, s58, v[16:17]
	v_mad_i32_i24 v31, s59, v178, v31
	v_or_b32_e32 v59, 2, v58
	global_store_short_d16_hi v[30:31], v40, off
	v_mad_u64_u32 v[40:41], s[4:5], v59, s53, v[36:37]
	v_mad_i32_i24 v41, s59, v174, v41
	v_lshl_add_u64 v[40:41], v[40:41], 0, s[2:3]
	v_lshl_add_u64 v[40:41], v[40:41], 0, v[12:13]
	v_add_co_u32_e32 v64, vcc, s54, v40
	s_waitcnt lgkmcnt(0)
	v_add_f32_e32 v22, v22, v26
	v_addc_co_u32_e32 v65, vcc, 0, v41, vcc
	global_load_ushort v64, v[64:65], off offset:2048
	ds_bpermute_b32 v26, v209, v22
	v_readlane_b32 s73, v254, 31
	v_readlane_b32 s76, v254, 34
	v_readlane_b32 s77, v254, 35
	v_readlane_b32 s78, v254, 36
	s_waitcnt lgkmcnt(0)
	v_add_f32_e32 v22, v22, v26
	v_fmamk_f32 v22, v22, 0x3c000000, v172
	v_mul_f32_e32 v25, 0x4f800000, v22
	v_cmp_gt_f32_e32 vcc, s55, v22
	v_readlane_b32 s79, v254, 37
	s_nop 0
	v_cndmask_b32_e32 v22, v22, v25, vcc
	v_sqrt_f32_e32 v25, v22
	s_nop 0
	v_add_u32_e32 v23, -1, v25
	v_fma_f32 v26, -v23, v25, v22
	v_cmp_ge_f32_e64 s[4:5], 0, v26
	v_add_u32_e32 v26, 1, v25
	s_nop 0
	v_cndmask_b32_e64 v23, v25, v23, s[4:5]
	v_fma_f32 v25, -v26, v25, v22
	v_cmp_lt_f32_e64 s[4:5], 0, v25
	s_nop 1
	v_cndmask_b32_e64 v23, v23, v26, s[4:5]
	s_nop 1
	v_mov_b32_dpp v26, v27 quad_perm:[1,0,3,2] row_mask:0xf bank_mask:0xf
	v_mul_f32_e32 v25, 0x37800000, v23
	v_cndmask_b32_e32 v23, v23, v25, vcc
	v_cmp_class_f32_e32 vcc, v22, v173
	s_waitcnt lgkmcnt(0)
; #define LAS __attribute__((address_space(3)))
; DI float bf2f(unsigned short u) { return __uint_as_float((unsigned)u << 16); }
; DI unsigned f2bf(float f) { unsigned u = __float_as_uint(f); return (u + 0x7fffu + ((u >> 16) & 1u)) >> 16; }
; DI int crow(int i, int hh) { return (i & 3) + 8 * (i >> 2) + 4 * hh; }
; DI void decode_unit(Ctx A_, LAS unsigned char* lds, int b, int h, float lam, int wave, int lane, int tid) {
;     ...
;     if (kr == 0 && mp == 0) {
;         float ssq[8];
; #pragma unroll
;         for (int i = 0; i < 8; ++i) ssq[i] = 0.f;
; #pragma unroll
;         for (int nb = 0; nb < 4; ++nb)
; #pragma unroll
;             for (int i = 0; i < 8; ++i) { const float d = acc[nb][i] - *(const LAS float*)(lds + X2_OFF + ((nb * 8 + i) * 64 + lane) * 4); acc[nb][i] = d; ssq[i] += d * d; }
; #pragma unroll
;         for (int i = 0; i < 8; ++i) { float v = ssq[i];
; #pragma unroll
;             for (int x = 1; x < 32; x <<= 1) v += __shfl_xor(v, x);
;             ssq[i] = ONE_M_LAMINIT / sqrtf(v * (1.0f / 128.0f) + NORM_EPS); }
; #pragma unroll
;         for (int nb = 0; nb < 4; ++nb) { const float sn = SUB_NORM[nb * 32 + r_e];
; #pragma unroll
;             for (int i = 0; i < 8; ++i) { const size_t rw = rowq + crow(i, hh); Y_[rw * YLD + C_YA + h * 128 + nb * 32 + r_e] = (bf16)f2bf(acc[nb][i] * ssq[i] * sn * bf2f(P[rw * PLD + C_ZA + h * 128 + nb * 32 + r_e])); } }
	v_add_f32_e32 v26, v27, v26
	v_cndmask_b32_e32 v22, v23, v22, vcc
	v_div_scale_f32 v23, s[4:5], v22, v22, s56
	s_nop 1
	v_mov_b32_dpp v27, v26 quad_perm:[2,3,0,1] row_mask:0xf bank_mask:0xf
	v_rcp_f32_e32 v25, v23
	s_waitcnt lgkmcnt(0)
	v_add_f32_e32 v26, v26, v27
	v_fma_f32 v62, -v23, v25, 1.0
	v_fmac_f32_e32 v25, v62, v25
	v_div_scale_f32 v62, vcc, s56, v22, s56
	s_nop 1
	v_mov_b32_dpp v27, v26 row_half_mirror row_mask:0xf bank_mask:0xf
	v_mul_f32_e32 v65, v62, v25
	v_fma_f32 v72, -v23, v65, v62
	v_fmac_f32_e32 v65, v72, v25
	v_fma_f32 v23, -v23, v65, v62
	v_div_fmas_f32 v23, v23, v25, v65
	s_waitcnt lgkmcnt(0)
	v_add_f32_e32 v65, v26, v27
	v_mul_f32_e32 v26, v71, v24
	v_mul_f32_e32 v26, v26, v33
	s_waitcnt vmcnt(6)
	v_lshlrev_b32_e32 v27, 16, v61
	v_mul_f32_e32 v26, v26, v27
	v_bfe_u32 v27, v26, 16, 1
	v_add3_u32 v26, v26, v27, s57
	global_store_short_d16_hi v[30:31], v26, off offset:64
	v_mul_f32_e32 v26, v69, v24
	v_div_fixup_f32 v62, v23, v22, s56
	v_mul_f32_e32 v26, v26, v35
	s_waitcnt vmcnt(4)
	v_lshlrev_b32_e32 v27, 16, v68
	v_mul_f32_e32 v22, v28, v62
	v_mul_f32_e32 v26, v26, v27
	v_mul_f32_e32 v25, v22, v38
	v_lshl_add_u64 v[22:23], v[40:41], 0, s[14:15]
	v_bfe_u32 v27, v26, 16, 1
	global_load_ushort v28, v[22:23], off offset:64
	v_add3_u32 v26, v26, v27, s57
	v_mul_f32_e32 v24, v70, v24
	global_store_short_d16_hi v[30:31], v26, off offset:128
	v_mul_f32_e32 v24, v24, v39
	s_waitcnt vmcnt(5)
	v_lshlrev_b32_e32 v26, 16, v73
	v_mul_f32_e32 v24, v24, v26
	v_bfe_u32 v26, v24, 16, 1
	v_add3_u32 v24, v24, v26, s57
	global_store_short_d16_hi v[30:31], v24, off offset:192
	global_load_ushort v30, v[22:23], off offset:128
	s_nop 0
	global_load_ushort v31, v[22:23], off offset:192
	s_waitcnt vmcnt(6)
	v_lshlrev_b32_e32 v22, 16, v64
	v_mul_f32_e32 v22, v25, v22
	v_bfe_u32 v23, v22, 16, 1
	v_add3_u32 v24, v22, v23, s57
	v_mad_u64_u32 v[22:23], s[4:5], v59, s58, v[16:17]
	v_mad_i32_i24 v23, s59, v178, v23
	v_or_b32_e32 v40, 3, v58
	global_store_short_d16_hi v[22:23], v24, off
	v_mad_u64_u32 v[24:25], s[4:5], v40, s53, v[36:37]
	s_nop 1
	v_mov_b32_dpp v72, v65 row_mirror row_mask:0xf bank_mask:0xf
	v_mad_i32_i24 v25, s59, v174, v25
	v_lshl_add_u64 v[24:25], v[24:25], 0, s[2:3]
	v_lshl_add_u64 v[24:25], v[24:25], 0, v[12:13]
	v_add_co_u32_e32 v26, vcc, s54, v24
	s_nop 1
	v_addc_co_u32_e32 v27, vcc, 0, v25, vcc
	global_load_ushort v26, v[26:27], off offset:2048
	s_waitcnt lgkmcnt(0)
	v_add_f32_e32 v27, v65, v72
	ds_bpermute_b32 v41, v209, v27
	v_lshl_add_u64 v[24:25], v[24:25], 0, s[14:15]
	s_waitcnt lgkmcnt(0)
	v_add_f32_e32 v14, v27, v41
	v_fmamk_f32 v14, v14, 0x3c000000, v172
	v_mul_f32_e32 v27, 0x4f800000, v14
	v_cmp_gt_f32_e32 vcc, s55, v14
	v_sub_f32_e32 v41, v10, v56
	v_fmac_f32_e32 v18, v41, v41
	v_cndmask_b32_e32 v14, v14, v27, vcc
	v_sqrt_f32_e32 v27, v14
	s_nop 0
	v_add_u32_e32 v10, -1, v27
	v_fma_f32 v55, -v10, v27, v14
	v_cmp_ge_f32_e64 s[4:5], 0, v55
	v_add_u32_e32 v55, 1, v27
	s_nop 0
	v_cndmask_b32_e64 v10, v27, v10, s[4:5]
	v_fma_f32 v27, -v55, v27, v14
	v_cmp_lt_f32_e64 s[4:5], 0, v27
	s_nop 1
	v_cndmask_b32_e64 v10, v10, v55, s[4:5]
	s_nop 1
	v_mov_b32_dpp v55, v18 quad_perm:[1,0,3,2] row_mask:0xf bank_mask:0xf
	v_mul_f32_e32 v27, 0x37800000, v10
	v_cndmask_b32_e32 v10, v10, v27, vcc
	v_cmp_class_f32_e32 vcc, v14, v173
	s_waitcnt lgkmcnt(0)
	v_add_f32_e32 v18, v18, v55
	v_cndmask_b32_e32 v10, v10, v14, vcc
	v_div_scale_f32 v14, s[4:5], v10, v10, s56
	v_rcp_f32_e32 v27, v14
	s_nop 1
	v_mov_b32_dpp v55, v18 quad_perm:[2,3,0,1] row_mask:0xf bank_mask:0xf
	v_fma_f32 v56, -v14, v27, 1.0
	v_fmac_f32_e32 v27, v56, v27
	v_div_scale_f32 v56, vcc, s56, v10, s56
	s_waitcnt lgkmcnt(0)
	v_add_f32_e32 v18, v18, v55
	v_mul_f32_e32 v59, v56, v27
	s_nop 1
	v_mov_b32_dpp v55, v18 row_half_mirror row_mask:0xf bank_mask:0xf
	v_fma_f32 v61, -v14, v59, v56
	v_fmac_f32_e32 v59, v61, v27
	v_fma_f32 v14, -v14, v59, v56
	v_div_fmas_f32 v14, v14, v27, v59
	v_div_fixup_f32 v14, v14, v10, s56
	s_waitcnt lgkmcnt(0)
	v_add_f32_e32 v10, v18, v55
	v_mul_f32_e32 v18, v63, v62
	v_mul_f32_e32 v18, v18, v33
	s_waitcnt vmcnt(6)
	v_lshlrev_b32_e32 v27, 16, v28
	v_mul_f32_e32 v18, v18, v27
	v_bfe_u32 v27, v18, 16, 1
	v_add3_u32 v18, v18, v27, s57
	global_store_short_d16_hi v[22:23], v18, off offset:64
	v_mul_f32_e32 v27, v66, v62
	global_load_ushort v18, v[24:25], off offset:64
	v_mul_f32_e32 v27, v27, v35
	s_waitcnt vmcnt(5)
	v_lshlrev_b32_e32 v28, 16, v30
	v_mul_f32_e32 v27, v27, v28
	v_bfe_u32 v28, v27, 16, 1
	v_add3_u32 v27, v27, v28, s57
	global_store_short_d16_hi v[22:23], v27, off offset:128
	v_mul_f32_e32 v27, v67, v62
	global_load_ushort v28, v[24:25], off offset:128
	v_mul_f32_e32 v27, v27, v39
	s_waitcnt vmcnt(6)
	v_lshlrev_b32_e32 v30, 16, v31
	v_mul_f32_e32 v27, v27, v30
	v_bfe_u32 v30, v27, 16, 1
	v_add3_u32 v27, v27, v30, s57
	global_store_short_d16_hi v[22:23], v27, off offset:192
	global_load_ushort v30, v[24:25], off offset:192
	v_mul_f32_e32 v22, v29, v14
	v_mul_f32_e32 v22, v22, v38
	s_waitcnt vmcnt(6)
	v_lshlrev_b32_e32 v23, 16, v26
	v_mul_f32_e32 v22, v22, v23
	v_bfe_u32 v23, v22, 16, 1
	v_add3_u32 v24, v22, v23, s57
	v_mad_u64_u32 v[22:23], s[4:5], v40, s58, v[16:17]
	v_mad_i32_i24 v23, s59, v178, v23
	v_or_b32_e32 v29, 8, v58
	s_nop 1
	v_mov_b32_dpp v31, v10 row_mirror row_mask:0xf bank_mask:0xf
	global_store_short_d16_hi v[22:23], v24, off
	v_mad_u64_u32 v[24:25], s[4:5], v29, s53, v[36:37]
	v_mad_i32_i24 v25, s59, v174, v25
	v_lshl_add_u64 v[24:25], v[24:25], 0, s[2:3]
	v_lshl_add_u64 v[24:25], v[24:25], 0, v[12:13]
	v_add_co_u32_e32 v26, vcc, s54, v24
	s_waitcnt lgkmcnt(0)
; #define LAS __attribute__((address_space(3)))
; DI float bf2f(unsigned short u) { return __uint_as_float((unsigned)u << 16); }
; DI unsigned f2bf(float f) { unsigned u = __float_as_uint(f); return (u + 0x7fffu + ((u >> 16) & 1u)) >> 16; }
; DI int crow(int i, int hh) { return (i & 3) + 8 * (i >> 2) + 4 * hh; }
; DI void decode_unit(Ctx A_, LAS unsigned char* lds, int b, int h, float lam, int wave, int lane, int tid) {
;     ...
;     if (kr == 0 && mp == 0) {
;         float ssq[8];
; #pragma unroll
;         for (int i = 0; i < 8; ++i) ssq[i] = 0.f;
; #pragma unroll
;         for (int nb = 0; nb < 4; ++nb)
; #pragma unroll
;             for (int i = 0; i < 8; ++i) { const float d = acc[nb][i] - *(const LAS float*)(lds + X2_OFF + ((nb * 8 + i) * 64 + lane) * 4); acc[nb][i] = d; ssq[i] += d * d; }
; #pragma unroll
;         for (int i = 0; i < 8; ++i) { float v = ssq[i];
; #pragma unroll
;             for (int x = 1; x < 32; x <<= 1) v += __shfl_xor(v, x);
;             ssq[i] = ONE_M_LAMINIT / sqrtf(v * (1.0f / 128.0f) + NORM_EPS); }
; #pragma unroll
;         for (int nb = 0; nb < 4; ++nb) { const float sn = SUB_NORM[nb * 32 + r_e];
; #pragma unroll
;             for (int i = 0; i < 8; ++i) { const size_t rw = rowq + crow(i, hh); Y_[rw * YLD + C_YA + h * 128 + nb * 32 + r_e] = (bf16)f2bf(acc[nb][i] * ssq[i] * sn * bf2f(P[rw * PLD + C_ZA + h * 128 + nb * 32 + r_e])); } }
	v_add_f32_e32 v10, v10, v31
	v_addc_co_u32_e32 v27, vcc, 0, v25, vcc
	global_load_ushort v26, v[26:27], off offset:2048
	ds_bpermute_b32 v27, v209, v10
	v_sub_f32_e32 v40, v15, v51
	v_sub_f32_e32 v31, v19, v49
	v_mul_f32_e32 v19, v31, v31
	v_fmac_f32_e32 v19, v21, v21
	s_waitcnt lgkmcnt(0)
	v_add_f32_e32 v10, v10, v27
	v_fmamk_f32 v10, v10, 0x3c000000, v172
	v_mul_f32_e32 v15, 0x4f800000, v10
	v_cmp_gt_f32_e32 vcc, s55, v10
	v_sub_f32_e32 v27, v11, v52
	v_fmac_f32_e32 v19, v40, v40
	v_cndmask_b32_e32 v10, v10, v15, vcc
	v_sqrt_f32_e32 v15, v10
	v_fmac_f32_e32 v19, v27, v27
	v_add_u32_e32 v11, -1, v15
	v_fma_f32 v46, -v11, v15, v10
	v_cmp_ge_f32_e64 s[4:5], 0, v46
	v_add_u32_e32 v46, 1, v15
	s_waitcnt vmcnt(6)
	v_lshlrev_b32_e32 v18, 16, v18
	v_cndmask_b32_e64 v11, v15, v11, s[4:5]
	v_fma_f32 v15, -v46, v15, v10
	v_cmp_lt_f32_e64 s[4:5], 0, v15
	s_nop 1
	v_cndmask_b32_e64 v11, v11, v46, s[4:5]
	v_mul_f32_e32 v15, 0x37800000, v11
	v_cndmask_b32_e32 v11, v11, v15, vcc
	v_cmp_class_f32_e32 vcc, v10, v173
	s_nop 1
	v_cndmask_b32_e32 v15, v11, v10, vcc
	v_div_scale_f32 v46, s[4:5], v15, v15, s56
	v_rcp_f32_e32 v49, v46
	s_nop 1
	v_mov_b32_dpp v10, v19 quad_perm:[1,0,3,2] row_mask:0xf bank_mask:0xf
	v_fma_f32 v11, -v46, v49, 1.0
	v_fmac_f32_e32 v49, v11, v49
	s_waitcnt lgkmcnt(0)
	v_add_f32_e32 v19, v19, v10
	v_lshl_add_u64 v[10:11], v[24:25], 0, s[14:15]
	v_mul_f32_e32 v24, v54, v14
	v_mul_f32_e32 v24, v24, v33
	v_mul_f32_e32 v18, v24, v18
	v_bfe_u32 v24, v18, 16, 1
	v_add3_u32 v18, v18, v24, s57
	global_store_short_d16_hi v[22:23], v18, off offset:64
	v_mul_f32_e32 v18, v57, v14
	global_load_ushort v24, v[10:11], off offset:64
	v_mul_f32_e32 v18, v18, v35
	s_waitcnt vmcnt(6)
	v_lshlrev_b32_e32 v25, 16, v28
	v_mul_f32_e32 v18, v18, v25
	v_bfe_u32 v25, v18, 16, 1
	v_add3_u32 v18, v18, v25, s57
	global_store_short_d16_hi v[22:23], v18, off offset:128
	v_mul_f32_e32 v14, v60, v14
	global_load_ushort v25, v[10:11], off offset:128
	v_mul_f32_e32 v14, v14, v39
	s_waitcnt vmcnt(6)
	v_lshlrev_b32_e32 v18, 16, v30
	v_mul_f32_e32 v14, v14, v18
	v_bfe_u32 v18, v14, 16, 1
	v_add3_u32 v14, v14, v18, s57
	global_store_short_d16_hi v[22:23], v14, off offset:192
	global_load_ushort v22, v[10:11], off offset:192
	s_nop 1
	v_mov_b32_dpp v10, v19 quad_perm:[2,3,0,1] row_mask:0xf bank_mask:0xf
	v_div_scale_f32 v11, vcc, s56, v15, s56
	v_mul_f32_e32 v14, v11, v49
	v_fma_f32 v18, -v46, v14, v11
	s_waitcnt lgkmcnt(0)
	v_add_f32_e32 v10, v19, v10
	v_fmac_f32_e32 v14, v18, v49
	s_nop 1
	v_mov_b32_dpp v18, v10 row_half_mirror row_mask:0xf bank_mask:0xf
	v_fma_f32 v11, -v46, v14, v11
	v_div_fmas_f32 v11, v11, v49, v14
	v_div_fixup_f32 v23, v11, v15, s56
	s_waitcnt vmcnt(6)
	v_lshlrev_b32_e32 v11, 16, v26
	s_waitcnt lgkmcnt(0)
	v_add_f32_e32 v28, v10, v18
	v_mul_f32_e32 v10, v20, v23
	v_mul_f32_e32 v10, v10, v38
	v_mul_f32_e32 v10, v10, v11
	v_bfe_u32 v11, v10, 16, 1
	v_add3_u32 v14, v10, v11, s57
	v_mad_u64_u32 v[10:11], s[4:5], v29, s58, v[16:17]
	v_mad_i32_i24 v11, s59, v178, v11
	v_or_b32_e32 v20, 9, v58
	global_store_short_d16_hi v[10:11], v14, off
	v_mad_u64_u32 v[14:15], s[4:5], v20, s53, v[36:37]
	s_nop 1
	v_mov_b32_dpp v30, v28 row_mirror row_mask:0xf bank_mask:0xf
	v_mad_i32_i24 v15, s59, v174, v15
	v_lshl_add_u64 v[14:15], v[14:15], 0, s[2:3]
	v_lshl_add_u64 v[14:15], v[14:15], 0, v[12:13]
	v_add_co_u32_e32 v18, vcc, s54, v14
	v_sub_f32_e32 v29, v2, v47
	s_nop 0
	v_addc_co_u32_e32 v19, vcc, 0, v15, vcc
	global_load_ushort v18, v[18:19], off offset:2048
	s_waitcnt lgkmcnt(0)
	v_add_f32_e32 v19, v28, v30
	ds_bpermute_b32 v26, v209, v19
	v_lshl_add_u64 v[14:15], v[14:15], 0, s[14:15]
	v_sub_f32_e32 v28, v6, v45
	v_mul_f32_e32 v6, v28, v28
	v_fmac_f32_e32 v6, v8, v8
	s_waitcnt lgkmcnt(0)
	v_add_f32_e32 v2, v19, v26
	v_fmamk_f32 v2, v2, 0x3c000000, v172
	v_mul_f32_e32 v19, 0x4f800000, v2
	v_cmp_gt_f32_e32 vcc, s55, v2
	v_sub_f32_e32 v26, v4, v48
	v_fmac_f32_e32 v6, v29, v29
	v_cndmask_b32_e32 v2, v2, v19, vcc
	v_sqrt_f32_e32 v19, v2
	v_fmac_f32_e32 v6, v26, v26
	v_add_u32_e32 v4, -1, v19
	v_fma_f32 v30, -v4, v19, v2
	v_cmp_ge_f32_e64 s[4:5], 0, v30
	v_add_u32_e32 v30, 1, v19
	s_waitcnt vmcnt(6)
	v_lshlrev_b32_e32 v24, 16, v24
	v_cndmask_b32_e64 v4, v19, v4, s[4:5]
	v_fma_f32 v19, -v30, v19, v2
	v_cmp_lt_f32_e64 s[4:5], 0, v19
	v_mul_f32_e32 v19, v50, v23
	v_mul_f32_e32 v19, v19, v33
	v_mul_f32_e32 v19, v19, v24
	v_bfe_u32 v24, v19, 16, 1
	v_add3_u32 v19, v19, v24, s57
	global_store_short_d16_hi v[10:11], v19, off offset:64
	v_mul_f32_e32 v19, v53, v23
	global_load_ushort v24, v[14:15], off offset:64
	v_mul_f32_e32 v19, v19, v35
	s_waitcnt vmcnt(6)
	v_lshlrev_b32_e32 v25, 16, v25
	v_mul_f32_e32 v19, v19, v25
	v_bfe_u32 v25, v19, 16, 1
	v_add3_u32 v19, v19, v25, s57
	global_store_short_d16_hi v[10:11], v19, off offset:128
	v_mul_f32_e32 v19, v41, v23
	global_load_ushort v25, v[14:15], off offset:128
	v_mul_f32_e32 v19, v19, v39
	s_waitcnt vmcnt(6)
	v_lshlrev_b32_e32 v22, 16, v22
	v_mul_f32_e32 v19, v19, v22
	v_bfe_u32 v22, v19, 16, 1
	v_add3_u32 v19, v19, v22, s57
	global_store_short_d16_hi v[10:11], v19, off offset:192
	global_load_ushort v22, v[14:15], off offset:192
	v_cndmask_b32_e64 v4, v4, v30, s[4:5]
	v_mul_f32_e32 v10, 0x37800000, v4
	s_nop 1
	v_mov_b32_dpp v11, v6 quad_perm:[1,0,3,2] row_mask:0xf bank_mask:0xf
	v_cndmask_b32_e32 v4, v4, v10, vcc
	v_cmp_class_f32_e32 vcc, v2, v173
	s_waitcnt lgkmcnt(0)
	v_add_f32_e32 v6, v6, v11
	v_cndmask_b32_e32 v2, v4, v2, vcc
	v_div_scale_f32 v4, s[4:5], v2, v2, s56
	v_rcp_f32_e32 v10, v4
	s_nop 1
	v_mov_b32_dpp v11, v6 quad_perm:[2,3,0,1] row_mask:0xf bank_mask:0xf
	v_fma_f32 v14, -v4, v10, 1.0
	v_fmac_f32_e32 v10, v14, v10
	v_div_scale_f32 v14, vcc, s56, v2, s56
	v_mul_f32_e32 v15, v14, v10
	v_fma_f32 v19, -v4, v15, v14
	s_waitcnt lgkmcnt(0)
; #define LAS __attribute__((address_space(3)))
; DI float bf2f(unsigned short u) { return __uint_as_float((unsigned)u << 16); }
; DI unsigned f2bf(float f) { unsigned u = __float_as_uint(f); return (u + 0x7fffu + ((u >> 16) & 1u)) >> 16; }
; DI int crow(int i, int hh) { return (i & 3) + 8 * (i >> 2) + 4 * hh; }
; DI void decode_unit(Ctx A_, LAS unsigned char* lds, int b, int h, float lam, int wave, int lane, int tid) {
;     ...
;     if (kr == 0 && mp == 0) {
;         float ssq[8];
; #pragma unroll
;         for (int i = 0; i < 8; ++i) ssq[i] = 0.f;
; #pragma unroll
;         for (int nb = 0; nb < 4; ++nb)
; #pragma unroll
;             for (int i = 0; i < 8; ++i) { const float d = acc[nb][i] - *(const LAS float*)(lds + X2_OFF + ((nb * 8 + i) * 64 + lane) * 4); acc[nb][i] = d; ssq[i] += d * d; }
; #pragma unroll
;         for (int i = 0; i < 8; ++i) { float v = ssq[i];
; #pragma unroll
;             for (int x = 1; x < 32; x <<= 1) v += __shfl_xor(v, x);
;             ssq[i] = ONE_M_LAMINIT / sqrtf(v * (1.0f / 128.0f) + NORM_EPS); }
; #pragma unroll
;         for (int nb = 0; nb < 4; ++nb) { const float sn = SUB_NORM[nb * 32 + r_e];
; #pragma unroll
;             for (int i = 0; i < 8; ++i) { const size_t rw = rowq + crow(i, hh); Y_[rw * YLD + C_YA + h * 128 + nb * 32 + r_e] = (bf16)f2bf(acc[nb][i] * ssq[i] * sn * bf2f(P[rw * PLD + C_ZA + h * 128 + nb * 32 + r_e])); } }
	v_add_f32_e32 v6, v6, v11
	v_fmac_f32_e32 v15, v19, v10
	s_nop 1
	v_mov_b32_dpp v11, v6 row_half_mirror row_mask:0xf bank_mask:0xf
	v_fma_f32 v4, -v4, v15, v14
	v_div_fmas_f32 v4, v4, v10, v15
	v_div_fixup_f32 v2, v4, v2, s56
	v_mul_f32_e32 v10, v21, v2
	s_waitcnt lgkmcnt(0)
	v_add_f32_e32 v4, v6, v11
	v_mul_f32_e32 v10, v10, v38
	s_waitcnt vmcnt(6)
	v_lshlrev_b32_e32 v11, 16, v18
	v_mul_f32_e32 v10, v10, v11
	v_bfe_u32 v11, v10, 16, 1
	v_add3_u32 v14, v10, v11, s57
	v_mad_u64_u32 v[10:11], s[4:5], v20, s58, v[16:17]
	v_mad_i32_i24 v11, s59, v178, v11
	v_or_b32_e32 v20, 10, v58
	global_store_short_d16_hi v[10:11], v14, off
	v_mad_u64_u32 v[14:15], s[4:5], v20, s53, v[36:37]
	s_nop 1
	v_mov_b32_dpp v6, v4 row_mirror row_mask:0xf bank_mask:0xf
	v_mad_i32_i24 v15, s59, v174, v15
	v_lshl_add_u64 v[14:15], v[14:15], 0, s[2:3]
	v_lshl_add_u64 v[14:15], v[14:15], 0, v[12:13]
	v_add_co_u32_e32 v18, vcc, s54, v14
	s_waitcnt lgkmcnt(0)
	v_add_f32_e32 v4, v4, v6
	v_addc_co_u32_e32 v19, vcc, 0, v15, vcc
	global_load_ushort v18, v[18:19], off offset:2048
	ds_bpermute_b32 v6, v209, v4
	v_sub_f32_e32 v19, v7, v34
	s_waitcnt lgkmcnt(0)
	v_add_f32_e32 v4, v4, v6
	v_lshl_add_u64 v[6:7], v[14:15], 0, s[14:15]
	v_mul_f32_e32 v14, v31, v2
	v_mul_f32_e32 v14, v14, v33
	v_fmamk_f32 v4, v4, 0x3c000000, v172
	v_mul_f32_e32 v21, 0x4f800000, v4
	v_cmp_gt_f32_e32 vcc, s55, v4
	s_waitcnt vmcnt(6)
	v_lshlrev_b32_e32 v15, 16, v24
	v_mul_f32_e32 v14, v14, v15
	v_bfe_u32 v15, v14, 16, 1
	v_add3_u32 v14, v14, v15, s57
	global_store_short_d16_hi v[10:11], v14, off offset:64
	v_mul_f32_e32 v15, v40, v2
	global_load_ushort v14, v[6:7], off offset:64
	v_mul_f32_e32 v15, v15, v35
	s_waitcnt vmcnt(6)
	v_lshlrev_b32_e32 v23, 16, v25
	v_mul_f32_e32 v15, v15, v23
	v_bfe_u32 v23, v15, 16, 1
	v_add3_u32 v15, v15, v23, s57
	global_store_short_d16_hi v[10:11], v15, off offset:128
	v_mul_f32_e32 v2, v27, v2
	global_load_ushort v15, v[6:7], off offset:128
	v_mul_f32_e32 v2, v2, v39
	s_waitcnt vmcnt(6)
	v_lshlrev_b32_e32 v22, 16, v22
	v_mul_f32_e32 v2, v2, v22
	v_bfe_u32 v22, v2, 16, 1
	v_add3_u32 v2, v2, v22, s57
	global_store_short_d16_hi v[10:11], v2, off offset:192
	global_load_ushort v10, v[6:7], off offset:192
	v_cndmask_b32_e32 v2, v4, v21, vcc
	v_sqrt_f32_e32 v4, v2
	v_sub_f32_e32 v11, v3, v32
	v_mul_f32_e32 v6, v19, v19
	v_fmac_f32_e32 v6, v9, v9
	v_add_u32_e32 v3, -1, v4
	v_fma_f32 v7, -v3, v4, v2
	v_cmp_ge_f32_e64 s[4:5], 0, v7
	v_add_u32_e32 v7, 1, v4
	v_sub_f32_e32 v21, v5, v44
	v_cndmask_b32_e64 v3, v4, v3, s[4:5]
	v_fma_f32 v4, -v7, v4, v2
	v_cmp_lt_f32_e64 s[4:5], 0, v4
	v_fmac_f32_e32 v6, v11, v11
	v_fmac_f32_e32 v6, v21, v21
	v_cndmask_b32_e64 v3, v3, v7, s[4:5]
	v_mul_f32_e32 v4, 0x37800000, v3
	v_cndmask_b32_e32 v3, v3, v4, vcc
	v_cmp_class_f32_e32 vcc, v2, v173
	s_waitcnt vmcnt(0)
	v_lshlrev_b32_e32 v10, 16, v10
	v_cndmask_b32_e32 v2, v3, v2, vcc
	v_div_scale_f32 v3, s[4:5], v2, v2, s56
	v_rcp_f32_e32 v4, v3
	v_div_scale_f32 v7, vcc, s56, v2, s56
	v_fma_f32 v5, -v3, v4, 1.0
	v_fmac_f32_e32 v4, v5, v4
	v_mul_f32_e32 v22, v7, v4
	s_nop 1
	v_mov_b32_dpp v5, v6 quad_perm:[1,0,3,2] row_mask:0xf bank_mask:0xf
	v_fma_f32 v23, -v3, v22, v7
	v_fmac_f32_e32 v22, v23, v4
	v_fma_f32 v3, -v3, v22, v7
	v_div_fmas_f32 v3, v3, v4, v22
	v_div_fixup_f32 v22, v3, v2, s56
	s_waitcnt lgkmcnt(0)
	v_add_f32_e32 v5, v6, v5
	v_mul_f32_e32 v2, v8, v22
	s_nop 1
	v_mov_b32_dpp v6, v5 quad_perm:[2,3,0,1] row_mask:0xf bank_mask:0xf
	v_mul_f32_e32 v2, v38, v2
	v_lshlrev_b32_e32 v3, 16, v18
	v_mul_f32_e32 v2, v2, v3
	v_bfe_u32 v3, v2, 16, 1
	v_add3_u32 v4, v2, v3, s57
	v_mad_u64_u32 v[2:3], s[4:5], v20, s58, v[16:17]
	v_mad_i32_i24 v3, s59, v178, v3
	v_or_b32_e32 v8, 11, v58
	s_waitcnt lgkmcnt(0)
; #define LAS __attribute__((address_space(3)))
; DI float bf2f(unsigned short u) { return __uint_as_float((unsigned)u << 16); }
; DI unsigned f2bf(float f) { unsigned u = __float_as_uint(f); return (u + 0x7fffu + ((u >> 16) & 1u)) >> 16; }
; DI int crow(int i, int hh) { return (i & 3) + 8 * (i >> 2) + 4 * hh; }
; DI void decode_unit(Ctx A_, LAS unsigned char* lds, int b, int h, float lam, int wave, int lane, int tid) {
;     ...
;     if (kr == 0 && mp == 0) {
;         float ssq[8];
; #pragma unroll
;         for (int i = 0; i < 8; ++i) ssq[i] = 0.f;
; #pragma unroll
;         for (int nb = 0; nb < 4; ++nb)
; #pragma unroll
;             for (int i = 0; i < 8; ++i) { const float d = acc[nb][i] - *(const LAS float*)(lds + X2_OFF + ((nb * 8 + i) * 64 + lane) * 4); acc[nb][i] = d; ssq[i] += d * d; }
; #pragma unroll
;         for (int i = 0; i < 8; ++i) { float v = ssq[i];
; #pragma unroll
;             for (int x = 1; x < 32; x <<= 1) v += __shfl_xor(v, x);
;             ssq[i] = ONE_M_LAMINIT / sqrtf(v * (1.0f / 128.0f) + NORM_EPS); }
; #pragma unroll
;         for (int nb = 0; nb < 4; ++nb) { const float sn = SUB_NORM[nb * 32 + r_e];
; #pragma unroll
;             for (int i = 0; i < 8; ++i) { const size_t rw = rowq + crow(i, hh); Y_[rw * YLD + C_YA + h * 128 + nb * 32 + r_e] = (bf16)f2bf(acc[nb][i] * ssq[i] * sn * bf2f(P[rw * PLD + C_ZA + h * 128 + nb * 32 + r_e])); } }
	v_add_f32_e32 v23, v5, v6
	global_store_short_d16_hi v[2:3], v4, off
	v_mad_u64_u32 v[4:5], s[4:5], v8, s53, v[36:37]
	v_mad_i32_i24 v5, s59, v174, v5
	v_lshl_add_u64 v[4:5], v[4:5], 0, s[2:3]
	v_lshl_add_u64 v[4:5], v[4:5], 0, v[12:13]
	v_lshl_add_u64 v[6:7], v[4:5], 0, s[14:15]
	v_add_co_u32_e32 v4, vcc, s54, v4
	v_lshlrev_b32_e32 v12, 16, v14
	s_nop 0
	v_addc_co_u32_e32 v5, vcc, 0, v5, vcc
	global_load_ushort v4, v[4:5], off offset:2048
	v_mul_f32_e32 v5, v28, v22
	v_mul_f32_e32 v5, v5, v33
	v_mul_f32_e32 v5, v5, v12
	v_bfe_u32 v12, v5, 16, 1
	v_add3_u32 v5, v5, v12, s57
	global_store_short_d16_hi v[2:3], v5, off offset:64
	v_mul_f32_e32 v12, v29, v22
	global_load_ushort v5, v[6:7], off offset:64
	v_mul_f32_e32 v12, v12, v35
	v_lshlrev_b32_e32 v13, 16, v15
	v_mul_f32_e32 v12, v12, v13
	v_bfe_u32 v13, v12, 16, 1
	v_add3_u32 v12, v12, v13, s57
	global_store_short_d16_hi v[2:3], v12, off offset:128
	v_mul_f32_e32 v13, v26, v22
	global_load_ushort v12, v[6:7], off offset:128
	v_mul_f32_e32 v13, v13, v39
	v_mul_f32_e32 v10, v13, v10
	v_bfe_u32 v13, v10, 16, 1
	v_add3_u32 v10, v10, v13, s57
	global_store_short_d16_hi v[2:3], v10, off offset:192
	global_load_ushort v6, v[6:7], off offset:192
	s_nop 1
	v_mov_b32_dpp v24, v23 row_half_mirror row_mask:0xf bank_mask:0xf
	s_waitcnt lgkmcnt(0)
	v_add_f32_e32 v2, v23, v24
	s_nop 1
	v_mov_b32_dpp v3, v2 row_mirror row_mask:0xf bank_mask:0xf
	s_waitcnt lgkmcnt(0)
	v_add_f32_e32 v2, v2, v3
	ds_bpermute_b32 v3, v209, v2
	s_waitcnt lgkmcnt(0)
	v_add_f32_e32 v2, v2, v3
	v_fmamk_f32 v2, v2, 0x3c000000, v172
	v_mul_f32_e32 v3, 0x4f800000, v2
	v_cmp_gt_f32_e32 vcc, s55, v2
	s_waitcnt vmcnt(4)
	v_lshlrev_b32_e32 v5, 16, v5
	v_cndmask_b32_e32 v2, v2, v3, vcc
	v_sqrt_f32_e32 v3, v2
	s_nop 0
	v_add_u32_e32 v7, -1, v3
	v_fma_f32 v10, -v7, v3, v2
	v_cmp_ge_f32_e64 s[4:5], 0, v10
	v_add_u32_e32 v10, 1, v3
	s_nop 0
	v_cndmask_b32_e64 v7, v3, v7, s[4:5]
	v_fma_f32 v3, -v10, v3, v2
	v_cmp_lt_f32_e64 s[4:5], 0, v3
	s_nop 1
	v_cndmask_b32_e64 v3, v7, v10, s[4:5]
	v_mul_f32_e32 v7, 0x37800000, v3
	v_cndmask_b32_e32 v3, v3, v7, vcc
	v_cmp_class_f32_e32 vcc, v2, v173
	s_nop 1
	v_cndmask_b32_e32 v2, v3, v2, vcc
	v_div_scale_f32 v3, s[4:5], v2, v2, s56
	v_rcp_f32_e32 v7, v3
	s_nop 0
	v_fma_f32 v10, -v3, v7, 1.0
	v_fmac_f32_e32 v7, v10, v7
	v_div_scale_f32 v10, vcc, s56, v2, s56
	v_mul_f32_e32 v13, v10, v7
	v_fma_f32 v14, -v3, v13, v10
	v_fmac_f32_e32 v13, v14, v7
	v_fma_f32 v3, -v3, v13, v10
	v_div_fmas_f32 v3, v3, v7, v13
	v_div_fixup_f32 v7, v3, v2, s56
	v_mul_f32_e32 v2, v9, v7
	v_mul_f32_e32 v2, v38, v2
	v_lshlrev_b32_e32 v3, 16, v4
	v_mul_f32_e32 v2, v2, v3
	v_bfe_u32 v3, v2, 16, 1
	v_add3_u32 v4, v2, v3, s57
	v_mad_u64_u32 v[2:3], s[4:5], v8, s58, v[16:17]
	v_mad_i32_i24 v3, s59, v178, v3
	global_store_short_d16_hi v[2:3], v4, off
	v_mul_f32_e32 v4, v19, v7
	v_mul_f32_e32 v4, v4, v33
	v_mul_f32_e32 v4, v4, v5
	v_bfe_u32 v5, v4, 16, 1
	v_add3_u32 v4, v4, v5, s57
	global_store_short_d16_hi v[2:3], v4, off offset:64
	v_mul_f32_e32 v4, v11, v7
	v_mul_f32_e32 v4, v4, v35
	s_waitcnt vmcnt(4)
	v_lshlrev_b32_e32 v5, 16, v12
	v_mul_f32_e32 v4, v4, v5
	v_bfe_u32 v5, v4, 16, 1
	v_add3_u32 v4, v4, v5, s57
	global_store_short_d16_hi v[2:3], v4, off offset:128
	v_mul_f32_e32 v4, v21, v7
	v_mul_f32_e32 v4, v4, v39
	s_waitcnt vmcnt(3)
	v_lshlrev_b32_e32 v5, 16, v6
	v_mul_f32_e32 v4, v4, v5
	v_bfe_u32 v5, v4, 16, 1
	v_add3_u32 v4, v4, v5, s57
	global_store_short_d16_hi v[2:3], v4, off offset:192
	s_branch .LBB0_819

; DI float bf2f(unsigned short u) { return __uint_as_float((unsigned)u << 16); }
; DI unsigned f2bf(float f) { unsigned u = __float_as_uint(f); return (u + 0x7fffu + ((u >> 16) & 1u)) >> 16; }
; DI int crow(int i, int hh) { return (i & 3) + 8 * (i >> 2) + 4 * hh; }
; DI void attn_unit(Ctx A_, LAS unsigned char* lds, int b, int h, int qb, float lam, int wave, int lane) {
;     ...
;     if (mp == 0) {
;         float ssq[16];
; #pragma unroll
;         for (int i = 0; i < 16; ++i) ssq[i] = 0.f;
; #pragma unroll
;         for (int nb = 0; nb < 4; ++nb)
; #pragma unroll
;             for (int i = 0; i < 16; ++i) { const float d = o[nb][i] - X2[(nb * 16 + i) * 64]; o[nb][i] = d; ssq[i] += d * d; }
; #pragma unroll
;         for (int i = 0; i < 16; ++i) {
;             float v = ssq[i];
; #pragma unroll
;             for (int x = 1; x < 32; x <<= 1) v += __shfl_xor(v, x);
;             ssq[i] = ONE_M_LAMINIT / sqrtf(v * (1.0f / 128.0f) + NORM_EPS);
;         }
; #pragma unroll
;         for (int nb = 0; nb < 4; ++nb) {
;             const float sn = SUB_NORM[nb * 32 + r_e];
; #pragma unroll
;             for (int i = 0; i < 16; ++i) {
;                 const size_t rw = (size_t)(rowq_e + crow(i, hh_e));
;                 Y_[rw * YLD + C_YA + h_e * 128 + nb * 32 + r_e] = (bf16)f2bf(o[nb][i] * ssq[i] * sn * bf2f(P[rw * PLD + C_ZA + h_e * 128 + nb * 32 + r_e]));
;             }
.LBB0_894:
	s_waitcnt lgkmcnt(0)
	s_barrier
	v_readlane_b32 s4, v255, 36
	v_readlane_b32 s5, v255, 37
	s_andn2_b64 vcc, exec, s[4:5]
	s_cbranch_vccnz .LBB0_862
	ds_read2st64_b32 v[4:5], v64 offset1:1
	ds_read2st64_b32 v[24:25], v64 offset0:2 offset1:3
	ds_read2st64_b32 v[18:19], v64 offset0:4 offset1:5
	ds_read2st64_b32 v[16:17], v64 offset0:6 offset1:7
	ds_read2st64_b32 v[32:33], v64 offset0:16 offset1:17
	s_waitcnt lgkmcnt(4)
	v_sub_f32_e32 v104, v34, v4
	ds_read2st64_b32 v[26:27], v64 offset0:18 offset1:19
	ds_read2st64_b32 v[14:15], v64 offset0:20 offset1:21
	ds_read2st64_b32 v[10:11], v64 offset0:22 offset1:23
	v_readlane_b32 s64, v254, 22
	v_readlane_b32 s74, v254, 32
	s_waitcnt lgkmcnt(3)
	v_sub_f32_e32 v97, v35, v32
	ds_read2st64_b32 v[34:35], v64 offset0:32 offset1:33
	ds_read2st64_b32 v[28:29], v64 offset0:34 offset1:35
	ds_read2st64_b32 v[20:21], v64 offset0:36 offset1:37
	ds_read2st64_b32 v[8:9], v64 offset0:38 offset1:39
	v_readlane_b32 s75, v254, 33
	v_mul_f32_e32 v3, v97, v97
	v_fmac_f32_e32 v3, v104, v104
	s_waitcnt lgkmcnt(3)
	v_sub_f32_e32 v98, v36, v34
	ds_read2st64_b32 v[36:37], v64 offset0:48 offset1:49
	ds_read2st64_b32 v[30:31], v64 offset0:50 offset1:51
	ds_read2st64_b32 v[22:23], v64 offset0:52 offset1:53
	ds_read2st64_b32 v[12:13], v64 offset0:54 offset1:55
	v_fmac_f32_e32 v3, v98, v98
	v_readlane_b32 s4, v255, 9
	v_readlane_b32 s5, v255, 10
	s_waitcnt lgkmcnt(3)
	v_sub_f32_e32 v99, v2, v36
	v_lshl_add_u32 v36, v197, 2, s0
	v_ashrrev_i32_e32 v197, 31, v196
	v_lshl_add_u64 v[38:39], v[196:197], 2, s[74:75]
	global_load_dword v34, v[38:39], off
	v_fmac_f32_e32 v3, v99, v99
	s_nop 1
	v_mov_b32_dpp v2, v3 quad_perm:[1,0,3,2] row_mask:0xf bank_mask:0xf
	s_lshl_b32 s0, s63, 7
	s_ashr_i32 s1, s0, 31
	v_mov_b64_e32 v[6:7], s[4:5]
	s_lshl_b64 s[0:1], s[0:1], 1
	v_mad_i64_i32 v[106:107], s[4:5], v36, s57, v[6:7]
	s_waitcnt lgkmcnt(0)
	v_add_f32_e32 v4, v3, v2
	v_lshlrev_b64 v[2:3], 1, v[196:197]
	v_lshl_add_u64 v[106:107], v[106:107], 0, s[0:1]
	v_lshl_add_u64 v[110:111], v[106:107], 0, v[2:3]
	v_add_co_u32_e32 v106, vcc, s60, v110
	s_nop 1
	v_mov_b32_dpp v32, v4 quad_perm:[2,3,0,1] row_mask:0xf bank_mask:0xf
	s_nop 0
	v_addc_co_u32_e32 v107, vcc, 0, v111, vcc
	global_load_ushort v107, v[106:107], off offset:2048
	v_sub_f32_e32 v106, v100, v5
	s_waitcnt lgkmcnt(0)
	v_add_f32_e32 v4, v4, v32
	s_nop 1
	v_mov_b32_dpp v32, v4 row_half_mirror row_mask:0xf bank_mask:0xf
	v_sub_f32_e32 v105, v101, v33
	v_sub_f32_e32 v100, v102, v35
	v_sub_f32_e32 v101, v103, v37
	v_sub_f32_e32 v24, v93, v24
	s_waitcnt lgkmcnt(0)
	v_add_f32_e32 v4, v4, v32
	s_nop 1
	v_mov_b32_dpp v32, v4 row_mirror row_mask:0xf bank_mask:0xf
	v_sub_f32_e32 v30, v96, v30
	v_sub_f32_e32 v89, v89, v25
	v_sub_f32_e32 v91, v91, v29
	v_sub_f32_e32 v92, v92, v31
	s_waitcnt lgkmcnt(0)
	v_add_f32_e32 v4, v4, v32
	ds_bpermute_b32 v5, v209, v4
	v_mul_f32_e32 v32, v105, v105
	v_fmac_f32_e32 v32, v106, v106
	v_fmac_f32_e32 v32, v100, v100
	v_fmac_f32_e32 v32, v101, v101
	s_waitcnt lgkmcnt(0)
	v_add_f32_e32 v4, v4, v5
	v_fmamk_f32 v4, v4, 0x3c000000, v211
	v_mul_f32_e32 v5, 0x4f800000, v4
	v_cmp_gt_f32_e32 vcc, s58, v4
	v_sub_f32_e32 v90, v90, v27
	v_mul_f32_e32 v27, v90, v90
	v_cndmask_b32_e32 v4, v4, v5, vcc
	v_sqrt_f32_e32 v5, v4
	v_fmac_f32_e32 v27, v89, v89
	v_fmac_f32_e32 v27, v91, v91
	v_fmac_f32_e32 v27, v92, v92
	v_add_u32_e32 v33, -1, v5
	v_fma_f32 v35, -v33, v5, v4
	v_cmp_ge_f32_e64 s[4:5], 0, v35
	v_add_u32_e32 v35, 1, v5
	v_sub_f32_e32 v88, v88, v18
	v_cndmask_b32_e64 v33, v5, v33, s[4:5]
	v_fma_f32 v5, -v35, v5, v4
	v_cmp_lt_f32_e64 s[4:5], 0, v5
	v_sub_f32_e32 v84, v84, v16
	v_sub_f32_e32 v83, v83, v19
	v_cndmask_b32_e64 v5, v33, v35, s[4:5]
	s_nop 1
	v_mov_b32_dpp v35, v32 quad_perm:[1,0,3,2] row_mask:0xf bank_mask:0xf
	v_mul_f32_e32 v33, 0x37800000, v5
	v_cndmask_b32_e32 v5, v5, v33, vcc
	v_cmp_class_f32_e32 vcc, v4, v212
	v_sub_f32_e32 v86, v86, v20
	s_waitcnt lgkmcnt(0)
	v_add_f32_e32 v32, v32, v35
	v_cndmask_b32_e32 v4, v5, v4, vcc
	v_div_scale_f32 v5, s[4:5], v4, v4, s59
	s_nop 1
	v_mov_b32_dpp v35, v32 quad_perm:[2,3,0,1] row_mask:0xf bank_mask:0xf
	v_rcp_f32_e32 v33, v5
	s_add_u32 s4, s51, s0
	s_addc_u32 s5, s52, s1
	v_sub_f32_e32 v85, v85, v14
	v_fma_f32 v37, -v5, v33, 1.0
	s_waitcnt lgkmcnt(0)
	v_add_f32_e32 v32, v32, v35
	v_fmac_f32_e32 v33, v37, v33
	v_div_scale_f32 v37, vcc, s59, v4, s59
	s_nop 1
	v_mov_b32_dpp v35, v32 row_half_mirror row_mask:0xf bank_mask:0xf
	v_mul_f32_e32 v102, v37, v33
	v_fma_f32 v103, -v5, v102, v37
	v_fmac_f32_e32 v102, v103, v33
	v_fma_f32 v5, -v5, v102, v37
	v_div_fmas_f32 v5, v5, v33, v102
	s_waitcnt lgkmcnt(0)
	v_add_f32_e32 v103, v32, v35
	v_lshl_add_u64 v[32:33], v[110:111], 0, s[20:21]
	global_load_dword v35, v[38:39], off offset:128
	global_load_ushort v109, v[32:33], off offset:64
	global_load_dword v37, v[38:39], off offset:256
	s_nop 0
	global_load_dword v38, v[38:39], off offset:384
	v_div_fixup_f32 v102, v5, v4, s59
	v_mul_f32_e32 v104, v104, v102
	s_waitcnt vmcnt(5)
	v_mul_f32_e32 v39, v104, v34
	global_load_ushort v104, v[32:33], off offset:128
	global_load_ushort v114, v[32:33], off offset:192
	v_lshl_add_u64 v[4:5], s[4:5], 0, v[2:3]
	s_nop 1
	v_mov_b32_dpp v108, v103 row_mirror row_mask:0xf bank_mask:0xf
	v_mul_f32_e32 v97, v97, v102
	v_mul_f32_e32 v14, v85, v85
	v_fmac_f32_e32 v14, v88, v88
	v_fmac_f32_e32 v14, v86, v86
	s_waitcnt vmcnt(6)
	v_lshlrev_b32_e32 v32, 16, v107
	v_mul_f32_e32 v32, v39, v32
	v_bfe_u32 v33, v32, 16, 1
	v_add3_u32 v39, v32, v33, s61
	v_mad_i64_i32 v[32:33], s[4:5], v36, s62, v[4:5]
	global_store_short_d16_hi v[32:33], v39, off
	v_add_u32_e32 v39, 1, v36
	v_mad_i64_i32 v[110:111], s[4:5], v39, s57, v[6:7]
	v_lshl_add_u64 v[110:111], v[110:111], 0, s[0:1]
	v_lshl_add_u64 v[110:111], v[110:111], 0, v[2:3]
	v_add_co_u32_e32 v112, vcc, s60, v110
	s_waitcnt lgkmcnt(0)
; DI float bf2f(unsigned short u) { return __uint_as_float((unsigned)u << 16); }
; DI unsigned f2bf(float f) { unsigned u = __float_as_uint(f); return (u + 0x7fffu + ((u >> 16) & 1u)) >> 16; }
; DI int crow(int i, int hh) { return (i & 3) + 8 * (i >> 2) + 4 * hh; }
; DI void attn_unit(Ctx A_, LAS unsigned char* lds, int b, int h, int qb, float lam, int wave, int lane) {
;     ...
;     if (mp == 0) {
;         float ssq[16];
; #pragma unroll
;         for (int i = 0; i < 16; ++i) ssq[i] = 0.f;
; #pragma unroll
;         for (int nb = 0; nb < 4; ++nb)
; #pragma unroll
;             for (int i = 0; i < 16; ++i) { const float d = o[nb][i] - X2[(nb * 16 + i) * 64]; o[nb][i] = d; ssq[i] += d * d; }
; #pragma unroll
;         for (int i = 0; i < 16; ++i) {
;             float v = ssq[i];
; #pragma unroll
;             for (int x = 1; x < 32; x <<= 1) v += __shfl_xor(v, x);
;             ssq[i] = ONE_M_LAMINIT / sqrtf(v * (1.0f / 128.0f) + NORM_EPS);
;         }
; #pragma unroll
;         for (int nb = 0; nb < 4; ++nb) {
;             const float sn = SUB_NORM[nb * 32 + r_e];
; #pragma unroll
;             for (int i = 0; i < 16; ++i) {
;                 const size_t rw = (size_t)(rowq_e + crow(i, hh_e));
;                 Y_[rw * YLD + C_YA + h_e * 128 + nb * 32 + r_e] = (bf16)f2bf(o[nb][i] * ssq[i] * sn * bf2f(P[rw * PLD + C_ZA + h_e * 128 + nb * 32 + r_e]));
;             }
	v_add_f32_e32 v93, v103, v108
	v_addc_co_u32_e32 v113, vcc, 0, v111, vcc
	global_load_ushort v107, v[112:113], off offset:2048
	ds_bpermute_b32 v103, v209, v93
	v_sub_f32_e32 v112, v95, v28
	v_sub_f32_e32 v108, v94, v26
	v_mul_f32_e32 v26, v108, v108
	v_fmac_f32_e32 v26, v24, v24
	s_waitcnt lgkmcnt(0)
	v_add_f32_e32 v28, v93, v103
	v_fmamk_f32 v28, v28, 0x3c000000, v211
	v_mul_f32_e32 v93, 0x4f800000, v28
	v_cmp_gt_f32_e32 vcc, s58, v28
	v_fmac_f32_e32 v26, v112, v112
	v_fmac_f32_e32 v26, v30, v30
	v_cndmask_b32_e32 v28, v28, v93, vcc
	v_sqrt_f32_e32 v93, v28
	v_sub_f32_e32 v87, v87, v22
	v_fmac_f32_e32 v14, v87, v87
	v_sub_f32_e32 v82, v82, v17
	v_add_u32_e32 v94, -1, v93
	v_fma_f32 v95, -v94, v93, v28
	v_cmp_ge_f32_e64 s[4:5], 0, v95
	v_add_u32_e32 v95, 1, v93
	v_readlane_b32 s65, v254, 23
	v_cndmask_b32_e64 v94, v93, v94, s[4:5]
	v_fma_f32 v93, -v95, v93, v28
	v_cmp_lt_f32_e64 s[4:5], 0, v93
	v_readlane_b32 s66, v254, 24
	v_readlane_b32 s67, v254, 25
	v_cndmask_b32_e64 v93, v94, v95, s[4:5]
	v_mul_f32_e32 v94, 0x37800000, v93
	v_cndmask_b32_e32 v93, v93, v94, vcc
	v_cmp_class_f32_e32 vcc, v28, v212
	s_nop 1
	v_mov_b32_dpp v95, v26 quad_perm:[1,0,3,2] row_mask:0xf bank_mask:0xf
	v_readlane_b32 s68, v254, 26
	v_cndmask_b32_e32 v28, v93, v28, vcc
	v_div_scale_f32 v93, s[4:5], v28, v28, s59
	v_rcp_f32_e32 v94, v93
	s_waitcnt lgkmcnt(0)
	v_add_f32_e32 v26, v26, v95
	s_nop 1
	v_mov_b32_dpp v95, v26 quad_perm:[2,3,0,1] row_mask:0xf bank_mask:0xf
	v_readlane_b32 s69, v254, 27
	v_fma_f32 v96, -v93, v94, 1.0
	v_fmac_f32_e32 v94, v96, v94
	v_div_scale_f32 v96, vcc, s59, v28, s59
	v_mul_f32_e32 v103, v96, v94
	v_fma_f32 v113, -v93, v103, v96
	v_fmac_f32_e32 v103, v113, v94
	v_fma_f32 v93, -v93, v103, v96
	v_div_fmas_f32 v93, v93, v94, v103
	s_waitcnt vmcnt(7)
	v_mul_f32_e32 v97, v97, v35
	s_waitcnt vmcnt(6)
	v_lshlrev_b32_e32 v103, 16, v109
	v_mul_f32_e32 v97, v97, v103
	s_waitcnt lgkmcnt(0)
	v_add_f32_e32 v26, v26, v95
	v_bfe_u32 v103, v97, 16, 1
	s_nop 1
	v_mov_b32_dpp v95, v26 row_half_mirror row_mask:0xf bank_mask:0xf
	v_add3_u32 v97, v97, v103, s61
	global_store_short_d16_hi v[32:33], v97, off offset:64
	v_mul_f32_e32 v97, v98, v102
	s_waitcnt vmcnt(6)
	v_mul_f32_e32 v97, v97, v37
	s_waitcnt vmcnt(4)
	v_lshlrev_b32_e32 v98, 16, v104
	v_div_fixup_f32 v28, v93, v28, s59
	v_mul_f32_e32 v97, v97, v98
	v_mul_f32_e32 v94, v106, v28
	v_bfe_u32 v98, v97, 16, 1
	s_waitcnt lgkmcnt(0)
	v_add_f32_e32 v26, v26, v95
	v_mul_f32_e32 v96, v94, v34
	v_lshl_add_u64 v[94:95], v[110:111], 0, s[20:21]
	v_add3_u32 v97, v97, v98, s61
	global_load_ushort v103, v[94:95], off offset:64
	s_waitcnt vmcnt(4)
	v_lshlrev_b32_e32 v98, 16, v114
	global_store_short_d16_hi v[32:33], v97, off offset:128
	v_mul_f32_e32 v97, v99, v102
	v_mul_f32_e32 v97, v97, v38
	v_mul_f32_e32 v97, v97, v98
	v_bfe_u32 v98, v97, 16, 1
	v_add3_u32 v97, v97, v98, s61
	global_store_short_d16_hi v[32:33], v97, off offset:192
	global_load_ushort v98, v[94:95], off offset:128
	global_load_ushort v99, v[94:95], off offset:192
	s_nop 1
	v_mov_b32_dpp v93, v26 row_mirror row_mask:0xf bank_mask:0xf
	v_readlane_b32 s70, v254, 28
	s_waitcnt vmcnt(6)
	v_lshlrev_b32_e32 v32, 16, v107
	v_mul_f32_e32 v32, v96, v32
	v_bfe_u32 v33, v32, 16, 1
	v_add3_u32 v94, v32, v33, s61
	v_mad_i64_i32 v[32:33], s[4:5], v39, s62, v[4:5]
	v_add_u32_e32 v39, 2, v36
	global_store_short_d16_hi v[32:33], v94, off
	v_mad_i64_i32 v[94:95], s[4:5], v39, s57, v[6:7]
	v_lshl_add_u64 v[94:95], v[94:95], 0, s[0:1]
	v_lshl_add_u64 v[94:95], v[94:95], 0, v[2:3]
	v_add_co_u32_e32 v96, vcc, s60, v94
	s_waitcnt lgkmcnt(0)
	v_add_f32_e32 v25, v26, v93
	v_addc_co_u32_e32 v97, vcc, 0, v95, vcc
	global_load_ushort v96, v[96:97], off offset:2048
	ds_bpermute_b32 v26, v209, v25
	v_readlane_b32 s71, v254, 29
	v_readlane_b32 s72, v254, 30
	v_readlane_b32 s73, v254, 31
	v_readlane_b32 s76, v254, 34
	s_waitcnt lgkmcnt(0)
	v_add_f32_e32 v25, v25, v26
	v_fmamk_f32 v25, v25, 0x3c000000, v211
	v_mul_f32_e32 v26, 0x4f800000, v25
	v_cmp_gt_f32_e32 vcc, s58, v25
	v_readlane_b32 s77, v254, 35
	v_readlane_b32 s78, v254, 36
	v_cndmask_b32_e32 v25, v25, v26, vcc
	v_sqrt_f32_e32 v26, v25
	v_readlane_b32 s79, v254, 37
	v_add_u32_e32 v29, -1, v26
	v_fma_f32 v31, -v29, v26, v25
	v_cmp_ge_f32_e64 s[4:5], 0, v31
	v_add_u32_e32 v31, 1, v26
	s_nop 0
	v_cndmask_b32_e64 v29, v26, v29, s[4:5]
	v_fma_f32 v26, -v31, v26, v25
	v_cmp_lt_f32_e64 s[4:5], 0, v26
	s_nop 1
	v_cndmask_b32_e64 v26, v29, v31, s[4:5]
	v_mul_f32_e32 v29, 0x37800000, v26
	v_cndmask_b32_e32 v26, v26, v29, vcc
	v_cmp_class_f32_e32 vcc, v25, v212
	s_nop 1
	v_mov_b32_dpp v31, v27 quad_perm:[1,0,3,2] row_mask:0xf bank_mask:0xf
	s_nop 0
	v_cndmask_b32_e32 v25, v26, v25, vcc
	v_div_scale_f32 v26, s[4:5], v25, v25, s59
	v_rcp_f32_e32 v29, v26
	s_nop 0
	v_fma_f32 v18, -v26, v29, 1.0
	v_fmac_f32_e32 v29, v18, v29
	s_waitcnt lgkmcnt(0)
	v_add_f32_e32 v18, v27, v31
	s_nop 1
	v_mov_b32_dpp v27, v18 quad_perm:[2,3,0,1] row_mask:0xf bank_mask:0xf
	v_div_scale_f32 v31, vcc, s59, v25, s59
	v_mul_f32_e32 v93, v31, v29
	v_fma_f32 v97, -v26, v93, v31
	s_waitcnt lgkmcnt(0)
	v_add_f32_e32 v18, v18, v27
	s_nop 1
	v_mov_b32_dpp v27, v18 row_half_mirror row_mask:0xf bank_mask:0xf
	v_fmac_f32_e32 v93, v97, v29
	v_fma_f32 v26, -v26, v93, v31
	v_div_fmas_f32 v26, v26, v29, v93
	s_waitcnt vmcnt(6)
	v_lshlrev_b32_e32 v29, 16, v103
	s_waitcnt lgkmcnt(0)
	v_add_f32_e32 v18, v18, v27
	v_mul_f32_e32 v27, v105, v28
	v_mul_f32_e32 v27, v27, v35
	v_mul_f32_e32 v27, v27, v29
	v_bfe_u32 v29, v27, 16, 1
	v_add3_u32 v27, v27, v29, s61
	global_store_short_d16_hi v[32:33], v27, off offset:64
	v_mul_f32_e32 v27, v100, v28
	v_mul_f32_e32 v27, v27, v37
	s_waitcnt vmcnt(4)
; DI float bf2f(unsigned short u) { return __uint_as_float((unsigned)u << 16); }
; DI unsigned f2bf(float f) { unsigned u = __float_as_uint(f); return (u + 0x7fffu + ((u >> 16) & 1u)) >> 16; }
; DI int crow(int i, int hh) { return (i & 3) + 8 * (i >> 2) + 4 * hh; }
; DI void attn_unit(Ctx A_, LAS unsigned char* lds, int b, int h, int qb, float lam, int wave, int lane) {
;     ...
;     if (mp == 0) {
;         float ssq[16];
; #pragma unroll
;         for (int i = 0; i < 16; ++i) ssq[i] = 0.f;
; #pragma unroll
;         for (int nb = 0; nb < 4; ++nb)
; #pragma unroll
;             for (int i = 0; i < 16; ++i) { const float d = o[nb][i] - X2[(nb * 16 + i) * 64]; o[nb][i] = d; ssq[i] += d * d; }
; #pragma unroll
;         for (int i = 0; i < 16; ++i) {
;             float v = ssq[i];
; #pragma unroll
;             for (int x = 1; x < 32; x <<= 1) v += __shfl_xor(v, x);
;             ssq[i] = ONE_M_LAMINIT / sqrtf(v * (1.0f / 128.0f) + NORM_EPS);
;         }
; #pragma unroll
;         for (int nb = 0; nb < 4; ++nb) {
;             const float sn = SUB_NORM[nb * 32 + r_e];
; #pragma unroll
;             for (int i = 0; i < 16; ++i) {
;                 const size_t rw = (size_t)(rowq_e + crow(i, hh_e));
;                 Y_[rw * YLD + C_YA + h_e * 128 + nb * 32 + r_e] = (bf16)f2bf(o[nb][i] * ssq[i] * sn * bf2f(P[rw * PLD + C_ZA + h_e * 128 + nb * 32 + r_e]));
;             }
	v_lshlrev_b32_e32 v29, 16, v98
	v_div_fixup_f32 v31, v26, v25, s59
	v_mul_f32_e32 v27, v27, v29
	v_mul_f32_e32 v24, v24, v31
	v_bfe_u32 v29, v27, 16, 1
	v_mul_f32_e32 v26, v24, v34
	v_lshl_add_u64 v[24:25], v[94:95], 0, s[20:21]
	v_add3_u32 v27, v27, v29, s61
	global_load_ushort v94, v[24:25], off offset:64
	s_nop 1
	v_mov_b32_dpp v93, v18 row_mirror row_mask:0xf bank_mask:0xf
	global_store_short_d16_hi v[32:33], v27, off offset:128
	v_mul_f32_e32 v27, v101, v28
	v_mul_f32_e32 v27, v27, v38
	s_waitcnt vmcnt(5)
	v_lshlrev_b32_e32 v28, 16, v99
	v_mul_f32_e32 v27, v27, v28
	v_bfe_u32 v28, v27, 16, 1
	v_add3_u32 v27, v27, v28, s61
	global_store_short_d16_hi v[32:33], v27, off offset:192
	global_load_ushort v32, v[24:25], off offset:128
	s_nop 0
	global_load_ushort v33, v[24:25], off offset:192
	s_waitcnt vmcnt(6)
	v_lshlrev_b32_e32 v24, 16, v96
	v_mul_f32_e32 v24, v26, v24
	v_bfe_u32 v25, v24, 16, 1
	v_add3_u32 v26, v24, v25, s61
	v_mad_i64_i32 v[24:25], s[4:5], v39, s62, v[4:5]
	v_add_u32_e32 v39, 3, v36
	global_store_short_d16_hi v[24:25], v26, off
	v_mad_i64_i32 v[26:27], s[4:5], v39, s57, v[6:7]
	v_lshl_add_u64 v[26:27], v[26:27], 0, s[0:1]
	v_lshl_add_u64 v[28:29], v[26:27], 0, v[2:3]
	v_add_co_u32_e32 v26, vcc, s60, v28
	s_waitcnt lgkmcnt(0)
	v_add_f32_e32 v16, v18, v93
	v_addc_co_u32_e32 v27, vcc, 0, v29, vcc
	global_load_ushort v95, v[26:27], off offset:2048
	ds_bpermute_b32 v18, v209, v16
	s_waitcnt lgkmcnt(0)
	v_add_f32_e32 v16, v16, v18
	v_fmamk_f32 v16, v16, 0x3c000000, v211
	v_mul_f32_e32 v18, 0x4f800000, v16
	v_cmp_gt_f32_e32 vcc, s58, v16
	s_nop 1
	v_cndmask_b32_e32 v16, v16, v18, vcc
	v_sqrt_f32_e32 v18, v16
	s_nop 0
	v_add_u32_e32 v19, -1, v18
	v_fma_f32 v20, -v19, v18, v16
	v_cmp_ge_f32_e64 s[4:5], 0, v20
	v_add_u32_e32 v20, 1, v18
	s_nop 0
	v_cndmask_b32_e64 v19, v18, v19, s[4:5]
	v_fma_f32 v18, -v20, v18, v16
	v_cmp_lt_f32_e64 s[4:5], 0, v18
	s_nop 1
	v_cndmask_b32_e64 v18, v19, v20, s[4:5]
	v_mul_f32_e32 v19, 0x37800000, v18
	v_cndmask_b32_e32 v18, v18, v19, vcc
	v_cmp_class_f32_e32 vcc, v16, v212
	s_nop 1
	v_mov_b32_dpp v20, v14 quad_perm:[1,0,3,2] row_mask:0xf bank_mask:0xf
	s_waitcnt lgkmcnt(0)
	v_add_f32_e32 v14, v14, v20
	v_cndmask_b32_e32 v16, v18, v16, vcc
	v_div_scale_f32 v18, s[4:5], v16, v16, s59
	v_rcp_f32_e32 v19, v18
	v_div_scale_f32 v20, vcc, s59, v16, s59
	v_fma_f32 v17, -v18, v19, 1.0
	v_fmac_f32_e32 v19, v17, v19
	s_nop 1
	v_mov_b32_dpp v17, v14 quad_perm:[2,3,0,1] row_mask:0xf bank_mask:0xf
	v_mul_f32_e32 v22, v20, v19
	v_fma_f32 v93, -v18, v22, v20
	v_fmac_f32_e32 v22, v93, v19
	v_fma_f32 v18, -v18, v22, v20
	s_waitcnt lgkmcnt(0)
	v_add_f32_e32 v14, v14, v17
	s_nop 1
	v_mov_b32_dpp v17, v14 row_half_mirror row_mask:0xf bank_mask:0xf
	v_div_fmas_f32 v18, v18, v19, v22
	v_div_fixup_f32 v20, v18, v16, s59
	v_mul_f32_e32 v16, v89, v20
	v_mul_f32_e32 v19, v108, v31
	s_waitcnt lgkmcnt(0)
	v_add_f32_e32 v14, v14, v17
	v_mul_f32_e32 v18, v16, v34
	v_lshl_add_u64 v[16:17], v[28:29], 0, s[20:21]
	v_mul_f32_e32 v19, v19, v35
	s_waitcnt vmcnt(6)
	v_lshlrev_b32_e32 v28, 16, v94
	v_mul_f32_e32 v19, v19, v28
	v_bfe_u32 v28, v19, 16, 1
	v_add3_u32 v19, v19, v28, s61
	global_store_short_d16_hi v[24:25], v19, off offset:64
	v_mul_f32_e32 v19, v112, v31
	v_mul_f32_e32 v19, v19, v37
	s_waitcnt vmcnt(4)
	v_lshlrev_b32_e32 v28, 16, v32
	v_mul_f32_e32 v19, v19, v28
	v_bfe_u32 v28, v19, 16, 1
	v_add3_u32 v19, v19, v28, s61
	global_load_ushort v89, v[16:17], off offset:64
	s_waitcnt vmcnt(4)
	v_lshlrev_b32_e32 v28, 16, v33
	global_store_short_d16_hi v[24:25], v19, off offset:128
	v_mul_f32_e32 v19, v30, v31
	v_mul_f32_e32 v19, v19, v38
	v_mul_f32_e32 v19, v19, v28
	v_bfe_u32 v28, v19, 16, 1
	v_add3_u32 v19, v19, v28, s61
	global_store_short_d16_hi v[24:25], v19, off offset:192
	ds_read2st64_b32 v[26:27], v64 offset0:8 offset1:9
	global_load_ushort v32, v[16:17], off offset:128
	global_load_ushort v33, v[16:17], off offset:192
	s_waitcnt vmcnt(6)
	v_lshlrev_b32_e32 v16, 16, v95
	v_mul_f32_e32 v16, v18, v16
	v_bfe_u32 v17, v16, 16, 1
	v_add3_u32 v16, v16, v17, s61
	v_mad_i64_i32 v[28:29], s[4:5], v39, s62, v[4:5]
	v_add_u32_e32 v39, 8, v36
	global_store_short_d16_hi v[28:29], v16, off
	v_mad_i64_i32 v[16:17], s[4:5], v39, s57, v[6:7]
	v_lshl_add_u64 v[16:17], v[16:17], 0, s[0:1]
	v_lshl_add_u64 v[30:31], v[16:17], 0, v[2:3]
	v_add_co_u32_e32 v16, vcc, s60, v30
	s_nop 1
	v_mov_b32_dpp v22, v14 row_mirror row_mask:0xf bank_mask:0xf
	s_nop 0
	v_addc_co_u32_e32 v17, vcc, 0, v31, vcc
	global_load_ushort v93, v[16:17], off offset:2048
	s_waitcnt lgkmcnt(1)
	v_sub_f32_e32 v26, v78, v26
	s_waitcnt lgkmcnt(0)
	v_add_f32_e32 v14, v14, v22
	ds_bpermute_b32 v22, v209, v14
	v_sub_f32_e32 v78, v79, v15
	v_sub_f32_e32 v79, v80, v21
	v_mul_f32_e32 v15, v78, v78
	v_sub_f32_e32 v80, v81, v23
	s_waitcnt lgkmcnt(0)
	v_add_f32_e32 v14, v14, v22
	v_fmamk_f32 v14, v14, 0x3c000000, v211
	v_mul_f32_e32 v21, 0x4f800000, v14
	v_cmp_gt_f32_e32 vcc, s58, v14
	v_fmac_f32_e32 v15, v83, v83
	v_fmac_f32_e32 v15, v79, v79
	v_cndmask_b32_e32 v14, v14, v21, vcc
	v_sqrt_f32_e32 v21, v14
	v_fmac_f32_e32 v15, v80, v80
	v_sub_f32_e32 v94, v77, v10
	ds_read2st64_b32 v[24:25], v64 offset0:10 offset1:11
	ds_read2st64_b32 v[18:19], v64 offset0:12 offset1:13
	ds_read2st64_b32 v[16:17], v64 offset0:14 offset1:15
	v_add_u32_e32 v22, -1, v21
	v_fma_f32 v23, -v22, v21, v14
	v_cmp_ge_f32_e64 s[4:5], 0, v23
	v_add_u32_e32 v23, 1, v21
	v_mul_f32_e32 v10, v94, v94
	v_cndmask_b32_e64 v22, v21, v22, s[4:5]
	v_fma_f32 v21, -v23, v21, v14
	v_cmp_lt_f32_e64 s[4:5], 0, v21
	v_fmac_f32_e32 v10, v84, v84
	v_sub_f32_e32 v70, v70, v27
	v_cndmask_b32_e64 v21, v22, v23, s[4:5]
	s_nop 1
	v_mov_b32_dpp v23, v15 quad_perm:[1,0,3,2] row_mask:0xf bank_mask:0xf
	v_mul_f32_e32 v22, 0x37800000, v21
	v_cndmask_b32_e32 v21, v21, v22, vcc
	v_cmp_class_f32_e32 vcc, v14, v212
	s_waitcnt lgkmcnt(3)
; DI float bf2f(unsigned short u) { return __uint_as_float((unsigned)u << 16); }
; DI unsigned f2bf(float f) { unsigned u = __float_as_uint(f); return (u + 0x7fffu + ((u >> 16) & 1u)) >> 16; }
; DI int crow(int i, int hh) { return (i & 3) + 8 * (i >> 2) + 4 * hh; }
; DI void attn_unit(Ctx A_, LAS unsigned char* lds, int b, int h, int qb, float lam, int wave, int lane) {
;     ...
;     if (mp == 0) {
;         float ssq[16];
; #pragma unroll
;         for (int i = 0; i < 16; ++i) ssq[i] = 0.f;
; #pragma unroll
;         for (int nb = 0; nb < 4; ++nb)
; #pragma unroll
;             for (int i = 0; i < 16; ++i) { const float d = o[nb][i] - X2[(nb * 16 + i) * 64]; o[nb][i] = d; ssq[i] += d * d; }
; #pragma unroll
;         for (int i = 0; i < 16; ++i) {
;             float v = ssq[i];
; #pragma unroll
;             for (int x = 1; x < 32; x <<= 1) v += __shfl_xor(v, x);
;             ssq[i] = ONE_M_LAMINIT / sqrtf(v * (1.0f / 128.0f) + NORM_EPS);
;         }
; #pragma unroll
;         for (int nb = 0; nb < 4; ++nb) {
;             const float sn = SUB_NORM[nb * 32 + r_e];
; #pragma unroll
;             for (int i = 0; i < 16; ++i) {
;                 const size_t rw = (size_t)(rowq_e + crow(i, hh_e));
;                 Y_[rw * YLD + C_YA + h_e * 128 + nb * 32 + r_e] = (bf16)f2bf(o[nb][i] * ssq[i] * sn * bf2f(P[rw * PLD + C_ZA + h_e * 128 + nb * 32 + r_e]));
;             }
	v_sub_f32_e32 v24, v69, v24
	s_waitcnt lgkmcnt(0)
	v_add_f32_e32 v15, v15, v23
	v_cndmask_b32_e32 v14, v21, v14, vcc
	v_div_scale_f32 v21, s[4:5], v14, v14, s59
	v_rcp_f32_e32 v22, v21
	s_nop 1
	v_mov_b32_dpp v23, v15 quad_perm:[2,3,0,1] row_mask:0xf bank_mask:0xf
	v_sub_f32_e32 v18, v67, v18
	v_sub_f32_e32 v16, v44, v16
	v_fma_f32 v77, -v21, v22, 1.0
	v_fmac_f32_e32 v22, v77, v22
	v_div_scale_f32 v77, vcc, s59, v14, s59
	s_waitcnt lgkmcnt(0)
	v_add_f32_e32 v15, v15, v23
	v_mul_f32_e32 v81, v77, v22
	s_nop 1
	v_mov_b32_dpp v23, v15 row_half_mirror row_mask:0xf bank_mask:0xf
	v_fma_f32 v95, -v21, v81, v77
	v_fmac_f32_e32 v81, v95, v22
	v_fma_f32 v21, -v21, v81, v77
	v_div_fmas_f32 v21, v21, v22, v81
	v_mul_f32_e32 v22, v90, v20
	s_waitcnt lgkmcnt(0)
	v_add_f32_e32 v81, v15, v23
	v_mul_f32_e32 v22, v22, v35
	s_waitcnt vmcnt(6)
	v_lshlrev_b32_e32 v23, 16, v89
	v_mul_f32_e32 v22, v22, v23
	v_bfe_u32 v23, v22, 16, 1
	v_add3_u32 v22, v22, v23, s61
	global_store_short_d16_hi v[28:29], v22, off offset:64
	v_mul_f32_e32 v22, v91, v20
	v_div_fixup_f32 v77, v21, v14, s59
	v_mul_f32_e32 v22, v22, v37
	s_waitcnt vmcnt(4)
	v_lshlrev_b32_e32 v23, 16, v32
	v_mul_f32_e32 v14, v88, v77
	v_mul_f32_e32 v22, v22, v23
	v_mul_f32_e32 v21, v14, v34
	v_lshl_add_u64 v[14:15], v[30:31], 0, s[20:21]
	v_bfe_u32 v23, v22, 16, 1
	global_load_ushort v30, v[14:15], off offset:64
	v_add3_u32 v22, v22, v23, s61
	v_mul_f32_e32 v20, v92, v20
	global_store_short_d16_hi v[28:29], v22, off offset:128
	v_mul_f32_e32 v20, v20, v38
	s_waitcnt vmcnt(5)
	v_lshlrev_b32_e32 v22, 16, v33
	v_mul_f32_e32 v20, v20, v22
	v_bfe_u32 v22, v20, 16, 1
	v_add3_u32 v20, v20, v22, s61
	global_store_short_d16_hi v[28:29], v20, off offset:192
	global_load_ushort v28, v[14:15], off offset:128
	s_nop 0
	global_load_ushort v29, v[14:15], off offset:192
	s_waitcnt vmcnt(6)
	v_lshlrev_b32_e32 v14, 16, v93
	v_mul_f32_e32 v14, v21, v14
	v_bfe_u32 v15, v14, 16, 1
	v_add3_u32 v20, v14, v15, s61
	v_mad_i64_i32 v[14:15], s[4:5], v39, s62, v[4:5]
	v_add_u32_e32 v31, 9, v36
	s_nop 1
	v_mov_b32_dpp v95, v81 row_mirror row_mask:0xf bank_mask:0xf
	global_store_short_d16_hi v[14:15], v20, off
	v_mad_i64_i32 v[20:21], s[4:5], v31, s57, v[6:7]
	v_lshl_add_u64 v[20:21], v[20:21], 0, s[0:1]
	v_lshl_add_u64 v[20:21], v[20:21], 0, v[2:3]
	v_add_co_u32_e32 v22, vcc, s60, v20
	v_sub_f32_e32 v88, v75, v8
	s_nop 0
	v_addc_co_u32_e32 v23, vcc, 0, v21, vcc
	global_load_ushort v22, v[22:23], off offset:2048
	s_waitcnt lgkmcnt(0)
	v_add_f32_e32 v23, v81, v95
	ds_bpermute_b32 v32, v209, v23
	v_sub_f32_e32 v39, v74, v11
	v_sub_f32_e32 v89, v76, v12
	v_fmac_f32_e32 v10, v88, v88
	v_fmac_f32_e32 v10, v89, v89
	s_waitcnt lgkmcnt(0)
	v_add_f32_e32 v8, v23, v32
	v_fmamk_f32 v8, v8, 0x3c000000, v211
	v_mul_f32_e32 v11, 0x4f800000, v8
	v_cmp_gt_f32_e32 vcc, s58, v8
	ds_read2st64_b32 v[74:75], v64 offset0:24 offset1:25
	v_mul_f32_e32 v33, v39, v39
	v_cndmask_b32_e32 v8, v8, v11, vcc
	v_sqrt_f32_e32 v11, v8
	v_fmac_f32_e32 v33, v82, v82
	s_waitcnt lgkmcnt(0)
	v_sub_f32_e32 v74, v72, v74
	v_add_u32_e32 v92, 11, v36
	v_add_u32_e32 v12, -1, v11
	v_fma_f32 v23, -v12, v11, v8
	v_cmp_ge_f32_e64 s[4:5], 0, v23
	v_add_u32_e32 v23, 1, v11
	v_sub_f32_e32 v71, v71, v75
	v_cndmask_b32_e64 v12, v11, v12, s[4:5]
	v_fma_f32 v11, -v23, v11, v8
	v_cmp_lt_f32_e64 s[4:5], 0, v11
	v_mul_f32_e32 v75, v71, v71
	v_fmac_f32_e32 v75, v70, v70
	v_cndmask_b32_e64 v11, v12, v23, s[4:5]
	v_mul_f32_e32 v12, 0x37800000, v11
	v_cndmask_b32_e32 v11, v11, v12, vcc
	s_nop 1
	v_mov_b32_dpp v12, v10 quad_perm:[1,0,3,2] row_mask:0xf bank_mask:0xf
	v_cmp_class_f32_e32 vcc, v8, v212
	v_sub_f32_e32 v17, v42, v17
	s_waitcnt lgkmcnt(0)
	v_add_f32_e32 v10, v10, v12
	s_nop 1
	v_mov_b32_dpp v12, v10 quad_perm:[2,3,0,1] row_mask:0xf bank_mask:0xf
	v_cndmask_b32_e32 v8, v11, v8, vcc
	v_div_scale_f32 v11, s[4:5], v8, v8, s59
	v_rcp_f32_e32 v23, v11
	s_waitcnt lgkmcnt(0)
	v_add_f32_e32 v10, v10, v12
	s_nop 1
	v_mov_b32_dpp v12, v10 row_half_mirror row_mask:0xf bank_mask:0xf
	v_fma_f32 v32, -v11, v23, 1.0
	v_fmac_f32_e32 v23, v32, v23
	v_div_scale_f32 v32, vcc, s59, v8, s59
	v_mul_f32_e32 v76, v32, v23
	s_waitcnt lgkmcnt(0)
	v_add_f32_e32 v10, v10, v12
	v_fma_f32 v81, -v11, v76, v32
	s_nop 1
	v_mov_b32_dpp v12, v10 row_mirror row_mask:0xf bank_mask:0xf
	v_fmac_f32_e32 v76, v81, v23
	v_fma_f32 v11, -v11, v76, v32
	v_div_fmas_f32 v11, v11, v23, v76
	v_div_fixup_f32 v32, v11, v8, s59
	s_waitcnt lgkmcnt(0)
	v_add_f32_e32 v8, v10, v12
	v_mul_f32_e32 v10, v83, v32
	v_mul_f32_e32 v23, v10, v34
	v_lshl_add_u64 v[10:11], v[20:21], 0, s[20:21]
	v_mul_f32_e32 v20, v85, v77
	v_mul_f32_e32 v20, v20, v35
	s_waitcnt vmcnt(6)
	v_lshlrev_b32_e32 v21, 16, v30
	v_mul_f32_e32 v20, v20, v21
	v_bfe_u32 v21, v20, 16, 1
	v_add3_u32 v20, v20, v21, s61
	global_store_short_d16_hi v[14:15], v20, off offset:64
	v_mul_f32_e32 v20, v86, v77
	v_mul_f32_e32 v20, v20, v37
	s_waitcnt vmcnt(4)
	v_lshlrev_b32_e32 v21, 16, v28
	v_mul_f32_e32 v20, v20, v21
	v_bfe_u32 v21, v20, 16, 1
	v_add3_u32 v20, v20, v21, s61
	global_load_ushort v30, v[10:11], off offset:64
	s_waitcnt vmcnt(4)
	v_lshlrev_b32_e32 v21, 16, v29
	global_store_short_d16_hi v[14:15], v20, off offset:128
	v_mul_f32_e32 v20, v87, v77
	v_mul_f32_e32 v20, v20, v38
	v_mul_f32_e32 v20, v20, v21
	v_bfe_u32 v21, v20, 16, 1
	v_add3_u32 v20, v20, v21, s61
	global_store_short_d16_hi v[14:15], v20, off offset:192
	global_load_ushort v76, v[10:11], off offset:128
	global_load_ushort v77, v[10:11], off offset:192
	s_waitcnt vmcnt(6)
; DI float bf2f(unsigned short u) { return __uint_as_float((unsigned)u << 16); }
; DI unsigned f2bf(float f) { unsigned u = __float_as_uint(f); return (u + 0x7fffu + ((u >> 16) & 1u)) >> 16; }
; DI int crow(int i, int hh) { return (i & 3) + 8 * (i >> 2) + 4 * hh; }
; DI void attn_unit(Ctx A_, LAS unsigned char* lds, int b, int h, int qb, float lam, int wave, int lane) {
;     ...
;     if (mp == 0) {
;         float ssq[16];
; #pragma unroll
;         for (int i = 0; i < 16; ++i) ssq[i] = 0.f;
; #pragma unroll
;         for (int nb = 0; nb < 4; ++nb)
; #pragma unroll
;             for (int i = 0; i < 16; ++i) { const float d = o[nb][i] - X2[(nb * 16 + i) * 64]; o[nb][i] = d; ssq[i] += d * d; }
; #pragma unroll
;         for (int i = 0; i < 16; ++i) {
;             float v = ssq[i];
; #pragma unroll
;             for (int x = 1; x < 32; x <<= 1) v += __shfl_xor(v, x);
;             ssq[i] = ONE_M_LAMINIT / sqrtf(v * (1.0f / 128.0f) + NORM_EPS);
;         }
; #pragma unroll
;         for (int nb = 0; nb < 4; ++nb) {
;             const float sn = SUB_NORM[nb * 32 + r_e];
; #pragma unroll
;             for (int i = 0; i < 16; ++i) {
;                 const size_t rw = (size_t)(rowq_e + crow(i, hh_e));
;                 Y_[rw * YLD + C_YA + h_e * 128 + nb * 32 + r_e] = (bf16)f2bf(o[nb][i] * ssq[i] * sn * bf2f(P[rw * PLD + C_ZA + h_e * 128 + nb * 32 + r_e]));
;             }
	v_lshlrev_b32_e32 v10, 16, v22
	v_mul_f32_e32 v10, v23, v10
	v_bfe_u32 v11, v10, 16, 1
	v_add3_u32 v10, v10, v11, s61
	v_mad_i64_i32 v[20:21], s[4:5], v31, s62, v[4:5]
	v_add_u32_e32 v31, 10, v36
	ds_bpermute_b32 v12, v209, v8
	global_store_short_d16_hi v[20:21], v10, off
	v_mad_i64_i32 v[10:11], s[4:5], v31, s57, v[6:7]
	v_lshl_add_u64 v[10:11], v[10:11], 0, s[0:1]
	v_lshl_add_u64 v[22:23], v[10:11], 0, v[2:3]
	v_add_co_u32_e32 v10, vcc, s60, v22
	s_waitcnt lgkmcnt(0)
	v_add_f32_e32 v8, v8, v12
	v_addc_co_u32_e32 v11, vcc, 0, v23, vcc
	global_load_ushort v81, v[10:11], off offset:2048
	v_fmamk_f32 v8, v8, 0x3c000000, v211
	v_sub_f32_e32 v85, v65, v9
	v_mul_f32_e32 v9, 0x4f800000, v8
	v_cmp_gt_f32_e32 vcc, s58, v8
	v_sub_f32_e32 v86, v73, v13
	v_fmac_f32_e32 v33, v85, v85
	v_cndmask_b32_e32 v8, v8, v9, vcc
	v_sqrt_f32_e32 v9, v8
	v_fmac_f32_e32 v33, v86, v86
	ds_read2st64_b32 v[28:29], v64 offset0:26 offset1:27
	ds_read2st64_b32 v[14:15], v64 offset0:28 offset1:29
	ds_read2st64_b32 v[10:11], v64 offset0:30 offset1:31
	ds_read2st64_b32 v[72:73], v64 offset0:40 offset1:41
	v_add_u32_e32 v12, -1, v9
	v_fma_f32 v13, -v12, v9, v8
	v_cmp_ge_f32_e64 s[4:5], 0, v13
	v_add_u32_e32 v13, 1, v9
	s_waitcnt lgkmcnt(0)
	v_sub_f32_e32 v72, v62, v72
	v_cndmask_b32_e64 v12, v9, v12, s[4:5]
	v_fma_f32 v9, -v13, v9, v8
	v_cmp_lt_f32_e64 s[4:5], 0, v9
	v_mul_f32_e32 v83, v74, v74
	v_fmac_f32_e32 v83, v26, v26
	v_cndmask_b32_e64 v9, v12, v13, s[4:5]
	v_mul_f32_e32 v12, 0x37800000, v9
	v_cndmask_b32_e32 v9, v9, v12, vcc
	s_nop 1
	v_mov_b32_dpp v12, v33 quad_perm:[1,0,3,2] row_mask:0xf bank_mask:0xf
	v_cmp_class_f32_e32 vcc, v8, v212
	v_fmac_f32_e32 v83, v72, v72
	v_sub_f32_e32 v73, v60, v73
	v_cndmask_b32_e32 v8, v9, v8, vcc
	s_waitcnt lgkmcnt(0)
	v_add_f32_e32 v12, v33, v12
	s_nop 1
	v_mov_b32_dpp v33, v12 quad_perm:[2,3,0,1] row_mask:0xf bank_mask:0xf
	v_div_scale_f32 v9, s[4:5], v8, v8, s59
	v_rcp_f32_e32 v13, v9
	v_fmac_f32_e32 v75, v73, v73
	s_waitcnt lgkmcnt(0)
	v_add_f32_e32 v12, v12, v33
	s_nop 1
	v_mov_b32_dpp v33, v12 row_half_mirror row_mask:0xf bank_mask:0xf
	v_fma_f32 v65, -v9, v13, 1.0
	v_fmac_f32_e32 v13, v65, v13
	v_div_scale_f32 v65, vcc, s59, v8, s59
	v_mul_f32_e32 v87, v65, v13
	v_fma_f32 v90, -v9, v87, v65
	s_waitcnt lgkmcnt(0)
	v_add_f32_e32 v12, v12, v33
	v_fmac_f32_e32 v87, v90, v13
	s_nop 1
	v_mov_b32_dpp v33, v12 row_mirror row_mask:0xf bank_mask:0xf
	v_fma_f32 v9, -v9, v87, v65
	v_div_fmas_f32 v9, v9, v13, v87
	v_div_fixup_f32 v65, v9, v8, s59
	v_mul_f32_e32 v8, v84, v65
	v_mul_f32_e32 v13, v78, v32
	s_waitcnt lgkmcnt(0)
	v_add_f32_e32 v33, v12, v33
	v_mul_f32_e32 v12, v8, v34
	v_lshl_add_u64 v[8:9], v[22:23], 0, s[20:21]
	v_mul_f32_e32 v13, v13, v35
	s_waitcnt vmcnt(6)
	v_lshlrev_b32_e32 v22, 16, v30
	v_mul_f32_e32 v13, v13, v22
	v_bfe_u32 v22, v13, 16, 1
	v_add3_u32 v13, v13, v22, s61
	global_store_short_d16_hi v[20:21], v13, off offset:64
	v_mul_f32_e32 v13, v79, v32
	v_mul_f32_e32 v13, v13, v37
	s_waitcnt vmcnt(4)
	v_lshlrev_b32_e32 v22, 16, v76
	v_mul_f32_e32 v13, v13, v22
	v_bfe_u32 v22, v13, 16, 1
	v_add3_u32 v13, v13, v22, s61
	global_store_short_d16_hi v[20:21], v13, off offset:128
	v_mul_f32_e32 v13, v80, v32
	global_load_ushort v84, v[8:9], off offset:64
	v_mul_f32_e32 v13, v13, v38
	s_waitcnt vmcnt(5)
	v_lshlrev_b32_e32 v22, 16, v77
	v_mul_f32_e32 v13, v13, v22
	v_bfe_u32 v22, v13, 16, 1
	v_add3_u32 v13, v13, v22, s61
	global_store_short_d16_hi v[20:21], v13, off offset:192
	global_load_ushort v90, v[8:9], off offset:128
	global_load_ushort v91, v[8:9], off offset:192
	v_mad_i64_i32 v[76:77], s[4:5], v31, s62, v[4:5]
	ds_bpermute_b32 v87, v209, v33
	s_waitcnt vmcnt(6)
	v_lshlrev_b32_e32 v8, 16, v81
	v_mul_f32_e32 v8, v12, v8
	v_bfe_u32 v9, v8, 16, 1
	v_add3_u32 v8, v8, v9, s61
	global_store_short_d16_hi v[76:77], v8, off
	v_mad_i64_i32 v[8:9], s[4:5], v92, s57, v[6:7]
	v_lshl_add_u64 v[8:9], v[8:9], 0, s[0:1]
	v_lshl_add_u64 v[78:79], v[8:9], 0, v[2:3]
	v_add_co_u32_e32 v8, vcc, s60, v78
	v_sub_f32_e32 v57, v57, v28
	s_nop 0
	v_addc_co_u32_e32 v9, vcc, 0, v79, vcc
	global_load_ushort v93, v[8:9], off offset:2048
	s_waitcnt lgkmcnt(0)
	v_add_f32_e32 v8, v33, v87
	v_fmamk_f32 v8, v8, 0x3c000000, v211
	v_mul_f32_e32 v9, 0x4f800000, v8
	v_cmp_gt_f32_e32 vcc, s58, v8
	ds_read2st64_b32 v[30:31], v64 offset0:42 offset1:43
	ds_read2st64_b32 v[20:21], v64 offset0:44 offset1:45
	ds_read2st64_b32 v[12:13], v64 offset0:46 offset1:47
	ds_read2st64_b32 v[80:81], v64 offset0:56 offset1:57
	v_cndmask_b32_e32 v62, v8, v9, vcc
	v_sqrt_f32_e32 v87, v62
	ds_read2st64_b32 v[32:33], v64 offset0:58 offset1:59
	ds_read2st64_b32 v[22:23], v64 offset0:60 offset1:61
	ds_read2st64_b32 v[8:9], v64 offset0:62 offset1:63
	s_waitcnt lgkmcnt(6)
	v_sub_f32_e32 v30, v58, v30
	s_waitcnt lgkmcnt(3)
	v_sub_f32_e32 v80, v63, v80
	v_add_u32_e32 v63, -1, v87
	v_fma_f32 v64, -v63, v87, v62
	v_cmp_ge_f32_e64 s[4:5], 0, v64
	v_add_u32_e32 v64, 1, v87
	v_fmac_f32_e32 v83, v80, v80
	v_cndmask_b32_e64 v63, v87, v63, s[4:5]
	v_fma_f32 v87, -v64, v87, v62
	v_cmp_lt_f32_e64 s[4:5], 0, v87
	s_nop 1
	v_mov_b32_dpp v87, v83 quad_perm:[1,0,3,2] row_mask:0xf bank_mask:0xf
	s_waitcnt lgkmcnt(3)
	v_sub_f32_e32 v32, v59, v32
	v_cndmask_b32_e64 v63, v63, v64, s[4:5]
	v_mul_f32_e32 v64, 0x37800000, v63
	v_cndmask_b32_e32 v63, v63, v64, vcc
	v_cmp_class_f32_e32 vcc, v62, v212
	s_waitcnt lgkmcnt(0)
	v_add_f32_e32 v83, v83, v87
	s_nop 1
	v_mov_b32_dpp v87, v83 quad_perm:[2,3,0,1] row_mask:0xf bank_mask:0xf
	v_cndmask_b32_e32 v62, v63, v62, vcc
	v_div_scale_f32 v63, s[4:5], v62, v62, s59
	v_rcp_f32_e32 v64, v63
	s_waitcnt lgkmcnt(0)
; DI float bf2f(unsigned short u) { return __uint_as_float((unsigned)u << 16); }
; DI unsigned f2bf(float f) { unsigned u = __float_as_uint(f); return (u + 0x7fffu + ((u >> 16) & 1u)) >> 16; }
; DI int crow(int i, int hh) { return (i & 3) + 8 * (i >> 2) + 4 * hh; }
; DI void attn_unit(Ctx A_, LAS unsigned char* lds, int b, int h, int qb, float lam, int wave, int lane) {
;     ...
;     if (mp == 0) {
;         float ssq[16];
; #pragma unroll
;         for (int i = 0; i < 16; ++i) ssq[i] = 0.f;
; #pragma unroll
;         for (int nb = 0; nb < 4; ++nb)
; #pragma unroll
;             for (int i = 0; i < 16; ++i) { const float d = o[nb][i] - X2[(nb * 16 + i) * 64]; o[nb][i] = d; ssq[i] += d * d; }
; #pragma unroll
;         for (int i = 0; i < 16; ++i) {
;             float v = ssq[i];
; #pragma unroll
;             for (int x = 1; x < 32; x <<= 1) v += __shfl_xor(v, x);
;             ssq[i] = ONE_M_LAMINIT / sqrtf(v * (1.0f / 128.0f) + NORM_EPS);
;         }
; #pragma unroll
;         for (int nb = 0; nb < 4; ++nb) {
;             const float sn = SUB_NORM[nb * 32 + r_e];
; #pragma unroll
;             for (int i = 0; i < 16; ++i) {
;                 const size_t rw = (size_t)(rowq_e + crow(i, hh_e));
;                 Y_[rw * YLD + C_YA + h_e * 128 + nb * 32 + r_e] = (bf16)f2bf(o[nb][i] * ssq[i] * sn * bf2f(P[rw * PLD + C_ZA + h_e * 128 + nb * 32 + r_e]));
;             }
	v_add_f32_e32 v83, v83, v87
	s_nop 1
	v_mov_b32_dpp v87, v83 row_half_mirror row_mask:0xf bank_mask:0xf
	v_mul_f32_e32 v28, v57, v57
	v_fma_f32 v95, -v63, v64, 1.0
	v_fmac_f32_e32 v64, v95, v64
	v_div_scale_f32 v95, vcc, s59, v62, s59
	v_mul_f32_e32 v96, v95, v64
	v_fma_f32 v97, -v63, v96, v95
	v_fmac_f32_e32 v96, v97, v64
	v_fma_f32 v63, -v63, v96, v95
	v_div_fmas_f32 v63, v63, v64, v96
	v_div_fixup_f32 v95, v63, v62, s59
	v_mul_f32_e32 v62, v82, v95
	v_mul_f32_e32 v64, v62, v34
	v_lshl_add_u64 v[62:63], v[78:79], 0, s[20:21]
	v_mul_f32_e32 v78, v94, v65
	v_mul_f32_e32 v78, v78, v35
	s_waitcnt lgkmcnt(0)
	v_add_f32_e32 v83, v83, v87
	s_nop 1
	v_mov_b32_dpp v87, v83 row_mirror row_mask:0xf bank_mask:0xf
	v_mul_f32_e32 v39, v39, v95
	v_mul_f32_e32 v39, v39, v35
	v_fmac_f32_e32 v28, v24, v24
	s_waitcnt vmcnt(5)
	v_lshlrev_b32_e32 v79, 16, v84
	v_mul_f32_e32 v78, v78, v79
	v_bfe_u32 v79, v78, 16, 1
	v_add3_u32 v78, v78, v79, s61
	v_mul_f32_e32 v79, v88, v65
	v_mul_f32_e32 v79, v79, v37
	s_waitcnt vmcnt(3)
	v_lshlrev_b32_e32 v82, 16, v90
	v_mul_f32_e32 v79, v79, v82
	v_bfe_u32 v82, v79, 16, 1
	global_store_short_d16_hi v[76:77], v78, off offset:64
	v_add3_u32 v79, v79, v82, s61
	v_mul_f32_e32 v65, v89, v65
	global_load_ushort v78, v[62:63], off offset:64
	v_mul_f32_e32 v65, v65, v38
	global_store_short_d16_hi v[76:77], v79, off offset:128
	s_waitcnt vmcnt(5)
	v_lshlrev_b32_e32 v79, 16, v91
	v_mul_f32_e32 v65, v65, v79
	v_bfe_u32 v79, v65, 16, 1
	v_add3_u32 v65, v65, v79, s61
	global_store_short_d16_hi v[76:77], v65, off offset:192
	global_load_ushort v79, v[62:63], off offset:128
	global_load_ushort v82, v[62:63], off offset:192
	v_add_u32_e32 v84, 16, v36
	s_waitcnt lgkmcnt(0)
	v_add_f32_e32 v27, v83, v87
	v_fmac_f32_e32 v28, v30, v30
	v_fmac_f32_e32 v28, v32, v32
	s_waitcnt vmcnt(6)
	v_lshlrev_b32_e32 v62, 16, v93
	v_mul_f32_e32 v62, v64, v62
	v_bfe_u32 v63, v62, 16, 1
	v_add3_u32 v64, v62, v63, s61
	v_mad_i64_i32 v[62:63], s[4:5], v92, s62, v[4:5]
	global_store_short_d16_hi v[62:63], v64, off
	v_mad_i64_i32 v[64:65], s[4:5], v84, s57, v[6:7]
	v_lshl_add_u64 v[64:65], v[64:65], 0, s[0:1]
	v_lshl_add_u64 v[64:65], v[64:65], 0, v[2:3]
	v_add_co_u32_e32 v76, vcc, s60, v64
	v_sub_f32_e32 v54, v54, v29
	s_nop 0
	v_addc_co_u32_e32 v77, vcc, 0, v65, vcc
	global_load_ushort v76, v[76:77], off offset:2048
	ds_bpermute_b32 v77, v209, v27
	v_sub_f32_e32 v31, v55, v31
	v_mul_f32_e32 v29, v54, v54
	v_sub_f32_e32 v33, v56, v33
	v_sub_f32_e32 v51, v51, v14
	s_waitcnt lgkmcnt(0)
	v_add_f32_e32 v27, v27, v77
	v_fmamk_f32 v27, v27, 0x3c000000, v211
	v_mul_f32_e32 v60, 0x4f800000, v27
	v_cmp_gt_f32_e32 vcc, s58, v27
	v_sub_f32_e32 v77, v61, v81
	v_fmac_f32_e32 v75, v77, v77
	v_cndmask_b32_e32 v27, v27, v60, vcc
	v_sqrt_f32_e32 v60, v27
	v_sub_f32_e32 v52, v52, v20
	v_sub_f32_e32 v22, v53, v22
	v_sub_f32_e32 v48, v48, v15
	v_add_u32_e32 v61, -1, v60
	v_fma_f32 v81, -v61, v60, v27
	v_cmp_ge_f32_e64 s[4:5], 0, v81
	v_add_u32_e32 v81, 1, v60
	v_sub_f32_e32 v49, v49, v21
	v_cndmask_b32_e64 v61, v60, v61, s[4:5]
	v_fma_f32 v60, -v81, v60, v27
	v_cmp_lt_f32_e64 s[4:5], 0, v60
	v_sub_f32_e32 v23, v50, v23
	v_sub_f32_e32 v12, v46, v12
	v_cndmask_b32_e64 v60, v61, v81, s[4:5]
	v_mul_f32_e32 v61, 0x37800000, v60
	v_cndmask_b32_e32 v60, v60, v61, vcc
	v_cmp_class_f32_e32 vcc, v27, v212
	s_nop 1
	v_mov_b32_dpp v81, v75 quad_perm:[1,0,3,2] row_mask:0xf bank_mask:0xf
	v_sub_f32_e32 v13, v40, v13
	v_cndmask_b32_e32 v27, v60, v27, vcc
	v_div_scale_f32 v60, s[4:5], v27, v27, s59
	v_rcp_f32_e32 v61, v60
	s_waitcnt lgkmcnt(0)
	v_add_f32_e32 v75, v75, v81
	s_nop 1
	v_mov_b32_dpp v81, v75 quad_perm:[2,3,0,1] row_mask:0xf bank_mask:0xf
	v_fma_f32 v83, -v60, v61, 1.0
	v_fmac_f32_e32 v61, v83, v61
	v_div_scale_f32 v83, vcc, s59, v27, s59
	v_mul_f32_e32 v87, v83, v61
	v_fma_f32 v88, -v60, v87, v83
	v_fmac_f32_e32 v87, v88, v61
	v_fma_f32 v60, -v60, v87, v83
	v_div_fmas_f32 v60, v60, v61, v87
	v_div_fixup_f32 v83, v60, v27, s59
	v_mul_f32_e32 v26, v26, v83
	s_waitcnt vmcnt(6)
	v_lshlrev_b32_e32 v61, 16, v78
	v_mul_f32_e32 v39, v39, v61
	v_bfe_u32 v61, v39, 16, 1
	v_add3_u32 v39, v39, v61, s61
	v_mul_f32_e32 v61, v85, v95
	v_mul_f32_e32 v60, v26, v34
	v_lshl_add_u64 v[26:27], v[64:65], 0, s[20:21]
	v_mul_f32_e32 v61, v61, v37
	s_waitcnt vmcnt(3)
	v_lshlrev_b32_e32 v64, 16, v79
	v_mul_f32_e32 v61, v61, v64
	v_bfe_u32 v64, v61, 16, 1
	v_add3_u32 v61, v61, v64, s61
	global_store_short_d16_hi v[62:63], v39, off offset:64
	global_store_short_d16_hi v[62:63], v61, off offset:128
	v_mul_f32_e32 v61, v86, v95
	global_load_ushort v39, v[26:27], off offset:64
	v_mul_f32_e32 v61, v61, v38
	s_waitcnt vmcnt(5)
	v_lshlrev_b32_e32 v64, 16, v82
	v_mul_f32_e32 v61, v61, v64
	v_bfe_u32 v64, v61, 16, 1
	v_add3_u32 v61, v61, v64, s61
	global_store_short_d16_hi v[62:63], v61, off offset:192
	global_load_ushort v64, v[26:27], off offset:128
	global_load_ushort v65, v[26:27], off offset:192
	s_waitcnt lgkmcnt(0)
	v_add_f32_e32 v75, v75, v81
	s_nop 1
	v_mov_b32_dpp v81, v75 row_half_mirror row_mask:0xf bank_mask:0xf
	s_waitcnt vmcnt(6)
	v_lshlrev_b32_e32 v26, 16, v76
	v_mul_f32_e32 v26, v60, v26
	v_bfe_u32 v27, v26, 16, 1
	s_waitcnt lgkmcnt(0)
	v_add_f32_e32 v75, v75, v81
	v_add3_u32 v60, v26, v27, s61
	v_mad_i64_i32 v[26:27], s[4:5], v84, s62, v[4:5]
	v_add_u32_e32 v76, 17, v36
	s_nop 1
	v_mov_b32_dpp v81, v75 row_mirror row_mask:0xf bank_mask:0xf
	global_store_short_d16_hi v[26:27], v60, off
	v_mad_i64_i32 v[60:61], s[4:5], v76, s57, v[6:7]
	v_lshl_add_u64 v[60:61], v[60:61], 0, s[0:1]
	v_lshl_add_u64 v[60:61], v[60:61], 0, v[2:3]
	v_add_co_u32_e32 v62, vcc, s60, v60
	s_waitcnt vmcnt(4)
; DI float bf2f(unsigned short u) { return __uint_as_float((unsigned)u << 16); }
; DI unsigned f2bf(float f) { unsigned u = __float_as_uint(f); return (u + 0x7fffu + ((u >> 16) & 1u)) >> 16; }
; DI int crow(int i, int hh) { return (i & 3) + 8 * (i >> 2) + 4 * hh; }
; DI void attn_unit(Ctx A_, LAS unsigned char* lds, int b, int h, int qb, float lam, int wave, int lane) {
;     ...
;     if (mp == 0) {
;         float ssq[16];
; #pragma unroll
;         for (int i = 0; i < 16; ++i) ssq[i] = 0.f;
; #pragma unroll
;         for (int nb = 0; nb < 4; ++nb)
; #pragma unroll
;             for (int i = 0; i < 16; ++i) { const float d = o[nb][i] - X2[(nb * 16 + i) * 64]; o[nb][i] = d; ssq[i] += d * d; }
; #pragma unroll
;         for (int i = 0; i < 16; ++i) {
;             float v = ssq[i];
; #pragma unroll
;             for (int x = 1; x < 32; x <<= 1) v += __shfl_xor(v, x);
;             ssq[i] = ONE_M_LAMINIT / sqrtf(v * (1.0f / 128.0f) + NORM_EPS);
;         }
; #pragma unroll
;         for (int nb = 0; nb < 4; ++nb) {
;             const float sn = SUB_NORM[nb * 32 + r_e];
; #pragma unroll
;             for (int i = 0; i < 16; ++i) {
;                 const size_t rw = (size_t)(rowq_e + crow(i, hh_e));
;                 Y_[rw * YLD + C_YA + h_e * 128 + nb * 32 + r_e] = (bf16)f2bf(o[nb][i] * ssq[i] * sn * bf2f(P[rw * PLD + C_ZA + h_e * 128 + nb * 32 + r_e]));
;             }
	v_lshlrev_b32_e32 v39, 16, v39
	v_addc_co_u32_e32 v63, vcc, 0, v61, vcc
	global_load_ushort v62, v[62:63], off offset:2048
	s_waitcnt lgkmcnt(0)
	v_add_f32_e32 v63, v75, v81
	ds_bpermute_b32 v69, v209, v63
	s_waitcnt lgkmcnt(0)
	v_add_f32_e32 v58, v63, v69
	v_fmamk_f32 v58, v58, 0x3c000000, v211
	v_mul_f32_e32 v63, 0x4f800000, v58
	v_cmp_gt_f32_e32 vcc, s58, v58
	s_nop 1
	v_cndmask_b32_e32 v58, v58, v63, vcc
	v_sqrt_f32_e32 v63, v58
	s_nop 0
	v_add_u32_e32 v59, -1, v63
	v_fma_f32 v69, -v59, v63, v58
	v_cmp_ge_f32_e64 s[4:5], 0, v69
	v_add_u32_e32 v69, 1, v63
	s_nop 0
	v_cndmask_b32_e64 v59, v63, v59, s[4:5]
	v_fma_f32 v63, -v69, v63, v58
	v_cmp_lt_f32_e64 s[4:5], 0, v63
	s_nop 1
	v_cndmask_b32_e64 v59, v59, v69, s[4:5]
	v_mul_f32_e32 v63, 0x37800000, v59
	v_cndmask_b32_e32 v59, v59, v63, vcc
	v_cmp_class_f32_e32 vcc, v58, v212
	s_nop 1
	v_mov_b32_dpp v69, v28 quad_perm:[1,0,3,2] row_mask:0xf bank_mask:0xf
	s_waitcnt lgkmcnt(0)
	v_add_f32_e32 v28, v28, v69
	v_cndmask_b32_e32 v58, v59, v58, vcc
	v_div_scale_f32 v59, s[4:5], v58, v58, s59
	v_rcp_f32_e32 v63, v59
	s_nop 1
	v_mov_b32_dpp v69, v28 quad_perm:[2,3,0,1] row_mask:0xf bank_mask:0xf
	v_fma_f32 v75, -v59, v63, 1.0
	v_fmac_f32_e32 v63, v75, v63
	v_div_scale_f32 v75, vcc, s59, v58, s59
	v_mul_f32_e32 v78, v75, v63
	v_fma_f32 v79, -v59, v78, v75
	v_fmac_f32_e32 v78, v79, v63
	v_fma_f32 v59, -v59, v78, v75
	v_div_fmas_f32 v59, v59, v63, v78
	v_div_fixup_f32 v63, v59, v58, s59
	v_mul_f32_e32 v58, v70, v63
	v_mul_f32_e32 v70, v58, v34
	v_lshl_add_u64 v[58:59], v[60:61], 0, s[20:21]
	v_mul_f32_e32 v60, v74, v83
	v_mul_f32_e32 v60, v60, v35
	v_mul_f32_e32 v39, v60, v39
	v_bfe_u32 v60, v39, 16, 1
	v_add3_u32 v39, v39, v60, s61
	v_mul_f32_e32 v60, v72, v83
	v_mul_f32_e32 v60, v60, v37
	s_waitcnt vmcnt(3)
	v_lshlrev_b32_e32 v61, 16, v64
	v_mul_f32_e32 v60, v60, v61
	v_bfe_u32 v61, v60, 16, 1
	global_store_short_d16_hi v[26:27], v39, off offset:64
	v_add3_u32 v60, v60, v61, s61
	global_load_ushort v39, v[58:59], off offset:64
	s_waitcnt vmcnt(4)
	v_lshlrev_b32_e32 v61, 16, v65
	global_store_short_d16_hi v[26:27], v60, off offset:128
	v_mul_f32_e32 v60, v80, v83
	v_mul_f32_e32 v60, v60, v38
	v_mul_f32_e32 v60, v60, v61
	v_bfe_u32 v61, v60, 16, 1
	v_add3_u32 v60, v60, v61, s61
	global_store_short_d16_hi v[26:27], v60, off offset:192
	global_load_ushort v64, v[58:59], off offset:128
	global_load_ushort v65, v[58:59], off offset:192
	s_waitcnt lgkmcnt(0)
	v_add_f32_e32 v28, v28, v69
	s_nop 1
	v_mov_b32_dpp v69, v28 row_half_mirror row_mask:0xf bank_mask:0xf
	s_waitcnt vmcnt(6)
	v_lshlrev_b32_e32 v26, 16, v62
	v_mul_f32_e32 v26, v70, v26
	v_bfe_u32 v27, v26, 16, 1
	v_add3_u32 v58, v26, v27, s61
	s_waitcnt lgkmcnt(0)
	v_add_f32_e32 v28, v28, v69
	v_mad_i64_i32 v[26:27], s[4:5], v76, s62, v[4:5]
	v_add_u32_e32 v62, 18, v36
	s_nop 1
	v_mov_b32_dpp v69, v28 row_mirror row_mask:0xf bank_mask:0xf
	global_store_short_d16_hi v[26:27], v58, off
	v_mad_i64_i32 v[58:59], s[4:5], v62, s57, v[6:7]
	v_lshl_add_u64 v[58:59], v[58:59], 0, s[0:1]
	v_lshl_add_u64 v[58:59], v[58:59], 0, v[2:3]
	v_add_co_u32_e32 v60, vcc, s60, v58
	s_waitcnt vmcnt(5)
	v_lshlrev_b32_e32 v39, 16, v39
	v_addc_co_u32_e32 v61, vcc, 0, v59, vcc
	global_load_ushort v60, v[60:61], off offset:2048
	v_sub_f32_e32 v61, v68, v25
	s_waitcnt lgkmcnt(0)
	v_add_f32_e32 v25, v28, v69
	ds_bpermute_b32 v28, v209, v25
	v_fmac_f32_e32 v29, v61, v61
	v_fmac_f32_e32 v29, v31, v31
	v_fmac_f32_e32 v29, v33, v33
	s_waitcnt lgkmcnt(0)
	v_add_f32_e32 v25, v25, v28
	v_fmamk_f32 v25, v25, 0x3c000000, v211
	v_mul_f32_e32 v28, 0x4f800000, v25
	v_cmp_gt_f32_e32 vcc, s58, v25
	s_nop 1
	v_cndmask_b32_e32 v25, v25, v28, vcc
	v_sqrt_f32_e32 v28, v25
	s_nop 0
	v_add_u32_e32 v55, -1, v28
	v_fma_f32 v56, -v55, v28, v25
	v_cmp_ge_f32_e64 s[4:5], 0, v56
	v_add_u32_e32 v56, 1, v28
	s_nop 0
	v_cndmask_b32_e64 v55, v28, v55, s[4:5]
	v_fma_f32 v28, -v56, v28, v25
	v_cmp_lt_f32_e64 s[4:5], 0, v28
	s_nop 1
	v_cndmask_b32_e64 v28, v55, v56, s[4:5]
	s_nop 1
	v_mov_b32_dpp v56, v29 quad_perm:[1,0,3,2] row_mask:0xf bank_mask:0xf
	v_mul_f32_e32 v55, 0x37800000, v28
	v_cndmask_b32_e32 v28, v28, v55, vcc
	v_cmp_class_f32_e32 vcc, v25, v212
	s_waitcnt lgkmcnt(0)
	v_add_f32_e32 v29, v29, v56
	s_nop 1
	v_mov_b32_dpp v56, v29 quad_perm:[2,3,0,1] row_mask:0xf bank_mask:0xf
	v_cndmask_b32_e32 v25, v28, v25, vcc
	v_div_scale_f32 v28, s[4:5], v25, v25, s59
	v_rcp_f32_e32 v55, v28
	s_waitcnt lgkmcnt(0)
	v_add_f32_e32 v29, v29, v56
	s_nop 1
	v_mov_b32_dpp v56, v29 row_half_mirror row_mask:0xf bank_mask:0xf
	v_fma_f32 v68, -v28, v55, 1.0
	v_fmac_f32_e32 v55, v68, v55
	v_div_scale_f32 v68, vcc, s59, v25, s59
	v_mul_f32_e32 v69, v68, v55
	v_fma_f32 v70, -v28, v69, v68
	s_waitcnt lgkmcnt(0)
	v_add_f32_e32 v56, v29, v56
	v_mul_f32_e32 v29, v71, v63
	v_fmac_f32_e32 v69, v70, v55
	v_mul_f32_e32 v29, v29, v35
	v_fma_f32 v28, -v28, v69, v68
	v_mul_f32_e32 v29, v29, v39
	v_div_fmas_f32 v28, v28, v55, v69
	v_bfe_u32 v39, v29, 16, 1
	v_div_fixup_f32 v55, v28, v25, s59
	v_add3_u32 v29, v29, v39, s61
	v_mul_f32_e32 v24, v24, v55
	global_store_short_d16_hi v[26:27], v29, off offset:64
	v_mul_f32_e32 v29, v73, v63
	v_mul_f32_e32 v28, v24, v34
	v_lshl_add_u64 v[24:25], v[58:59], 0, s[20:21]
	v_mul_f32_e32 v29, v29, v37
	s_waitcnt vmcnt(4)
	v_lshlrev_b32_e32 v58, 16, v64
	v_mul_f32_e32 v29, v29, v58
	v_bfe_u32 v58, v29, 16, 1
	v_add3_u32 v29, v29, v58, s61
	global_store_short_d16_hi v[26:27], v29, off offset:128
	v_mul_f32_e32 v29, v77, v63
	v_mul_f32_e32 v29, v29, v38
	s_waitcnt vmcnt(4)
; DI float bf2f(unsigned short u) { return __uint_as_float((unsigned)u << 16); }
; DI unsigned f2bf(float f) { unsigned u = __float_as_uint(f); return (u + 0x7fffu + ((u >> 16) & 1u)) >> 16; }
; DI int crow(int i, int hh) { return (i & 3) + 8 * (i >> 2) + 4 * hh; }
; DI void attn_unit(Ctx A_, LAS unsigned char* lds, int b, int h, int qb, float lam, int wave, int lane) {
;     ...
;     if (mp == 0) {
;         float ssq[16];
; #pragma unroll
;         for (int i = 0; i < 16; ++i) ssq[i] = 0.f;
; #pragma unroll
;         for (int nb = 0; nb < 4; ++nb)
; #pragma unroll
;             for (int i = 0; i < 16; ++i) { const float d = o[nb][i] - X2[(nb * 16 + i) * 64]; o[nb][i] = d; ssq[i] += d * d; }
; #pragma unroll
;         for (int i = 0; i < 16; ++i) {
;             float v = ssq[i];
; #pragma unroll
;             for (int x = 1; x < 32; x <<= 1) v += __shfl_xor(v, x);
;             ssq[i] = ONE_M_LAMINIT / sqrtf(v * (1.0f / 128.0f) + NORM_EPS);
;         }
; #pragma unroll
;         for (int nb = 0; nb < 4; ++nb) {
;             const float sn = SUB_NORM[nb * 32 + r_e];
; #pragma unroll
;             for (int i = 0; i < 16; ++i) {
;                 const size_t rw = (size_t)(rowq_e + crow(i, hh_e));
;                 Y_[rw * YLD + C_YA + h_e * 128 + nb * 32 + r_e] = (bf16)f2bf(o[nb][i] * ssq[i] * sn * bf2f(P[rw * PLD + C_ZA + h_e * 128 + nb * 32 + r_e]));
;             }
	v_lshlrev_b32_e32 v59, 16, v65
	v_mul_f32_e32 v29, v29, v59
	global_load_ushort v39, v[24:25], off offset:64
	global_load_ushort v58, v[24:25], off offset:128
	v_bfe_u32 v59, v29, 16, 1
	v_add3_u32 v29, v29, v59, s61
	global_store_short_d16_hi v[26:27], v29, off offset:192
	global_load_ushort v59, v[24:25], off offset:192
	s_waitcnt vmcnt(6)
	v_lshlrev_b32_e32 v24, 16, v60
	v_mul_f32_e32 v24, v28, v24
	v_bfe_u32 v25, v24, 16, 1
	v_add3_u32 v26, v24, v25, s61
	v_mad_i64_i32 v[24:25], s[4:5], v62, s62, v[4:5]
	v_add_u32_e32 v60, 19, v36
	global_store_short_d16_hi v[24:25], v26, off
	v_mad_i64_i32 v[26:27], s[4:5], v60, s57, v[6:7]
	v_lshl_add_u64 v[26:27], v[26:27], 0, s[0:1]
	v_lshl_add_u64 v[26:27], v[26:27], 0, v[2:3]
	v_add_co_u32_e32 v28, vcc, s60, v26
	v_mul_f32_e32 v57, v57, v55
	s_nop 0
	v_addc_co_u32_e32 v29, vcc, 0, v27, vcc
	global_load_ushort v28, v[28:29], off offset:2048
	v_mul_f32_e32 v57, v57, v35
	v_mul_f32_e32 v30, v30, v55
	v_mul_f32_e32 v32, v32, v55
	s_nop 1
	v_mov_b32_dpp v68, v56 row_mirror row_mask:0xf bank_mask:0xf
	v_mul_f32_e32 v30, v30, v37
	v_mul_f32_e32 v32, v32, v38
	v_lshl_add_u64 v[26:27], v[26:27], 0, s[20:21]
	s_waitcnt vmcnt(5)
	v_lshlrev_b32_e32 v39, 16, v39
	v_mul_f32_e32 v39, v57, v39
	v_bfe_u32 v57, v39, 16, 1
	v_add3_u32 v39, v39, v57, s61
	s_waitcnt vmcnt(4)
	v_lshlrev_b32_e32 v57, 16, v58
	s_waitcnt vmcnt(2)
	v_lshlrev_b32_e32 v55, 16, v59
	v_mul_f32_e32 v30, v30, v57
	v_mul_f32_e32 v32, v32, v55
	global_store_short_d16_hi v[24:25], v39, off offset:64
	v_bfe_u32 v57, v30, 16, 1
	v_bfe_u32 v55, v32, 16, 1
	global_load_ushort v39, v[26:27], off offset:64
	v_add3_u32 v30, v30, v57, s61
	v_add3_u32 v32, v32, v55, s61
	global_store_short_d16_hi v[24:25], v30, off offset:128
	global_store_short_d16_hi v[24:25], v32, off offset:192
	global_load_ushort v30, v[26:27], off offset:128
	v_add_u32_e32 v55, 24, v36
	global_load_ushort v32, v[26:27], off offset:192
	s_waitcnt lgkmcnt(0)
	v_add_f32_e32 v29, v56, v68
	ds_bpermute_b32 v56, v209, v29
	s_waitcnt lgkmcnt(0)
	v_add_f32_e32 v14, v29, v56
	v_fmamk_f32 v14, v14, 0x3c000000, v211
	v_mul_f32_e32 v29, 0x4f800000, v14
	v_cmp_gt_f32_e32 vcc, s58, v14
	v_mul_f32_e32 v56, v51, v51
	v_fmac_f32_e32 v56, v18, v18
	v_cndmask_b32_e32 v14, v14, v29, vcc
	v_sqrt_f32_e32 v29, v14
	v_fmac_f32_e32 v56, v52, v52
	v_fmac_f32_e32 v56, v22, v22
	v_add_u32_e32 v20, -1, v29
	v_fma_f32 v62, -v20, v29, v14
	v_cmp_ge_f32_e64 s[4:5], 0, v62
	v_add_u32_e32 v62, 1, v29
	s_waitcnt vmcnt(1)
	v_lshlrev_b32_e32 v30, 16, v30
	v_cndmask_b32_e64 v20, v29, v20, s[4:5]
	v_fma_f32 v29, -v62, v29, v14
	v_cmp_lt_f32_e64 s[4:5], 0, v29
	s_nop 1
	v_cndmask_b32_e64 v20, v20, v62, s[4:5]
	v_mul_f32_e32 v29, 0x37800000, v20
	v_cndmask_b32_e32 v20, v20, v29, vcc
	v_cmp_class_f32_e32 vcc, v14, v212
	s_nop 1
	v_cndmask_b32_e32 v14, v20, v14, vcc
	v_div_scale_f32 v20, s[4:5], v14, v14, s59
	v_rcp_f32_e32 v29, v20
	v_div_scale_f32 v62, vcc, s59, v14, s59
	v_fma_f32 v53, -v20, v29, 1.0
	v_fmac_f32_e32 v29, v53, v29
	s_nop 1
	v_mov_b32_dpp v53, v56 quad_perm:[1,0,3,2] row_mask:0xf bank_mask:0xf
	v_mul_f32_e32 v63, v62, v29
	v_fma_f32 v64, -v20, v63, v62
	v_fmac_f32_e32 v63, v64, v29
	v_fma_f32 v20, -v20, v63, v62
	s_waitcnt lgkmcnt(0)
	v_add_f32_e32 v53, v56, v53
	s_nop 1
	v_mov_b32_dpp v56, v53 quad_perm:[2,3,0,1] row_mask:0xf bank_mask:0xf
	v_div_fmas_f32 v20, v20, v29, v63
	v_div_fixup_f32 v20, v20, v14, s59
	s_waitcnt lgkmcnt(0)
	v_add_f32_e32 v24, v53, v56
	s_nop 1
	v_mov_b32_dpp v25, v24 row_half_mirror row_mask:0xf bank_mask:0xf
	s_waitcnt lgkmcnt(0)
	v_add_f32_e32 v14, v24, v25
	v_mul_f32_e32 v24, v61, v20
	v_mul_f32_e32 v24, v24, v34
	v_lshlrev_b32_e32 v25, 16, v28
	v_mul_f32_e32 v24, v24, v25
	v_bfe_u32 v25, v24, 16, 1
	s_nop 1
	v_mov_b32_dpp v53, v14 row_mirror row_mask:0xf bank_mask:0xf
	v_add3_u32 v26, v24, v25, s61
	v_mad_i64_i32 v[24:25], s[4:5], v60, s62, v[4:5]
	global_store_short_d16_hi v[24:25], v26, off
	v_mad_i64_i32 v[26:27], s[4:5], v55, s57, v[6:7]
	v_lshl_add_u64 v[26:27], v[26:27], 0, s[0:1]
	v_lshl_add_u64 v[26:27], v[26:27], 0, v[2:3]
	v_add_co_u32_e32 v28, vcc, s60, v26
	s_waitcnt lgkmcnt(0)
	v_add_f32_e32 v14, v14, v53
	v_addc_co_u32_e32 v29, vcc, 0, v27, vcc
	global_load_ushort v28, v[28:29], off offset:2048
	v_sub_f32_e32 v29, v66, v19
	ds_bpermute_b32 v19, v209, v14
	v_mul_f32_e32 v53, v48, v48
	v_fmac_f32_e32 v53, v29, v29
	v_fmac_f32_e32 v53, v49, v49
	v_fmac_f32_e32 v53, v23, v23
	s_waitcnt lgkmcnt(0)
	v_add_f32_e32 v14, v14, v19
	v_fmamk_f32 v14, v14, 0x3c000000, v211
	v_mul_f32_e32 v15, 0x4f800000, v14
	v_cmp_gt_f32_e32 vcc, s58, v14
	s_nop 1
	v_mov_b32_dpp v56, v53 quad_perm:[1,0,3,2] row_mask:0xf bank_mask:0xf
	s_nop 0
	v_cndmask_b32_e32 v14, v14, v15, vcc
	v_sqrt_f32_e32 v15, v14
	s_nop 0
	v_add_u32_e32 v19, -1, v15
	v_fma_f32 v21, -v19, v15, v14
	v_cmp_ge_f32_e64 s[4:5], 0, v21
	v_add_u32_e32 v21, 1, v15
	s_nop 0
	v_cndmask_b32_e64 v19, v15, v19, s[4:5]
	v_fma_f32 v15, -v21, v15, v14
	v_cmp_lt_f32_e64 s[4:5], 0, v15
	s_nop 1
	v_cndmask_b32_e64 v15, v19, v21, s[4:5]
	v_mul_f32_e32 v19, 0x37800000, v15
	v_cndmask_b32_e32 v15, v15, v19, vcc
	v_cmp_class_f32_e32 vcc, v14, v212
	s_nop 1
	v_cndmask_b32_e32 v19, v15, v14, vcc
	v_lshl_add_u64 v[14:15], v[26:27], 0, s[20:21]
	v_mul_f32_e32 v26, v54, v20
	v_mul_f32_e32 v26, v26, v35
	v_lshlrev_b32_e32 v27, 16, v39
	v_mul_f32_e32 v26, v26, v27
	v_bfe_u32 v27, v26, 16, 1
	v_add3_u32 v26, v26, v27, s61
	global_store_short_d16_hi v[24:25], v26, off offset:64
	v_mul_f32_e32 v27, v31, v20
	global_load_ushort v26, v[14:15], off offset:64
	v_mul_f32_e32 v27, v27, v37
	v_mul_f32_e32 v27, v27, v30
	v_bfe_u32 v30, v27, 16, 1
	v_add3_u32 v27, v27, v30, s61
	global_store_short_d16_hi v[24:25], v27, off offset:128
	v_mul_f32_e32 v20, v33, v20
	global_load_ushort v27, v[14:15], off offset:128
	v_mul_f32_e32 v20, v20, v38
	s_waitcnt vmcnt(6)
; DI float bf2f(unsigned short u) { return __uint_as_float((unsigned)u << 16); }
; DI unsigned f2bf(float f) { unsigned u = __float_as_uint(f); return (u + 0x7fffu + ((u >> 16) & 1u)) >> 16; }
; DI int crow(int i, int hh) { return (i & 3) + 8 * (i >> 2) + 4 * hh; }
; DI void attn_unit(Ctx A_, LAS unsigned char* lds, int b, int h, int qb, float lam, int wave, int lane) {
;     ...
;     if (mp == 0) {
;         float ssq[16];
; #pragma unroll
;         for (int i = 0; i < 16; ++i) ssq[i] = 0.f;
; #pragma unroll
;         for (int nb = 0; nb < 4; ++nb)
; #pragma unroll
;             for (int i = 0; i < 16; ++i) { const float d = o[nb][i] - X2[(nb * 16 + i) * 64]; o[nb][i] = d; ssq[i] += d * d; }
; #pragma unroll
;         for (int i = 0; i < 16; ++i) {
;             float v = ssq[i];
; #pragma unroll
;             for (int x = 1; x < 32; x <<= 1) v += __shfl_xor(v, x);
;             ssq[i] = ONE_M_LAMINIT / sqrtf(v * (1.0f / 128.0f) + NORM_EPS);
;         }
; #pragma unroll
;         for (int nb = 0; nb < 4; ++nb) {
;             const float sn = SUB_NORM[nb * 32 + r_e];
; #pragma unroll
;             for (int i = 0; i < 16; ++i) {
;                 const size_t rw = (size_t)(rowq_e + crow(i, hh_e));
;                 Y_[rw * YLD + C_YA + h_e * 128 + nb * 32 + r_e] = (bf16)f2bf(o[nb][i] * ssq[i] * sn * bf2f(P[rw * PLD + C_ZA + h_e * 128 + nb * 32 + r_e]));
;             }
	v_lshlrev_b32_e32 v30, 16, v32
	v_mul_f32_e32 v20, v20, v30
	v_bfe_u32 v30, v20, 16, 1
	v_add3_u32 v20, v20, v30, s61
	global_store_short_d16_hi v[24:25], v20, off offset:192
	global_load_ushort v24, v[14:15], off offset:192
	v_div_scale_f32 v21, s[4:5], v19, v19, s59
	v_rcp_f32_e32 v50, v21
	v_div_scale_f32 v20, vcc, s59, v19, s59
	v_sub_f32_e32 v32, v47, v8
	v_fma_f32 v14, -v21, v50, 1.0
	v_fmac_f32_e32 v50, v14, v50
	s_waitcnt lgkmcnt(0)
	v_add_f32_e32 v14, v53, v56
	s_nop 1
	v_mov_b32_dpp v15, v14 quad_perm:[2,3,0,1] row_mask:0xf bank_mask:0xf
	v_mul_f32_e32 v25, v20, v50
	v_fma_f32 v30, -v21, v25, v20
	v_fmac_f32_e32 v25, v30, v50
	v_fma_f32 v20, -v21, v25, v20
	s_waitcnt lgkmcnt(0)
	v_add_f32_e32 v14, v14, v15
	s_nop 1
	v_mov_b32_dpp v15, v14 row_half_mirror row_mask:0xf bank_mask:0xf
	v_div_fmas_f32 v20, v20, v50, v25
	v_div_fixup_f32 v25, v20, v19, s59
	v_mul_f32_e32 v39, v51, v25
	v_mul_f32_e32 v39, v39, v35
	s_waitcnt lgkmcnt(0)
	v_add_f32_e32 v30, v14, v15
	v_mul_f32_e32 v14, v18, v25
	v_mul_f32_e32 v14, v14, v34
	s_waitcnt vmcnt(6)
	v_lshlrev_b32_e32 v15, 16, v28
	v_mul_f32_e32 v14, v14, v15
	v_bfe_u32 v15, v14, 16, 1
	v_add3_u32 v18, v14, v15, s61
	v_mad_i64_i32 v[14:15], s[4:5], v55, s62, v[4:5]
	v_add_u32_e32 v28, 25, v36
	global_store_short_d16_hi v[14:15], v18, off
	v_mad_i64_i32 v[18:19], s[4:5], v28, s57, v[6:7]
	v_lshl_add_u64 v[18:19], v[18:19], 0, s[0:1]
	v_lshl_add_u64 v[18:19], v[18:19], 0, v[2:3]
	v_add_co_u32_e32 v20, vcc, s60, v18
	v_mul_f32_e32 v22, v22, v25
	s_nop 0
	v_addc_co_u32_e32 v21, vcc, 0, v19, vcc
	global_load_ushort v20, v[20:21], off offset:2048
	v_lshl_add_u64 v[18:19], v[18:19], 0, s[20:21]
	v_mul_f32_e32 v22, v22, v38
	s_nop 1
	v_mov_b32_dpp v31, v30 row_mirror row_mask:0xf bank_mask:0xf
	s_waitcnt vmcnt(6)
	v_lshlrev_b32_e32 v26, 16, v26
	v_mul_f32_e32 v26, v39, v26
	v_bfe_u32 v39, v26, 16, 1
	v_add3_u32 v26, v26, v39, s61
	global_store_short_d16_hi v[14:15], v26, off offset:64
	v_mul_f32_e32 v39, v52, v25
	global_load_ushort v26, v[18:19], off offset:64
	v_mul_f32_e32 v39, v39, v37
	s_waitcnt vmcnt(6)
	v_lshlrev_b32_e32 v27, 16, v27
	v_mul_f32_e32 v27, v39, v27
	v_bfe_u32 v39, v27, 16, 1
	v_add3_u32 v27, v27, v39, s61
	global_store_short_d16_hi v[14:15], v27, off offset:128
	global_load_ushort v27, v[18:19], off offset:128
	s_waitcnt vmcnt(6)
	v_lshlrev_b32_e32 v24, 16, v24
	v_mul_f32_e32 v22, v22, v24
	v_bfe_u32 v24, v22, 16, 1
	v_add3_u32 v22, v22, v24, s61
	global_store_short_d16_hi v[14:15], v22, off offset:192
	global_load_ushort v22, v[18:19], off offset:192
	s_waitcnt lgkmcnt(0)
	v_add_f32_e32 v21, v30, v31
	ds_bpermute_b32 v30, v209, v21
	v_sub_f32_e32 v31, v45, v10
	v_mul_f32_e32 v10, v31, v31
	v_fmac_f32_e32 v10, v16, v16
	v_fmac_f32_e32 v10, v12, v12
	s_waitcnt lgkmcnt(0)
	v_add_f32_e32 v21, v21, v30
	v_fmamk_f32 v21, v21, 0x3c000000, v211
	v_mul_f32_e32 v30, 0x4f800000, v21
	v_cmp_gt_f32_e32 vcc, s58, v21
	v_fmac_f32_e32 v10, v32, v32
	s_nop 1
	v_mov_b32_dpp v18, v10 quad_perm:[1,0,3,2] row_mask:0xf bank_mask:0xf
	v_cndmask_b32_e32 v21, v21, v30, vcc
	v_sqrt_f32_e32 v30, v21
	v_add_u32_e32 v25, 26, v36
	s_waitcnt lgkmcnt(0)
	v_add_f32_e32 v10, v10, v18
	v_add_u32_e32 v8, -1, v30
	v_fma_f32 v33, -v8, v30, v21
	v_cmp_ge_f32_e64 s[4:5], 0, v33
	v_add_u32_e32 v33, 1, v30
	v_fma_f32 v14, -v33, v30, v21
	v_cndmask_b32_e64 v8, v30, v8, s[4:5]
	v_cmp_lt_f32_e64 s[4:5], 0, v14
	s_nop 1
	v_mov_b32_dpp v18, v10 quad_perm:[2,3,0,1] row_mask:0xf bank_mask:0xf
	s_waitcnt lgkmcnt(0)
	v_add_f32_e32 v10, v10, v18
	v_cndmask_b32_e64 v8, v8, v33, s[4:5]
	v_mul_f32_e32 v14, 0x37800000, v8
	v_cndmask_b32_e32 v8, v8, v14, vcc
	v_cmp_class_f32_e32 vcc, v21, v212
	s_nop 1
	v_mov_b32_dpp v18, v10 row_half_mirror row_mask:0xf bank_mask:0xf
	s_waitcnt lgkmcnt(0)
	v_add_f32_e32 v10, v10, v18
	v_cndmask_b32_e32 v8, v8, v21, vcc
	v_div_scale_f32 v14, s[4:5], v8, v8, s59
	v_rcp_f32_e32 v15, v14
	s_waitcnt vmcnt(0)
	v_lshlrev_b32_e32 v22, 16, v22
	v_fma_f32 v19, -v14, v15, 1.0
	v_fmac_f32_e32 v15, v19, v15
	v_div_scale_f32 v19, vcc, s59, v8, s59
	v_mul_f32_e32 v21, v19, v15
	v_fma_f32 v24, -v14, v21, v19
	v_fmac_f32_e32 v21, v24, v15
	v_fma_f32 v14, -v14, v21, v19
	v_div_fmas_f32 v14, v14, v15, v21
	v_div_fixup_f32 v8, v14, v8, s59
	v_mul_f32_e32 v14, v29, v8
	v_mul_f32_e32 v14, v14, v34
	v_lshlrev_b32_e32 v15, 16, v20
	v_mul_f32_e32 v14, v14, v15
	v_bfe_u32 v15, v14, 16, 1
	s_nop 1
	v_mov_b32_dpp v24, v10 row_mirror row_mask:0xf bank_mask:0xf
	v_add3_u32 v18, v14, v15, s61
	v_mad_i64_i32 v[14:15], s[4:5], v28, s62, v[4:5]
	global_store_short_d16_hi v[14:15], v18, off
	v_mad_i64_i32 v[18:19], s[4:5], v25, s57, v[6:7]
	v_lshl_add_u64 v[18:19], v[18:19], 0, s[0:1]
	v_lshl_add_u64 v[18:19], v[18:19], 0, v[2:3]
	v_add_co_u32_e32 v20, vcc, s60, v18
	s_waitcnt lgkmcnt(0)
	v_add_f32_e32 v10, v10, v24
	v_addc_co_u32_e32 v21, vcc, 0, v19, vcc
	global_load_ushort v20, v[20:21], off offset:2048
	ds_bpermute_b32 v21, v209, v10
	v_sub_f32_e32 v24, v43, v11
	s_waitcnt lgkmcnt(0)
; DI float bf2f(unsigned short u) { return __uint_as_float((unsigned)u << 16); }
; DI unsigned f2bf(float f) { unsigned u = __float_as_uint(f); return (u + 0x7fffu + ((u >> 16) & 1u)) >> 16; }
; DI int crow(int i, int hh) { return (i & 3) + 8 * (i >> 2) + 4 * hh; }
; DI void attn_unit(Ctx A_, LAS unsigned char* lds, int b, int h, int qb, float lam, int wave, int lane) {
;     ...
;     if (mp == 0) {
;         float ssq[16];
; #pragma unroll
;         for (int i = 0; i < 16; ++i) ssq[i] = 0.f;
; #pragma unroll
;         for (int nb = 0; nb < 4; ++nb)
; #pragma unroll
;             for (int i = 0; i < 16; ++i) { const float d = o[nb][i] - X2[(nb * 16 + i) * 64]; o[nb][i] = d; ssq[i] += d * d; }
; #pragma unroll
;         for (int i = 0; i < 16; ++i) {
;             float v = ssq[i];
; #pragma unroll
;             for (int x = 1; x < 32; x <<= 1) v += __shfl_xor(v, x);
;             ssq[i] = ONE_M_LAMINIT / sqrtf(v * (1.0f / 128.0f) + NORM_EPS);
;         }
; #pragma unroll
;         for (int nb = 0; nb < 4; ++nb) {
;             const float sn = SUB_NORM[nb * 32 + r_e];
; #pragma unroll
;             for (int i = 0; i < 16; ++i) {
;                 const size_t rw = (size_t)(rowq_e + crow(i, hh_e));
;                 Y_[rw * YLD + C_YA + h_e * 128 + nb * 32 + r_e] = (bf16)f2bf(o[nb][i] * ssq[i] * sn * bf2f(P[rw * PLD + C_ZA + h_e * 128 + nb * 32 + r_e]));
;             }
	v_add_f32_e32 v10, v10, v21
	v_fmamk_f32 v21, v10, 0x3c000000, v211
	v_lshl_add_u64 v[10:11], v[18:19], 0, s[20:21]
	v_mul_f32_e32 v18, v48, v8
	v_mul_f32_e32 v18, v18, v35
	v_lshlrev_b32_e32 v19, 16, v26
	v_mul_f32_e32 v18, v18, v19
	v_bfe_u32 v19, v18, 16, 1
	v_add3_u32 v18, v18, v19, s61
	global_store_short_d16_hi v[14:15], v18, off offset:64
	v_mul_f32_e32 v19, v49, v8
	global_load_ushort v18, v[10:11], off offset:64
	v_mul_f32_e32 v19, v19, v37
	v_lshlrev_b32_e32 v26, 16, v27
	v_mul_f32_e32 v19, v19, v26
	v_bfe_u32 v26, v19, 16, 1
	v_add3_u32 v19, v19, v26, s61
	global_store_short_d16_hi v[14:15], v19, off offset:128
	v_mul_f32_e32 v8, v23, v8
	global_load_ushort v19, v[10:11], off offset:128
	v_mul_f32_e32 v8, v8, v38
	v_mul_f32_e32 v8, v8, v22
	v_bfe_u32 v22, v8, 16, 1
	v_add3_u32 v8, v8, v22, s61
	global_store_short_d16_hi v[14:15], v8, off offset:192
	global_load_ushort v10, v[10:11], off offset:192
	v_mul_f32_e32 v8, 0x4f800000, v21
	v_cmp_gt_f32_e32 vcc, s58, v21
	v_mul_f32_e32 v14, v24, v24
	v_fmac_f32_e32 v14, v17, v17
	v_cndmask_b32_e32 v8, v21, v8, vcc
	v_sqrt_f32_e32 v11, v8
	v_fmac_f32_e32 v14, v13, v13
	v_add_u32_e32 v15, -1, v11
	v_fma_f32 v21, -v15, v11, v8
	v_cmp_ge_f32_e64 s[4:5], 0, v21
	v_add_u32_e32 v21, 1, v11
	s_waitcnt vmcnt(4)
	v_lshlrev_b32_e32 v18, 16, v18
	v_cndmask_b32_e64 v15, v11, v15, s[4:5]
	v_fma_f32 v11, -v21, v11, v8
	v_cmp_lt_f32_e64 s[4:5], 0, v11
	s_waitcnt vmcnt(0)
	v_lshlrev_b32_e32 v10, 16, v10
	v_cndmask_b32_e64 v11, v15, v21, s[4:5]
	v_mul_f32_e32 v15, 0x37800000, v11
	v_cndmask_b32_e32 v11, v11, v15, vcc
	v_cmp_class_f32_e32 vcc, v8, v212
	v_sub_f32_e32 v21, v41, v9
	v_fmac_f32_e32 v14, v21, v21
	v_cndmask_b32_e32 v8, v11, v8, vcc
	v_div_scale_f32 v11, s[4:5], v8, v8, s59
	v_rcp_f32_e32 v15, v11
	v_div_scale_f32 v22, vcc, s59, v8, s59
	v_fma_f32 v9, -v11, v15, 1.0
	v_fmac_f32_e32 v15, v9, v15
	s_nop 1
	v_mov_b32_dpp v9, v14 quad_perm:[1,0,3,2] row_mask:0xf bank_mask:0xf
	v_mul_f32_e32 v23, v22, v15
	v_fma_f32 v26, -v11, v23, v22
	v_fmac_f32_e32 v23, v26, v15
	v_fma_f32 v11, -v11, v23, v22
	s_waitcnt lgkmcnt(0)
	v_add_f32_e32 v9, v14, v9
	s_nop 1
	v_mov_b32_dpp v14, v9 quad_perm:[2,3,0,1] row_mask:0xf bank_mask:0xf
	v_div_fmas_f32 v11, v11, v15, v23
	v_div_fixup_f32 v11, v11, v8, s59
	v_mul_f32_e32 v8, v16, v11
	v_mul_f32_e32 v8, v34, v8
	s_waitcnt lgkmcnt(0)
	v_add_f32_e32 v14, v9, v14
	v_lshlrev_b32_e32 v9, 16, v20
	v_mul_f32_e32 v8, v8, v9
	v_bfe_u32 v9, v8, 16, 1
	v_add3_u32 v16, v8, v9, s61
	v_mad_i64_i32 v[8:9], s[4:5], v25, s62, v[4:5]
	global_store_short_d16_hi v[8:9], v16, off
	v_add_u32_e32 v16, 27, v36
	v_mad_i64_i32 v[6:7], s[4:5], v16, s57, v[6:7]
	v_lshl_add_u64 v[6:7], v[6:7], 0, s[0:1]
	v_lshl_add_u64 v[2:3], v[6:7], 0, v[2:3]
	v_lshl_add_u64 v[6:7], v[2:3], 0, s[20:21]
	v_add_co_u32_e32 v2, vcc, s60, v2
	s_nop 1
	v_mov_b32_dpp v15, v14 row_half_mirror row_mask:0xf bank_mask:0xf
	s_nop 0
	v_addc_co_u32_e32 v3, vcc, 0, v3, vcc
	global_load_ushort v2, v[2:3], off offset:2048
	v_mul_f32_e32 v3, v31, v11
	v_mul_f32_e32 v3, v3, v35
	v_mul_f32_e32 v3, v3, v18
	v_bfe_u32 v18, v3, 16, 1
	v_add3_u32 v3, v3, v18, s61
	global_store_short_d16_hi v[8:9], v3, off offset:64
	v_mul_f32_e32 v3, v12, v11
	global_load_ushort v18, v[6:7], off offset:64
	v_mul_f32_e32 v3, v3, v37
	v_lshlrev_b32_e32 v12, 16, v19
	v_mul_f32_e32 v3, v3, v12
	v_bfe_u32 v12, v3, 16, 1
	v_add3_u32 v3, v3, v12, s61
	global_store_short_d16_hi v[8:9], v3, off offset:128
	v_mul_f32_e32 v3, v32, v11
	global_load_ushort v12, v[6:7], off offset:128
	v_mul_f32_e32 v3, v3, v38
	v_mul_f32_e32 v3, v3, v10
	v_bfe_u32 v10, v3, 16, 1
	v_add3_u32 v3, v3, v10, s61
	global_store_short_d16_hi v[8:9], v3, off offset:192
	global_load_ushort v6, v[6:7], off offset:192
	s_waitcnt lgkmcnt(0)
	v_add_f32_e32 v3, v14, v15
	s_nop 1
	v_mov_b32_dpp v7, v3 row_mirror row_mask:0xf bank_mask:0xf
	s_waitcnt lgkmcnt(0)
	v_add_f32_e32 v3, v3, v7
	ds_bpermute_b32 v7, v209, v3
	s_waitcnt lgkmcnt(0)
	v_add_f32_e32 v3, v3, v7
	v_fmamk_f32 v3, v3, 0x3c000000, v211
	v_mul_f32_e32 v7, 0x4f800000, v3
	v_cmp_gt_f32_e32 vcc, s58, v3
	s_waitcnt vmcnt(6)
	v_lshlrev_b32_e32 v2, 16, v2
	v_cndmask_b32_e32 v3, v3, v7, vcc
	v_sqrt_f32_e32 v7, v3
	s_nop 0
	v_add_u32_e32 v8, -1, v7
	v_fma_f32 v9, -v8, v7, v3
	v_cmp_ge_f32_e64 s[4:5], 0, v9
	v_add_u32_e32 v9, 1, v7
	s_nop 0
	v_cndmask_b32_e64 v8, v7, v8, s[4:5]
	v_fma_f32 v7, -v9, v7, v3
	v_cmp_lt_f32_e64 s[4:5], 0, v7
	s_nop 1
	v_cndmask_b32_e64 v7, v8, v9, s[4:5]
	v_mul_f32_e32 v8, 0x37800000, v7
	v_cndmask_b32_e32 v7, v7, v8, vcc
	v_cmp_class_f32_e32 vcc, v3, v212
	s_nop 1
	v_cndmask_b32_e32 v3, v7, v3, vcc
	v_div_scale_f32 v7, s[0:1], v3, v3, s59
	v_rcp_f32_e32 v8, v7
	s_nop 0
	v_fma_f32 v9, -v7, v8, 1.0
	v_fmac_f32_e32 v8, v9, v8
	v_div_scale_f32 v9, vcc, s59, v3, s59
	v_mul_f32_e32 v10, v9, v8
	v_fma_f32 v11, -v7, v10, v9
	v_fmac_f32_e32 v10, v11, v8
	v_fma_f32 v7, -v7, v10, v9
	v_div_fmas_f32 v7, v7, v8, v10
	v_div_fixup_f32 v7, v7, v3, s59
	v_mul_f32_e32 v3, v17, v7
	v_mul_f32_e32 v3, v34, v3
	v_mul_f32_e32 v2, v3, v2
	v_bfe_u32 v3, v2, 16, 1
	v_add3_u32 v8, v2, v3, s61
	v_mad_i64_i32 v[2:3], s[0:1], v16, s62, v[4:5]
	v_mul_f32_e32 v4, v24, v7
	v_mul_f32_e32 v4, v4, v35
	s_waitcnt vmcnt(4)
	v_lshlrev_b32_e32 v5, 16, v18
	v_mul_f32_e32 v4, v4, v5
	v_bfe_u32 v5, v4, 16, 1
	v_add3_u32 v4, v4, v5, s61
	global_store_short_d16_hi v[2:3], v4, off offset:64
	v_mul_f32_e32 v4, v13, v7
	v_mul_f32_e32 v4, v4, v37
	s_waitcnt vmcnt(3)
	v_lshlrev_b32_e32 v5, 16, v12
	v_mul_f32_e32 v4, v4, v5
	v_bfe_u32 v5, v4, 16, 1
	v_add3_u32 v4, v4, v5, s61
	global_store_short_d16_hi v[2:3], v4, off offset:128
	v_mul_f32_e32 v4, v21, v7
	v_mul_f32_e32 v4, v4, v38
	s_waitcnt vmcnt(2)
	v_lshlrev_b32_e32 v5, 16, v6
	v_mul_f32_e32 v4, v4, v5
	v_bfe_u32 v5, v4, 16, 1
	v_add3_u32 v4, v4, v5, s61
	global_store_short_d16_hi v[2:3], v8, off
	global_store_short_d16_hi v[2:3], v4, off offset:192
	s_branch .LBB0_862
